# GEMM K-loops: four counted vmcnt waits per iteration (10/8/10/8) instead of two vmcnt(6)
# baseline (speedup 1.0000x reference)
; #define PG8_STAGE(bufoff, gbase, voff) do { _Pragma("unroll") for (int _i = 0; _i < 2; ++_i) \
;         __builtin_amdgcn_global_load_lds((const unsigned*)((const char*)(gbase) + (voff)[_i]), (LAS unsigned*)(lds + (bufoff) + ldsw + _i * 8192), 16, 0, 0); } while (0)
; #define PG8_LDA(dst, b, h) do { _Pragma("unroll") for (int m = 0; m < 4; ++m) _Pragma("unroll") for (int k = 0; k < 2; ++k) dst[m][k] = *(const LAS bf16x8*)(lds + PG8_SA(b, h) + aoff + m * 2048 + k * 1024); } while (0)
; #define PG8_LDB(dst, b, h) do { _Pragma("unroll") for (int n = 0; n < 2; ++n) _Pragma("unroll") for (int k = 0; k < 2; ++k) dst[n][k] = *(const LAS bf16x8*)(lds + PG8_SB(b, h) + boff + n * 2048 + k * 1024); } while (0)
; #define PG8_MMA(ai, bj, At, Bt) do { __builtin_amdgcn_s_setprio(1); _Pragma("unroll") for (int m = 0; m < 4; ++m) _Pragma("unroll") for (int n = 0; n < 2; ++n) _Pragma("unroll") for (int k = 0; k < 2; ++k) \
;         acc[ai][bj][m][n] = __builtin_amdgcn_mfma_f32_16x16x32_bf16(Bt[n][k], At[m][k], acc[ai][bj][m][n], 0, 0, 0); __builtin_amdgcn_s_setprio(0); } while (0)
; #define PG8_WAIT_V(n) asm volatile("s_waitcnt vmcnt(" #n ")" ::: "memory")
; #define PG8_WAIT_L(n) asm volatile("s_waitcnt lgkmcnt(" #n ")" ::: "memory")
; template <class Epi>
; __device__ __forceinline__ void gemm_phase(LAS unsigned char* lds, const Gemm g, const StaticOrder& S, const Epi& E) {
;     ...
;         for (int t = 0; t < nt; t += 2) {
;             const bool last = (t == nt - 2);
;             const char* a1 = cA + (size_t)(t + 1) * kstepA;
;             const char* a2 = last ? nA : cA + (size_t)(t + 2) * kstepA; const char* b2 = last ? nB : cB + (size_t)(t + 2) * kstep;
;             const char* a3 = a2 + kstepA; const char* b3 = b2 + kstep;
;             PG8_LDB(B0, 0, 0); PG8_SCHED; PG8_LDA(At, 0, 0); PG8_STAGE(PG8_SA(1, 1), a1 + hstepA, voffA);
;             PG8_WAIT_L(8); PG8_BAR; PG8_WAIT_L(0); PG8_MMA(0, 0, At, B0); PG8_BAR; PG8_SCHED;
;             PG8_LDB(B1, 0, 1); PG8_STAGE(PG8_SB(0, 0), b2, voffB);
;             PG8_BAR; PG8_WAIT_L(0); PG8_MMA(0, 1, At, B1); PG8_BAR;
;             PG8_LDA(At, 0, 1); PG8_STAGE(PG8_SA(0, 0), a2, voffA);
;             PG8_BAR; PG8_WAIT_L(0); PG8_MMA(1, 0, At, B0); PG8_BAR; PG8_SCHED;
;             PG8_STAGE(PG8_SB(0, 1), b2 + hstepB, voffB);
;             PG8_WAIT_V(6); PG8_BAR; PG8_MMA(1, 1, At, B1); PG8_BAR;
.LBB0_158:
	s_add_u32 s42, s38, 0x100
	s_addc_u32 s43, s39, 0
	s_add_i32 s60, 0, 0x10000
	v_add_u32_e32 v0, s60, v152
	ds_read_b128 v[146:149], v0
	ds_read_b128 v[162:165], v0 offset:1024
	ds_read_b128 v[166:169], v0 offset:2048
	ds_read_b128 v[170:173], v0 offset:3072
	s_cmp_eq_u32 s59, 28
	s_cselect_b32 s25, s23, s43
	s_cselect_b32 s24, s55, s42
	s_cselect_b32 s5, s21, s58
	s_cselect_b32 s4, s56, s57
	v_lshl_add_u64 v[150:151], s[38:39], 0, v[140:141]
	s_add_i32 m0, s46, 0xc000
	ds_read_b128 v[174:177], v154
	ds_read_b128 v[188:191], v154 offset:1024
	ds_read_b128 v[192:195], v154 offset:2048
	ds_read_b128 v[196:199], v154 offset:3072
	ds_read_b128 v[200:203], v154 offset:4096
	ds_read_b128 v[204:207], v154 offset:5120
	ds_read_b128 v[208:211], v154 offset:6144
	ds_read_b128 v[212:215], v154 offset:7168
	global_load_lds_dwordx4 v[150:151], off
	v_lshl_add_u64 v[150:151], s[38:39], 0, v[142:143]
	s_add_i32 m0, s46, 0xe000
	s_nop 0
	global_load_lds_dwordx4 v[150:151], off
	s_waitcnt lgkmcnt(8)
	s_barrier
	s_waitcnt lgkmcnt(0)
	s_setprio 1
	s_waitcnt lgkmcnt(0)
	v_mfma_f32_16x16x32_bf16 v[126:129], v[146:149], v[174:177], v[126:129]
	v_mfma_f32_16x16x32_bf16 v[122:125], v[166:169], v[174:177], v[122:125]
	v_mfma_f32_16x16x32_bf16 v[110:113], v[146:149], v[192:195], v[110:113]
	v_mfma_f32_16x16x32_bf16 v[106:109], v[166:169], v[192:195], v[106:109]
	v_mfma_f32_16x16x32_bf16 v[94:97], v[146:149], v[200:203], v[94:97]
	v_mfma_f32_16x16x32_bf16 v[90:93], v[166:169], v[200:203], v[90:93]
	v_mfma_f32_16x16x32_bf16 v[78:81], v[146:149], v[208:211], v[78:81]
	v_mfma_f32_16x16x32_bf16 v[74:77], v[166:169], v[208:211], v[74:77]
	v_mfma_f32_16x16x32_bf16 v[126:129], v[162:165], v[188:191], v[126:129]
	v_mfma_f32_16x16x32_bf16 v[122:125], v[170:173], v[188:191], v[122:125]
	v_mfma_f32_16x16x32_bf16 v[110:113], v[162:165], v[196:199], v[110:113]
	v_mfma_f32_16x16x32_bf16 v[106:109], v[170:173], v[196:199], v[106:109]
	v_mfma_f32_16x16x32_bf16 v[94:97], v[162:165], v[204:207], v[94:97]
	v_mfma_f32_16x16x32_bf16 v[90:93], v[170:173], v[204:207], v[90:93]
	v_mfma_f32_16x16x32_bf16 v[78:81], v[162:165], v[212:215], v[78:81]
	v_mfma_f32_16x16x32_bf16 v[74:77], v[170:173], v[212:215], v[74:77]
	s_setprio 0
	s_barrier
	s_add_i32 s61, 0, 0x14000
	s_add_i32 s38, s60, s45
	v_add_u32_e32 v0, s61, v152
	v_lshl_add_u64 v[150:151], s[4:5], 0, v[134:135]
	s_mov_b32 m0, s38
	ds_read_b128 v[216:219], v0
	ds_read_b128 v[220:223], v0 offset:1024
	ds_read_b128 v[224:227], v0 offset:2048
	ds_read_b128 v[228:231], v0 offset:3072
	global_load_lds_dwordx4 v[150:151], off
	v_lshl_add_u64 v[184:185], s[4:5], 0, v[130:131]
	s_add_i32 m0, s38, 0x2000
	s_nop 0
	global_load_lds_dwordx4 v[184:185], off
	s_waitcnt vmcnt(10)
	s_barrier
	s_waitcnt lgkmcnt(0)
	s_setprio 1
	s_waitcnt lgkmcnt(0)
	v_mfma_f32_16x16x32_bf16 v[118:121], v[216:219], v[174:177], v[118:121]
	v_mfma_f32_16x16x32_bf16 v[114:117], v[224:227], v[174:177], v[114:117]
	v_mfma_f32_16x16x32_bf16 v[102:105], v[216:219], v[192:195], v[102:105]
	v_mfma_f32_16x16x32_bf16 v[98:101], v[224:227], v[192:195], v[98:101]
	v_mfma_f32_16x16x32_bf16 v[86:89], v[216:219], v[200:203], v[86:89]
	v_mfma_f32_16x16x32_bf16 v[82:85], v[224:227], v[200:203], v[82:85]
	v_mfma_f32_16x16x32_bf16 v[70:73], v[216:219], v[208:211], v[70:73]
	v_mfma_f32_16x16x32_bf16 v[66:69], v[224:227], v[208:211], v[66:69]
	v_mfma_f32_16x16x32_bf16 v[118:121], v[220:223], v[188:191], v[118:121]
	v_mfma_f32_16x16x32_bf16 v[114:117], v[228:231], v[188:191], v[114:117]
	v_mfma_f32_16x16x32_bf16 v[102:105], v[220:223], v[196:199], v[102:105]
	v_mfma_f32_16x16x32_bf16 v[98:101], v[228:231], v[196:199], v[98:101]
	v_mfma_f32_16x16x32_bf16 v[86:89], v[220:223], v[204:207], v[86:89]
	v_mfma_f32_16x16x32_bf16 v[82:85], v[228:231], v[204:207], v[82:85]
	v_mfma_f32_16x16x32_bf16 v[70:73], v[220:223], v[212:215], v[70:73]
	v_mfma_f32_16x16x32_bf16 v[66:69], v[228:231], v[212:215], v[66:69]
	s_setprio 0
	s_mov_b32 m0, s46
	v_lshl_add_u64 v[186:187], s[24:25], 0, v[136:137]
	s_barrier
	ds_read_b128 v[174:177], v154 offset:16384
	ds_read_b128 v[188:191], v154 offset:17408
	ds_read_b128 v[192:195], v154 offset:18432
	ds_read_b128 v[196:199], v154 offset:19456
	ds_read_b128 v[200:203], v154 offset:20480
	ds_read_b128 v[204:207], v154 offset:21504
	ds_read_b128 v[208:211], v154 offset:22528
	ds_read_b128 v[212:215], v154 offset:23552
	global_load_lds_dwordx4 v[186:187], off
	v_lshl_add_u64 v[244:245], s[24:25], 0, v[132:133]
	s_mov_b32 m0, s47
	s_nop 0
	global_load_lds_dwordx4 v[244:245], off
	s_barrier
	s_waitcnt lgkmcnt(0)
	s_setprio 1
	s_waitcnt lgkmcnt(0)
	v_mfma_f32_16x16x32_bf16 v[62:65], v[146:149], v[174:177], v[62:65]
	v_mfma_f32_16x16x32_bf16 v[58:61], v[166:169], v[174:177], v[58:61]
	v_mfma_f32_16x16x32_bf16 v[46:49], v[146:149], v[192:195], v[46:49]
	v_mfma_f32_16x16x32_bf16 v[42:45], v[166:169], v[192:195], v[42:45]
	v_mfma_f32_16x16x32_bf16 v[30:33], v[146:149], v[200:203], v[30:33]
	v_mfma_f32_16x16x32_bf16 v[26:29], v[166:169], v[200:203], v[26:29]
	v_mfma_f32_16x16x32_bf16 v[14:17], v[146:149], v[208:211], v[14:17]
	v_mfma_f32_16x16x32_bf16 v[10:13], v[166:169], v[208:211], v[10:13]
	v_mfma_f32_16x16x32_bf16 v[62:65], v[162:165], v[188:191], v[62:65]
	v_mfma_f32_16x16x32_bf16 v[58:61], v[170:173], v[188:191], v[58:61]
	v_mfma_f32_16x16x32_bf16 v[46:49], v[162:165], v[196:199], v[46:49]
	v_mfma_f32_16x16x32_bf16 v[42:45], v[170:173], v[196:199], v[42:45]
	v_mfma_f32_16x16x32_bf16 v[30:33], v[162:165], v[204:207], v[30:33]
	v_mfma_f32_16x16x32_bf16 v[26:29], v[170:173], v[204:207], v[26:29]
	v_mfma_f32_16x16x32_bf16 v[14:17], v[162:165], v[212:215], v[14:17]
	v_mfma_f32_16x16x32_bf16 v[10:13], v[170:173], v[212:215], v[10:13]
	s_setprio 0
	s_barrier
; #define PG8_STAGE(bufoff, gbase, voff) do { _Pragma("unroll") for (int _i = 0; _i < 2; ++_i) \
;         __builtin_amdgcn_global_load_lds((const unsigned*)((const char*)(gbase) + (voff)[_i]), (LAS unsigned*)(lds + (bufoff) + ldsw + _i * 8192), 16, 0, 0); } while (0)
; #define PG8_LDA(dst, b, h) do { _Pragma("unroll") for (int m = 0; m < 4; ++m) _Pragma("unroll") for (int k = 0; k < 2; ++k) dst[m][k] = *(const LAS bf16x8*)(lds + PG8_SA(b, h) + aoff + m * 2048 + k * 1024); } while (0)
; #define PG8_LDB(dst, b, h) do { _Pragma("unroll") for (int n = 0; n < 2; ++n) _Pragma("unroll") for (int k = 0; k < 2; ++k) dst[n][k] = *(const LAS bf16x8*)(lds + PG8_SB(b, h) + boff + n * 2048 + k * 1024); } while (0)
; #define PG8_MMA(ai, bj, At, Bt) do { __builtin_amdgcn_s_setprio(1); _Pragma("unroll") for (int m = 0; m < 4; ++m) _Pragma("unroll") for (int n = 0; n < 2; ++n) _Pragma("unroll") for (int k = 0; k < 2; ++k) \
;         acc[ai][bj][m][n] = __builtin_amdgcn_mfma_f32_16x16x32_bf16(Bt[n][k], At[m][k], acc[ai][bj][m][n], 0, 0, 0); __builtin_amdgcn_s_setprio(0); } while (0)
; #define PG8_WAIT_V(n) asm volatile("s_waitcnt vmcnt(" #n ")" ::: "memory")
; #define PG8_WAIT_L(n) asm volatile("s_waitcnt lgkmcnt(" #n ")" ::: "memory")
; #define PG8_BAR __builtin_amdgcn_s_barrier()
; #define PG8_SCHED __builtin_amdgcn_sched_barrier(0)
; template <class Epi>
; __device__ __forceinline__ void gemm_phase(LAS unsigned char* lds, const Gemm g, const StaticOrder& S, const Epi& E) {
;     ...
;             PG8_WAIT_V(6); PG8_BAR; PG8_MMA(1, 1, At, B1); PG8_BAR;
;             PG8_LDB(B0, 1, 0); PG8_SCHED; PG8_LDA(At, 1, 0); PG8_STAGE(PG8_SA(0, 1), a2 + hstepA, voffA);
;             PG8_WAIT_L(8); PG8_BAR; PG8_WAIT_L(0); PG8_MMA(0, 0, At, B0); PG8_BAR; PG8_SCHED;
;             PG8_LDB(B1, 1, 1); PG8_STAGE(PG8_SB(1, 0), b3, voffB);
;             PG8_BAR; PG8_WAIT_L(0); PG8_MMA(0, 1, At, B1); PG8_BAR;
;             PG8_LDA(At, 1, 1); PG8_STAGE(PG8_SA(1, 0), a3, voffA);
;             PG8_BAR; PG8_WAIT_L(0); PG8_MMA(1, 0, At, B0); PG8_BAR; PG8_SCHED;
	s_add_u32 s38, s4, 0x80000
	s_addc_u32 s39, s5, 0
	s_add_i32 s60, s61, s45
	v_lshl_add_u64 v[146:147], s[38:39], 0, v[134:135]
	s_mov_b32 m0, s60
	s_nop 0
	global_load_lds_dwordx4 v[146:147], off
	v_lshl_add_u64 v[146:147], s[38:39], 0, v[130:131]
	s_add_i32 m0, s60, 0x2000
	s_nop 0
	global_load_lds_dwordx4 v[146:147], off
	s_waitcnt vmcnt(8)
	s_barrier
	s_setprio 1
	v_mfma_f32_16x16x32_bf16 v[54:57], v[216:219], v[174:177], v[54:57]
	v_mfma_f32_16x16x32_bf16 v[50:53], v[224:227], v[174:177], v[50:53]
	v_mfma_f32_16x16x32_bf16 v[38:41], v[216:219], v[192:195], v[38:41]
	v_mfma_f32_16x16x32_bf16 v[34:37], v[224:227], v[192:195], v[34:37]
	v_mfma_f32_16x16x32_bf16 v[22:25], v[216:219], v[200:203], v[22:25]
	v_mfma_f32_16x16x32_bf16 v[18:21], v[224:227], v[200:203], v[18:21]
	v_mfma_f32_16x16x32_bf16 v[6:9], v[216:219], v[208:211], v[6:9]
	v_mfma_f32_16x16x32_bf16 v[2:5], v[224:227], v[208:211], v[2:5]
	v_mfma_f32_16x16x32_bf16 v[54:57], v[220:223], v[188:191], v[54:57]
	v_mfma_f32_16x16x32_bf16 v[50:53], v[228:231], v[188:191], v[50:53]
	v_mfma_f32_16x16x32_bf16 v[38:41], v[220:223], v[196:199], v[38:41]
	v_mfma_f32_16x16x32_bf16 v[34:37], v[228:231], v[196:199], v[34:37]
	v_mfma_f32_16x16x32_bf16 v[22:25], v[220:223], v[204:207], v[22:25]
	v_mfma_f32_16x16x32_bf16 v[18:21], v[228:231], v[204:207], v[18:21]
	v_mfma_f32_16x16x32_bf16 v[6:9], v[220:223], v[212:215], v[6:9]
	v_mfma_f32_16x16x32_bf16 v[2:5], v[228:231], v[212:215], v[2:5]
	s_setprio 0
	s_add_i32 s38, 0, 0x18000
	v_add_u32_e32 v0, s38, v152
	s_barrier
	ds_read_b128 v[146:149], v0
	ds_read_b128 v[162:165], v0 offset:1024
	ds_read_b128 v[166:169], v0 offset:2048
	ds_read_b128 v[170:173], v0 offset:3072
	s_add_u32 s24, s24, 0x80000
	s_addc_u32 s25, s25, 0
	s_mov_b32 m0, s48
	v_lshl_add_u64 v[216:217], s[24:25], 0, v[136:137]
	ds_read_b128 v[174:177], v154 offset:32768
	ds_read_b128 v[188:191], v154 offset:33792
	ds_read_b128 v[192:195], v154 offset:34816
	ds_read_b128 v[196:199], v154 offset:35840
	ds_read_b128 v[200:203], v154 offset:36864
	ds_read_b128 v[204:207], v154 offset:37888
	ds_read_b128 v[208:211], v154 offset:38912
	ds_read_b128 v[212:215], v154 offset:39936
	global_load_lds_dwordx4 v[216:217], off
	v_lshl_add_u64 v[216:217], s[24:25], 0, v[132:133]
	s_mov_b32 m0, s49
	s_nop 0
	global_load_lds_dwordx4 v[216:217], off
	s_waitcnt lgkmcnt(8)
	s_barrier
	s_waitcnt lgkmcnt(0)
	s_setprio 1
	s_waitcnt lgkmcnt(0)
	v_mfma_f32_16x16x32_bf16 v[126:129], v[146:149], v[174:177], v[126:129]
	v_mfma_f32_16x16x32_bf16 v[122:125], v[166:169], v[174:177], v[122:125]
	v_mfma_f32_16x16x32_bf16 v[110:113], v[146:149], v[192:195], v[110:113]
	v_mfma_f32_16x16x32_bf16 v[106:109], v[166:169], v[192:195], v[106:109]
	v_mfma_f32_16x16x32_bf16 v[94:97], v[146:149], v[200:203], v[94:97]
	v_mfma_f32_16x16x32_bf16 v[90:93], v[166:169], v[200:203], v[90:93]
	v_mfma_f32_16x16x32_bf16 v[78:81], v[146:149], v[208:211], v[78:81]
	v_mfma_f32_16x16x32_bf16 v[74:77], v[166:169], v[208:211], v[74:77]
	v_mfma_f32_16x16x32_bf16 v[126:129], v[162:165], v[188:191], v[126:129]
	v_mfma_f32_16x16x32_bf16 v[122:125], v[170:173], v[188:191], v[122:125]
	v_mfma_f32_16x16x32_bf16 v[110:113], v[162:165], v[196:199], v[110:113]
	v_mfma_f32_16x16x32_bf16 v[106:109], v[170:173], v[196:199], v[106:109]
	v_mfma_f32_16x16x32_bf16 v[94:97], v[162:165], v[204:207], v[94:97]
	v_mfma_f32_16x16x32_bf16 v[90:93], v[170:173], v[204:207], v[90:93]
	v_mfma_f32_16x16x32_bf16 v[78:81], v[162:165], v[212:215], v[78:81]
	v_mfma_f32_16x16x32_bf16 v[74:77], v[170:173], v[212:215], v[74:77]
	s_setprio 0
	s_barrier
	s_add_i32 s24, 0, 0x1c000
	s_add_i32 s25, s38, s45
	v_add_u32_e32 v0, s24, v152
	v_lshl_add_u64 v[150:151], v[150:151], 0, s[6:7]
	s_mov_b32 m0, s25
	ds_read_b128 v[216:219], v0
	ds_read_b128 v[220:223], v0 offset:1024
	ds_read_b128 v[224:227], v0 offset:2048
	ds_read_b128 v[228:231], v0 offset:3072
	global_load_lds_dwordx4 v[150:151], off
	v_lshl_add_u64 v[150:151], v[184:185], 0, s[6:7]
	s_add_i32 m0, s25, 0x2000
	s_nop 0
	global_load_lds_dwordx4 v[150:151], off
	s_waitcnt vmcnt(10)
	s_barrier
	s_waitcnt lgkmcnt(0)
	s_setprio 1
	s_waitcnt lgkmcnt(0)
	v_mfma_f32_16x16x32_bf16 v[118:121], v[216:219], v[174:177], v[118:121]
	v_mfma_f32_16x16x32_bf16 v[114:117], v[224:227], v[174:177], v[114:117]
	v_mfma_f32_16x16x32_bf16 v[102:105], v[216:219], v[192:195], v[102:105]
	v_mfma_f32_16x16x32_bf16 v[98:101], v[224:227], v[192:195], v[98:101]
	v_mfma_f32_16x16x32_bf16 v[86:89], v[216:219], v[200:203], v[86:89]
	v_mfma_f32_16x16x32_bf16 v[82:85], v[224:227], v[200:203], v[82:85]
	v_mfma_f32_16x16x32_bf16 v[70:73], v[216:219], v[208:211], v[70:73]
	v_mfma_f32_16x16x32_bf16 v[66:69], v[224:227], v[208:211], v[66:69]
	v_mfma_f32_16x16x32_bf16 v[118:121], v[220:223], v[188:191], v[118:121]
	v_mfma_f32_16x16x32_bf16 v[114:117], v[228:231], v[188:191], v[114:117]
	v_mfma_f32_16x16x32_bf16 v[102:105], v[220:223], v[196:199], v[102:105]
	v_mfma_f32_16x16x32_bf16 v[98:101], v[228:231], v[196:199], v[98:101]
	v_mfma_f32_16x16x32_bf16 v[86:89], v[220:223], v[204:207], v[86:89]
	v_mfma_f32_16x16x32_bf16 v[82:85], v[228:231], v[204:207], v[82:85]
	v_mfma_f32_16x16x32_bf16 v[70:73], v[220:223], v[212:215], v[70:73]
	v_mfma_f32_16x16x32_bf16 v[66:69], v[228:231], v[212:215], v[66:69]
	s_setprio 0
	s_mov_b32 m0, s50
	v_lshl_add_u64 v[150:151], v[186:187], 0, s[6:7]
	s_barrier
; __device__ __forceinline__ unsigned cvt_pk_bf16(float lo, float hi) { unsigned r; asm volatile("v_cvt_pk_bf16_f32 %0, %1, %2" : "=v"(r) : "v"(lo), "v"(hi)); return r; }
; #define PG8_STAGE(bufoff, gbase, voff) do { _Pragma("unroll") for (int _i = 0; _i < 2; ++_i) \
;         __builtin_amdgcn_global_load_lds((const unsigned*)((const char*)(gbase) + (voff)[_i]), (LAS unsigned*)(lds + (bufoff) + ldsw + _i * 8192), 16, 0, 0); } while (0)
; #define PG8_LDA(dst, b, h) do { _Pragma("unroll") for (int m = 0; m < 4; ++m) _Pragma("unroll") for (int k = 0; k < 2; ++k) dst[m][k] = *(const LAS bf16x8*)(lds + PG8_SA(b, h) + aoff + m * 2048 + k * 1024); } while (0)
; #define PG8_WAIT_V(n) asm volatile("s_waitcnt vmcnt(" #n ")" ::: "memory")
; #define PG8_WAIT_L(n) asm volatile("s_waitcnt lgkmcnt(" #n ")" ::: "memory")
; #define PG8_BAR __builtin_amdgcn_s_barrier()
; template <class Epi>
; __device__ __forceinline__ void gemm_phase(LAS unsigned char* lds, const Gemm g, const StaticOrder& S, const Epi& E) {
;     ...
;             PG8_LDA(At, 1, 1); PG8_STAGE(PG8_SA(1, 0), a3, voffA);
;             PG8_BAR; PG8_WAIT_L(0); PG8_MMA(1, 0, At, B0); PG8_BAR; PG8_SCHED;
;             PG8_STAGE(PG8_SB(1, 1), b3 + hstepB, voffB);
;             PG8_WAIT_V(6); PG8_BAR; PG8_MMA(1, 1, At, B1); PG8_BAR;
;         }
;         if constexpr (!Epi::AFTER_DRAIN) E(acc, cur, wr, wc, fr, fq, pre);
;     __device__ __forceinline__ void operator()(const f32x4 (&acc)[2][2][4][2], const Unit& u, int wr, int wc, int fr, int fq, const Pre& pp) const {
;         const int row0 = u.pm * BM + wr * 64 + fr, col0 = u.pn * BM + wc * 32 + 8 * fq;
;         const bool gm = (UG != nullptr) && (u.pn < DE / BM);
;         const float (&rs)[8] = pp.rs;
; #pragma unroll
;         for (int ai = 0; ai < 2; ++ai)
; #pragma unroll
;             for (int m = 0; m < 4; ++m) { const int r = row0 + ai * HALF + m * 16; const float inv = rsqrtf(rs[ai * 4 + m] * (1.0f / DM) + EPS);
; #pragma unroll
;                 for (int bj = 0; bj < 2; ++bj) { const f32x4 v0 = acc[ai][bj][m][0] * inv, v1 = acc[ai][bj][m][1] * inv; const int c = col0 + bj * HALF;
;                     u32x4 w; w.x = cvt_pk_bf16(v0[0], v0[1]); w.y = cvt_pk_bf16(v0[2], v0[3]); w.z = cvt_pk_bf16(v1[0], v1[1]); w.w = cvt_pk_bf16(v1[2], v1[3]);
;                     bf16_t* dst = gm ? UG + (size_t)(c >> 4) * GSTR + r * 16 + (c & 15) : O + (size_t)r * DE2 + c;
	ds_read_b128 v[174:177], v154 offset:49152
	ds_read_b128 v[188:191], v154 offset:50176
	ds_read_b128 v[192:195], v154 offset:51200
	ds_read_b128 v[196:199], v154 offset:52224
	ds_read_b128 v[200:203], v154 offset:53248
	ds_read_b128 v[204:207], v154 offset:54272
	ds_read_b128 v[208:211], v154 offset:55296
	ds_read_b128 v[212:215], v154 offset:56320
	global_load_lds_dwordx4 v[150:151], off
	v_lshl_add_u64 v[150:151], v[244:245], 0, s[6:7]
	s_mov_b32 m0, s51
	s_nop 0
	global_load_lds_dwordx4 v[150:151], off
	s_barrier
	s_waitcnt lgkmcnt(0)
	s_setprio 1
	s_waitcnt lgkmcnt(0)
	v_mfma_f32_16x16x32_bf16 v[62:65], v[146:149], v[174:177], v[62:65]
	v_mfma_f32_16x16x32_bf16 v[58:61], v[166:169], v[174:177], v[58:61]
	v_mfma_f32_16x16x32_bf16 v[46:49], v[146:149], v[192:195], v[46:49]
	v_mfma_f32_16x16x32_bf16 v[42:45], v[166:169], v[192:195], v[42:45]
	v_mfma_f32_16x16x32_bf16 v[30:33], v[146:149], v[200:203], v[30:33]
	v_mfma_f32_16x16x32_bf16 v[26:29], v[166:169], v[200:203], v[26:29]
	v_mfma_f32_16x16x32_bf16 v[14:17], v[146:149], v[208:211], v[14:17]
	v_mfma_f32_16x16x32_bf16 v[10:13], v[166:169], v[208:211], v[10:13]
	v_mfma_f32_16x16x32_bf16 v[62:65], v[162:165], v[188:191], v[62:65]
	v_mfma_f32_16x16x32_bf16 v[58:61], v[170:173], v[188:191], v[58:61]
	v_mfma_f32_16x16x32_bf16 v[46:49], v[162:165], v[196:199], v[46:49]
	v_mfma_f32_16x16x32_bf16 v[42:45], v[170:173], v[196:199], v[42:45]
	v_mfma_f32_16x16x32_bf16 v[30:33], v[162:165], v[204:207], v[30:33]
	v_mfma_f32_16x16x32_bf16 v[26:29], v[170:173], v[204:207], v[26:29]
	v_mfma_f32_16x16x32_bf16 v[14:17], v[162:165], v[212:215], v[14:17]
	v_mfma_f32_16x16x32_bf16 v[10:13], v[170:173], v[212:215], v[10:13]
	s_setprio 0
	s_barrier
	s_add_u32 s4, s4, 0x80080
	s_addc_u32 s5, s5, 0
	s_add_i32 s24, s24, s45
	v_lshl_add_u64 v[146:147], s[4:5], 0, v[134:135]
	s_mov_b32 m0, s24
	s_nop 0
	global_load_lds_dwordx4 v[146:147], off
	v_lshl_add_u64 v[146:147], s[4:5], 0, v[130:131]
	s_add_i32 m0, s24, 0x2000
	s_nop 0
	global_load_lds_dwordx4 v[146:147], off
	s_waitcnt vmcnt(8)
	s_barrier
	s_setprio 1
	v_mfma_f32_16x16x32_bf16 v[54:57], v[216:219], v[174:177], v[54:57]
	v_mfma_f32_16x16x32_bf16 v[50:53], v[224:227], v[174:177], v[50:53]
	v_mfma_f32_16x16x32_bf16 v[38:41], v[216:219], v[192:195], v[38:41]
	v_mfma_f32_16x16x32_bf16 v[34:37], v[224:227], v[192:195], v[34:37]
	v_mfma_f32_16x16x32_bf16 v[22:25], v[216:219], v[200:203], v[22:25]
	v_mfma_f32_16x16x32_bf16 v[18:21], v[224:227], v[200:203], v[18:21]
	v_mfma_f32_16x16x32_bf16 v[6:9], v[216:219], v[208:211], v[6:9]
	v_mfma_f32_16x16x32_bf16 v[2:5], v[224:227], v[208:211], v[2:5]
	v_mfma_f32_16x16x32_bf16 v[54:57], v[220:223], v[188:191], v[54:57]
	v_mfma_f32_16x16x32_bf16 v[50:53], v[228:231], v[188:191], v[50:53]
	v_mfma_f32_16x16x32_bf16 v[38:41], v[220:223], v[196:199], v[38:41]
	v_mfma_f32_16x16x32_bf16 v[34:37], v[228:231], v[196:199], v[34:37]
	v_mfma_f32_16x16x32_bf16 v[22:25], v[220:223], v[204:207], v[22:25]
	v_mfma_f32_16x16x32_bf16 v[18:21], v[228:231], v[204:207], v[18:21]
	v_mfma_f32_16x16x32_bf16 v[6:9], v[220:223], v[212:215], v[6:9]
	v_mfma_f32_16x16x32_bf16 v[2:5], v[228:231], v[212:215], v[2:5]
	s_setprio 0
	s_add_i32 s59, s59, 2
	s_add_u32 s57, s57, 0x100
	s_addc_u32 s58, s58, 0
	s_cmp_gt_u32 s59, 29
	s_mov_b64 s[38:39], s[42:43]
	s_barrier
	s_cbranch_scc0 .LBB0_158
	v_fmamk_f32 v0, v145, 0x3a000000, v233
	v_cmp_gt_f32_e32 vcc, s66, v0
	v_mul_f32_e32 v145, 0x4b800000, v0
	v_readlane_b32 s38, v254, 47
	v_cndmask_b32_e32 v0, v0, v145, vcc
	v_rsq_f32_e32 v0, v0
	v_lshl_add_u32 v146, s54, 8, v139
	s_cmp_gt_i32 s53, 15
	v_readlane_b32 s39, v254, 48
	v_mul_f32_e32 v145, 0x45800000, v0
	s_cselect_b64 s[4:5], -1, 0
	s_xor_b64 s[38:39], s[38:39], -1
	v_cndmask_b32_e32 v148, v0, v145, vcc
	v_ashrrev_i32_e32 v147, 31, v146
	s_or_b64 s[4:5], s[38:39], s[4:5]
	v_lshl_or_b32 v144, s53, 8, v153
	v_lshlrev_b64 v[150:151], 14, v[146:147]
	v_pk_mul_f32 v[128:129], v[148:149], v[128:129] op_sel_hi:[0,1]
	s_mov_b64 s[24:25], -1
	v_pk_mul_f32 v[126:127], v[148:149], v[126:127] op_sel_hi:[0,1]
	v_pk_mul_f32 v[162:163], v[148:149], v[124:125] op_sel_hi:[0,1]
	v_pk_mul_f32 v[124:125], v[148:149], v[122:123] op_sel_hi:[0,1]
	v_cvt_pk_bf16_f32 v122, v126, v127
	v_cvt_pk_bf16_f32 v123, v128, v129
	s_and_b64 vcc, exec, s[4:5]
	v_lshl_add_u64 v[128:129], s[16:17], 0, v[150:151]
	v_ashrrev_i32_e32 v145, 31, v144
	v_cvt_pk_bf16_f32 v124, v124, v125
	v_cvt_pk_bf16_f32 v125, v162, v163
	s_cbranch_vccz .LBB0_161
	v_lshl_add_u64 v[150:151], v[144:145], 1, v[128:129]
	s_mov_b64 s[24:25], 0

; #define PG8_STAGE(bufoff, gbase, voff) do { _Pragma("unroll") for (int _i = 0; _i < 2; ++_i) \
;         __builtin_amdgcn_global_load_lds((const unsigned*)((const char*)(gbase) + (voff)[_i]), (LAS unsigned*)(lds + (bufoff) + ldsw + _i * 8192), 16, 0, 0); } while (0)
; #define PG8_LDA(dst, b, h) do { _Pragma("unroll") for (int m = 0; m < 4; ++m) _Pragma("unroll") for (int k = 0; k < 2; ++k) dst[m][k] = *(const LAS bf16x8*)(lds + PG8_SA(b, h) + aoff + m * 2048 + k * 1024); } while (0)
; #define PG8_LDB(dst, b, h) do { _Pragma("unroll") for (int n = 0; n < 2; ++n) _Pragma("unroll") for (int k = 0; k < 2; ++k) dst[n][k] = *(const LAS bf16x8*)(lds + PG8_SB(b, h) + boff + n * 2048 + k * 1024); } while (0)
; #define PG8_MMA(ai, bj, At, Bt) do { __builtin_amdgcn_s_setprio(1); _Pragma("unroll") for (int m = 0; m < 4; ++m) _Pragma("unroll") for (int n = 0; n < 2; ++n) _Pragma("unroll") for (int k = 0; k < 2; ++k) \
;         acc[ai][bj][m][n] = __builtin_amdgcn_mfma_f32_16x16x32_bf16(Bt[n][k], At[m][k], acc[ai][bj][m][n], 0, 0, 0); __builtin_amdgcn_s_setprio(0); } while (0)
; #define PG8_WAIT_V(n) asm volatile("s_waitcnt vmcnt(" #n ")" ::: "memory")
; #define PG8_WAIT_L(n) asm volatile("s_waitcnt lgkmcnt(" #n ")" ::: "memory")
; template <class Epi>
; __device__ __forceinline__ void gemm_phase(LAS unsigned char* lds, const Gemm g, const StaticOrder& S, const Epi& E) {
;     ...
;         for (int t = 0; t < nt; t += 2) {
;             const bool last = (t == nt - 2);
;             const char* a1 = cA + (size_t)(t + 1) * kstepA;
;             const char* a2 = last ? nA : cA + (size_t)(t + 2) * kstepA; const char* b2 = last ? nB : cB + (size_t)(t + 2) * kstep;
;             const char* a3 = a2 + kstepA; const char* b3 = b2 + kstep;
;             PG8_LDB(B0, 0, 0); PG8_SCHED; PG8_LDA(At, 0, 0); PG8_STAGE(PG8_SA(1, 1), a1 + hstepA, voffA);
;             PG8_WAIT_L(8); PG8_BAR; PG8_WAIT_L(0); PG8_MMA(0, 0, At, B0); PG8_BAR; PG8_SCHED;
;             PG8_LDB(B1, 0, 1); PG8_STAGE(PG8_SB(0, 0), b2, voffB);
;             PG8_BAR; PG8_WAIT_L(0); PG8_MMA(0, 1, At, B1); PG8_BAR;
;             PG8_LDA(At, 0, 1); PG8_STAGE(PG8_SA(0, 0), a2, voffA);
;             PG8_BAR; PG8_WAIT_L(0); PG8_MMA(1, 0, At, B0); PG8_BAR; PG8_SCHED;
;             PG8_STAGE(PG8_SB(0, 1), b2 + hstepB, voffB);
;             PG8_WAIT_V(6); PG8_BAR; PG8_MMA(1, 1, At, B1); PG8_BAR;
.LBB0_359:
	s_add_u32 s26, s22, 0x100
	s_addc_u32 s27, s23, 0
	s_add_i32 s65, 0, 0x10000
	v_add_u32_e32 v86, s65, v209
	ds_read_b128 v[70:73], v86
	ds_read_b128 v[74:77], v86 offset:1024
	ds_read_b128 v[82:85], v86 offset:2048
	ds_read_b128 v[86:89], v86 offset:3072
	s_cmp_eq_u32 s64, 60
	s_cselect_b32 s25, s17, s27
	s_cselect_b32 s24, s60, s26
	s_cselect_b32 s37, s15, s63
	s_cselect_b32 s36, s61, s62
	v_lshl_add_u64 v[194:195], s[22:23], 0, v[190:191]
	s_add_i32 m0, s53, 0xc000
	ds_read_b128 v[146:149], v211
	ds_read_b128 v[150:153], v211 offset:1024
	ds_read_b128 v[154:157], v211 offset:2048
	ds_read_b128 v[158:161], v211 offset:3072
	ds_read_b128 v[162:165], v211 offset:4096
	ds_read_b128 v[166:169], v211 offset:5120
	ds_read_b128 v[170:173], v211 offset:6144
	ds_read_b128 v[184:187], v211 offset:7168
	global_load_lds_dwordx4 v[194:195], off
	v_lshl_add_u64 v[194:195], s[22:23], 0, v[192:193]
	s_add_i32 m0, s53, 0xe000
	s_nop 0
	global_load_lds_dwordx4 v[194:195], off
	s_waitcnt lgkmcnt(8)
	s_barrier
	s_waitcnt lgkmcnt(0)
	s_setprio 1
	s_waitcnt lgkmcnt(0)
	v_mfma_f32_16x16x32_bf16 v[142:145], v[70:73], v[146:149], v[142:145]
	v_mfma_f32_16x16x32_bf16 v[138:141], v[82:85], v[146:149], v[138:141]
	v_mfma_f32_16x16x32_bf16 v[126:129], v[70:73], v[154:157], v[126:129]
	v_mfma_f32_16x16x32_bf16 v[122:125], v[82:85], v[154:157], v[122:125]
	v_mfma_f32_16x16x32_bf16 v[110:113], v[70:73], v[162:165], v[110:113]
	v_mfma_f32_16x16x32_bf16 v[106:109], v[82:85], v[162:165], v[106:109]
	v_mfma_f32_16x16x32_bf16 v[94:97], v[70:73], v[170:173], v[94:97]
	v_mfma_f32_16x16x32_bf16 v[90:93], v[82:85], v[170:173], v[90:93]
	v_mfma_f32_16x16x32_bf16 v[142:145], v[74:77], v[150:153], v[142:145]
	v_mfma_f32_16x16x32_bf16 v[138:141], v[86:89], v[150:153], v[138:141]
	v_mfma_f32_16x16x32_bf16 v[126:129], v[74:77], v[158:161], v[126:129]
	v_mfma_f32_16x16x32_bf16 v[122:125], v[86:89], v[158:161], v[122:125]
	v_mfma_f32_16x16x32_bf16 v[110:113], v[74:77], v[166:169], v[110:113]
	v_mfma_f32_16x16x32_bf16 v[106:109], v[86:89], v[166:169], v[106:109]
	v_mfma_f32_16x16x32_bf16 v[94:97], v[74:77], v[184:187], v[94:97]
	v_mfma_f32_16x16x32_bf16 v[90:93], v[86:89], v[184:187], v[90:93]
	s_setprio 0
	s_barrier
	s_add_i32 s66, 0, 0x14000
	v_add_u32_e32 v206, s66, v209
	s_add_i32 s22, s65, s52
	ds_read_b128 v[194:197], v206
	ds_read_b128 v[198:201], v206 offset:1024
	ds_read_b128 v[202:205], v206 offset:2048
	ds_read_b128 v[212:215], v206 offset:3072
	v_lshl_add_u64 v[206:207], s[36:37], 0, v[0:1]
	s_mov_b32 m0, s22
	v_lshl_add_u64 v[216:217], s[36:37], 0, v[174:175]
	global_load_lds_dwordx4 v[206:207], off
	s_add_i32 m0, s22, 0x2000
	s_nop 0
	global_load_lds_dwordx4 v[216:217], off
	s_waitcnt vmcnt(10)
	s_barrier
	s_waitcnt lgkmcnt(0)
	s_setprio 1
	s_waitcnt lgkmcnt(0)
	v_mfma_f32_16x16x32_bf16 v[134:137], v[194:197], v[146:149], v[134:137]
	v_mfma_f32_16x16x32_bf16 v[130:133], v[202:205], v[146:149], v[130:133]
	v_mfma_f32_16x16x32_bf16 v[118:121], v[194:197], v[154:157], v[118:121]
	v_mfma_f32_16x16x32_bf16 v[114:117], v[202:205], v[154:157], v[114:117]
	v_mfma_f32_16x16x32_bf16 v[102:105], v[194:197], v[162:165], v[102:105]
	v_mfma_f32_16x16x32_bf16 v[98:101], v[202:205], v[162:165], v[98:101]
	v_mfma_f32_16x16x32_bf16 v[78:81], v[194:197], v[170:173], v[78:81]
	v_mfma_f32_16x16x32_bf16 v[66:69], v[202:205], v[170:173], v[66:69]
	v_mfma_f32_16x16x32_bf16 v[134:137], v[198:201], v[150:153], v[134:137]
	v_mfma_f32_16x16x32_bf16 v[130:133], v[212:215], v[150:153], v[130:133]
	v_mfma_f32_16x16x32_bf16 v[118:121], v[198:201], v[158:161], v[118:121]
	v_mfma_f32_16x16x32_bf16 v[114:117], v[212:215], v[158:161], v[114:117]
	v_mfma_f32_16x16x32_bf16 v[102:105], v[198:201], v[166:169], v[102:105]
	v_mfma_f32_16x16x32_bf16 v[98:101], v[212:215], v[166:169], v[98:101]
	v_mfma_f32_16x16x32_bf16 v[78:81], v[198:201], v[184:187], v[78:81]
	v_mfma_f32_16x16x32_bf16 v[66:69], v[212:215], v[184:187], v[66:69]
	s_setprio 0
	s_mov_b32 m0, s53
	v_lshl_add_u64 v[218:219], s[24:25], 0, v[188:189]
	s_barrier
	ds_read_b128 v[146:149], v211 offset:16384
	ds_read_b128 v[150:153], v211 offset:17408
	ds_read_b128 v[154:157], v211 offset:18432
	ds_read_b128 v[158:161], v211 offset:19456
	ds_read_b128 v[162:165], v211 offset:20480
	ds_read_b128 v[166:169], v211 offset:21504
	ds_read_b128 v[170:173], v211 offset:22528
	ds_read_b128 v[184:187], v211 offset:23552
	global_load_lds_dwordx4 v[218:219], off
	v_lshl_add_u64 v[220:221], s[24:25], 0, v[176:177]
	s_mov_b32 m0, s54
	s_nop 0
	global_load_lds_dwordx4 v[220:221], off
	s_barrier
	s_waitcnt lgkmcnt(0)
	s_setprio 1
	s_waitcnt lgkmcnt(0)
	v_mfma_f32_16x16x32_bf16 v[62:65], v[70:73], v[146:149], v[62:65]
	v_mfma_f32_16x16x32_bf16 v[58:61], v[82:85], v[146:149], v[58:61]
	v_mfma_f32_16x16x32_bf16 v[46:49], v[70:73], v[154:157], v[46:49]
	v_mfma_f32_16x16x32_bf16 v[42:45], v[82:85], v[154:157], v[42:45]
	v_mfma_f32_16x16x32_bf16 v[30:33], v[70:73], v[162:165], v[30:33]
	v_mfma_f32_16x16x32_bf16 v[26:29], v[82:85], v[162:165], v[26:29]
	v_mfma_f32_16x16x32_bf16 v[14:17], v[70:73], v[170:173], v[14:17]
	v_mfma_f32_16x16x32_bf16 v[10:13], v[82:85], v[170:173], v[10:13]
	v_mfma_f32_16x16x32_bf16 v[62:65], v[74:77], v[150:153], v[62:65]
	v_mfma_f32_16x16x32_bf16 v[58:61], v[86:89], v[150:153], v[58:61]
	v_mfma_f32_16x16x32_bf16 v[46:49], v[74:77], v[158:161], v[46:49]
	v_mfma_f32_16x16x32_bf16 v[42:45], v[86:89], v[158:161], v[42:45]
	v_mfma_f32_16x16x32_bf16 v[30:33], v[74:77], v[166:169], v[30:33]
	v_mfma_f32_16x16x32_bf16 v[26:29], v[86:89], v[166:169], v[26:29]
	v_mfma_f32_16x16x32_bf16 v[14:17], v[74:77], v[184:187], v[14:17]
	v_mfma_f32_16x16x32_bf16 v[10:13], v[86:89], v[184:187], v[10:13]
	s_setprio 0
	s_barrier
; #define PG8_STAGE(bufoff, gbase, voff) do { _Pragma("unroll") for (int _i = 0; _i < 2; ++_i) \
;         __builtin_amdgcn_global_load_lds((const unsigned*)((const char*)(gbase) + (voff)[_i]), (LAS unsigned*)(lds + (bufoff) + ldsw + _i * 8192), 16, 0, 0); } while (0)
; #define PG8_LDA(dst, b, h) do { _Pragma("unroll") for (int m = 0; m < 4; ++m) _Pragma("unroll") for (int k = 0; k < 2; ++k) dst[m][k] = *(const LAS bf16x8*)(lds + PG8_SA(b, h) + aoff + m * 2048 + k * 1024); } while (0)
; #define PG8_LDB(dst, b, h) do { _Pragma("unroll") for (int n = 0; n < 2; ++n) _Pragma("unroll") for (int k = 0; k < 2; ++k) dst[n][k] = *(const LAS bf16x8*)(lds + PG8_SB(b, h) + boff + n * 2048 + k * 1024); } while (0)
; #define PG8_MMA(ai, bj, At, Bt) do { __builtin_amdgcn_s_setprio(1); _Pragma("unroll") for (int m = 0; m < 4; ++m) _Pragma("unroll") for (int n = 0; n < 2; ++n) _Pragma("unroll") for (int k = 0; k < 2; ++k) \
;         acc[ai][bj][m][n] = __builtin_amdgcn_mfma_f32_16x16x32_bf16(Bt[n][k], At[m][k], acc[ai][bj][m][n], 0, 0, 0); __builtin_amdgcn_s_setprio(0); } while (0)
; #define PG8_WAIT_V(n) asm volatile("s_waitcnt vmcnt(" #n ")" ::: "memory")
; #define PG8_WAIT_L(n) asm volatile("s_waitcnt lgkmcnt(" #n ")" ::: "memory")
; #define PG8_BAR __builtin_amdgcn_s_barrier()
; #define PG8_SCHED __builtin_amdgcn_sched_barrier(0)
; template <class Epi>
; __device__ __forceinline__ void gemm_phase(LAS unsigned char* lds, const Gemm g, const StaticOrder& S, const Epi& E) {
;     ...
;             PG8_WAIT_V(6); PG8_BAR; PG8_MMA(1, 1, At, B1); PG8_BAR;
;             PG8_LDB(B0, 1, 0); PG8_SCHED; PG8_LDA(At, 1, 0); PG8_STAGE(PG8_SA(0, 1), a2 + hstepA, voffA);
;             PG8_WAIT_L(8); PG8_BAR; PG8_WAIT_L(0); PG8_MMA(0, 0, At, B0); PG8_BAR; PG8_SCHED;
;             PG8_LDB(B1, 1, 1); PG8_STAGE(PG8_SB(1, 0), b3, voffB);
;             PG8_BAR; PG8_WAIT_L(0); PG8_MMA(0, 1, At, B1); PG8_BAR;
;             PG8_LDA(At, 1, 1); PG8_STAGE(PG8_SA(1, 0), a3, voffA);
;             PG8_BAR; PG8_WAIT_L(0); PG8_MMA(1, 0, At, B0); PG8_BAR; PG8_SCHED;
	s_add_u32 s22, s36, 0x100000
	s_addc_u32 s23, s37, 0
	s_add_i32 s65, s66, s52
	v_lshl_add_u64 v[70:71], s[22:23], 0, v[0:1]
	s_mov_b32 m0, s65
	s_nop 0
	global_load_lds_dwordx4 v[70:71], off
	v_lshl_add_u64 v[70:71], s[22:23], 0, v[174:175]
	s_add_i32 m0, s65, 0x2000
	s_nop 0
	global_load_lds_dwordx4 v[70:71], off
	s_waitcnt vmcnt(8)
	s_barrier
	s_setprio 1
	v_mfma_f32_16x16x32_bf16 v[54:57], v[194:197], v[146:149], v[54:57]
	v_mfma_f32_16x16x32_bf16 v[50:53], v[202:205], v[146:149], v[50:53]
	v_mfma_f32_16x16x32_bf16 v[38:41], v[194:197], v[154:157], v[38:41]
	v_mfma_f32_16x16x32_bf16 v[34:37], v[202:205], v[154:157], v[34:37]
	v_mfma_f32_16x16x32_bf16 v[22:25], v[194:197], v[162:165], v[22:25]
	v_mfma_f32_16x16x32_bf16 v[18:21], v[202:205], v[162:165], v[18:21]
	v_mfma_f32_16x16x32_bf16 v[6:9], v[194:197], v[170:173], v[6:9]
	v_mfma_f32_16x16x32_bf16 v[2:5], v[202:205], v[170:173], v[2:5]
	v_mfma_f32_16x16x32_bf16 v[54:57], v[198:201], v[150:153], v[54:57]
	v_mfma_f32_16x16x32_bf16 v[50:53], v[212:215], v[150:153], v[50:53]
	v_mfma_f32_16x16x32_bf16 v[38:41], v[198:201], v[158:161], v[38:41]
	v_mfma_f32_16x16x32_bf16 v[34:37], v[212:215], v[158:161], v[34:37]
	v_mfma_f32_16x16x32_bf16 v[22:25], v[198:201], v[166:169], v[22:25]
	v_mfma_f32_16x16x32_bf16 v[18:21], v[212:215], v[166:169], v[18:21]
	v_mfma_f32_16x16x32_bf16 v[6:9], v[198:201], v[184:187], v[6:9]
	v_mfma_f32_16x16x32_bf16 v[2:5], v[212:215], v[184:187], v[2:5]
	s_setprio 0
	s_add_i32 s65, 0, 0x18000
	v_add_u32_e32 v86, s65, v209
	s_barrier
	ds_read_b128 v[70:73], v86
	ds_read_b128 v[74:77], v86 offset:1024
	ds_read_b128 v[82:85], v86 offset:2048
	ds_read_b128 v[86:89], v86 offset:3072
	s_add_u32 s22, s24, 0x100000
	s_addc_u32 s23, s25, 0
	s_mov_b32 m0, s55
	v_lshl_add_u64 v[194:195], s[22:23], 0, v[188:189]
	ds_read_b128 v[146:149], v211 offset:32768
	ds_read_b128 v[150:153], v211 offset:33792
	ds_read_b128 v[154:157], v211 offset:34816
	ds_read_b128 v[158:161], v211 offset:35840
	ds_read_b128 v[162:165], v211 offset:36864
	ds_read_b128 v[166:169], v211 offset:37888
	ds_read_b128 v[170:173], v211 offset:38912
	ds_read_b128 v[184:187], v211 offset:39936
	global_load_lds_dwordx4 v[194:195], off
	v_lshl_add_u64 v[194:195], s[22:23], 0, v[176:177]
	s_mov_b32 m0, s56
	s_nop 0
	global_load_lds_dwordx4 v[194:195], off
	s_waitcnt lgkmcnt(8)
	s_barrier
	s_waitcnt lgkmcnt(0)
	s_setprio 1
	s_waitcnt lgkmcnt(0)
	v_mfma_f32_16x16x32_bf16 v[142:145], v[70:73], v[146:149], v[142:145]
	v_mfma_f32_16x16x32_bf16 v[138:141], v[82:85], v[146:149], v[138:141]
	v_mfma_f32_16x16x32_bf16 v[126:129], v[70:73], v[154:157], v[126:129]
	v_mfma_f32_16x16x32_bf16 v[122:125], v[82:85], v[154:157], v[122:125]
	v_mfma_f32_16x16x32_bf16 v[110:113], v[70:73], v[162:165], v[110:113]
	v_mfma_f32_16x16x32_bf16 v[106:109], v[82:85], v[162:165], v[106:109]
	v_mfma_f32_16x16x32_bf16 v[94:97], v[70:73], v[170:173], v[94:97]
	v_mfma_f32_16x16x32_bf16 v[90:93], v[82:85], v[170:173], v[90:93]
	v_mfma_f32_16x16x32_bf16 v[142:145], v[74:77], v[150:153], v[142:145]
	v_mfma_f32_16x16x32_bf16 v[138:141], v[86:89], v[150:153], v[138:141]
	v_mfma_f32_16x16x32_bf16 v[126:129], v[74:77], v[158:161], v[126:129]
	v_mfma_f32_16x16x32_bf16 v[122:125], v[86:89], v[158:161], v[122:125]
	v_mfma_f32_16x16x32_bf16 v[110:113], v[74:77], v[166:169], v[110:113]
	v_mfma_f32_16x16x32_bf16 v[106:109], v[86:89], v[166:169], v[106:109]
	v_mfma_f32_16x16x32_bf16 v[94:97], v[74:77], v[184:187], v[94:97]
	v_mfma_f32_16x16x32_bf16 v[90:93], v[86:89], v[184:187], v[90:93]
	s_setprio 0
	s_barrier
	s_add_i32 s24, 0, 0x1c000
	s_add_i32 s22, s65, s52
	v_add_u32_e32 v212, s24, v209
	v_lshl_add_u64 v[206:207], v[206:207], 0, s[6:7]
	s_mov_b32 m0, s22
	ds_read_b128 v[194:197], v212
	ds_read_b128 v[198:201], v212 offset:1024
	ds_read_b128 v[202:205], v212 offset:2048
	ds_read_b128 v[212:215], v212 offset:3072
	global_load_lds_dwordx4 v[206:207], off
	v_lshl_add_u64 v[206:207], v[216:217], 0, s[6:7]
	s_add_i32 m0, s22, 0x2000
	s_nop 0
	global_load_lds_dwordx4 v[206:207], off
	s_waitcnt vmcnt(10)
	s_barrier
	s_waitcnt lgkmcnt(0)
	s_setprio 1
	s_waitcnt lgkmcnt(0)
	v_mfma_f32_16x16x32_bf16 v[134:137], v[194:197], v[146:149], v[134:137]
	v_mfma_f32_16x16x32_bf16 v[130:133], v[202:205], v[146:149], v[130:133]
	v_mfma_f32_16x16x32_bf16 v[118:121], v[194:197], v[154:157], v[118:121]
	v_mfma_f32_16x16x32_bf16 v[114:117], v[202:205], v[154:157], v[114:117]
	v_mfma_f32_16x16x32_bf16 v[102:105], v[194:197], v[162:165], v[102:105]
	v_mfma_f32_16x16x32_bf16 v[98:101], v[202:205], v[162:165], v[98:101]
	v_mfma_f32_16x16x32_bf16 v[78:81], v[194:197], v[170:173], v[78:81]
	v_mfma_f32_16x16x32_bf16 v[66:69], v[202:205], v[170:173], v[66:69]
	v_mfma_f32_16x16x32_bf16 v[134:137], v[198:201], v[150:153], v[134:137]
	v_mfma_f32_16x16x32_bf16 v[130:133], v[212:215], v[150:153], v[130:133]
	v_mfma_f32_16x16x32_bf16 v[118:121], v[198:201], v[158:161], v[118:121]
	v_mfma_f32_16x16x32_bf16 v[114:117], v[212:215], v[158:161], v[114:117]
	v_mfma_f32_16x16x32_bf16 v[102:105], v[198:201], v[166:169], v[102:105]
	v_mfma_f32_16x16x32_bf16 v[98:101], v[212:215], v[166:169], v[98:101]
	v_mfma_f32_16x16x32_bf16 v[78:81], v[198:201], v[184:187], v[78:81]
	v_mfma_f32_16x16x32_bf16 v[66:69], v[212:215], v[184:187], v[66:69]
	s_setprio 0
	s_mov_b32 m0, s58
	v_lshl_add_u64 v[206:207], v[218:219], 0, s[6:7]
	s_barrier
; __device__ __forceinline__ unsigned cvt_pk_bf16(float lo, float hi) { unsigned r; asm volatile("v_cvt_pk_bf16_f32 %0, %1, %2" : "=v"(r) : "v"(lo), "v"(hi)); return r; }
; #define PG8_BAR __builtin_amdgcn_s_barrier()
; template <class Epi>
; __device__ __forceinline__ void gemm_phase(LAS unsigned char* lds, const Gemm g, const StaticOrder& S, const Epi& E) {
;     ...
;             PG8_LDA(At, 1, 1); PG8_STAGE(PG8_SA(1, 0), a3, voffA);
;             PG8_BAR; PG8_WAIT_L(0); PG8_MMA(1, 0, At, B0); PG8_BAR; PG8_SCHED;
;             PG8_STAGE(PG8_SB(1, 1), b3 + hstepB, voffB);
;             PG8_WAIT_V(6); PG8_BAR; PG8_MMA(1, 1, At, B1); PG8_BAR;
;     __device__ __forceinline__ void operator()(const f32x4 (&acc)[2][2][4][2], const Unit& u, int wr, int wc, int fr, int fq, const Pre&) const {
;         const int row0 = u.pm * BM + wr * 64 + fr, col0 = u.pn * BM + wc * 32 + 4 * fq;
;         f32x4 gv[2][2];
; #pragma unroll
;         for (int bj = 0; bj < 2; ++bj)
; #pragma unroll
;             for (int n = 0; n < 2; ++n) gv[bj][n] = *(const f32x4*)(gnext + col0 + bj * HALF + n * 16);
;         f32x4 xb[2][2][2];
; #pragma unroll
;         for (int bj = 0; bj < 2; ++bj)
; #pragma unroll
;             for (int n = 0; n < 2; ++n) xb[0][bj][n] = *(const f32x4*)(Xin + (size_t)row0 * DM + col0 + bj * HALF + n * 16);
; #pragma unroll
;         for (int grp = 0; grp < 8; ++grp) { const int ai = grp >> 2, m = grp & 3, cur = grp & 1; const int r = row0 + ai * HALF + m * 16; float ss = 0.f;
;             if (grp < 7) { const int rn = row0 + ((grp + 1) >> 2) * HALF + ((grp + 1) & 3) * 16;
; #pragma unroll
;                 for (int bj = 0; bj < 2; ++bj)
; #pragma unroll
;                     for (int n = 0; n < 2; ++n) xb[cur ^ 1][bj][n] = *(const f32x4*)(Xin + (size_t)rn * DM + col0 + bj * HALF + n * 16); }
; #pragma unroll
;             for (int bj = 0; bj < 2; ++bj)
; #pragma unroll
;                 for (int n = 0; n < 2; ++n) { const int c = col0 + bj * HALF + n * 16;
;                     const f32x4 xv = xb[cur][bj][n] + acc[ai][bj][m][n]; *(f32x4*)(X + (size_t)r * DM + c) = xv;
;                     ss += (xv[0] * xv[0] + xv[1] * xv[1]) + (xv[2] * xv[2] + xv[3] * xv[3]);
;                     if (H) { const f32x4 hv = xv * gv[bj][n]; u32x2 w; w.x = cvt_pk_bf16(hv[0], hv[1]); w.y = cvt_pk_bf16(hv[2], hv[3]);
;                         *(u32x2*)(H + (size_t)r * DM + c) = w; } }
	ds_read_b128 v[146:149], v211 offset:49152
	ds_read_b128 v[150:153], v211 offset:50176
	ds_read_b128 v[154:157], v211 offset:51200
	ds_read_b128 v[158:161], v211 offset:52224
	ds_read_b128 v[162:165], v211 offset:53248
	ds_read_b128 v[166:169], v211 offset:54272
	ds_read_b128 v[170:173], v211 offset:55296
	ds_read_b128 v[184:187], v211 offset:56320
	global_load_lds_dwordx4 v[206:207], off
	v_lshl_add_u64 v[206:207], v[220:221], 0, s[6:7]
	s_mov_b32 m0, s59
	s_nop 0
	global_load_lds_dwordx4 v[206:207], off
	s_barrier
	s_waitcnt lgkmcnt(0)
	s_setprio 1
	s_waitcnt lgkmcnt(0)
	v_mfma_f32_16x16x32_bf16 v[62:65], v[70:73], v[146:149], v[62:65]
	v_mfma_f32_16x16x32_bf16 v[58:61], v[82:85], v[146:149], v[58:61]
	v_mfma_f32_16x16x32_bf16 v[46:49], v[70:73], v[154:157], v[46:49]
	v_mfma_f32_16x16x32_bf16 v[42:45], v[82:85], v[154:157], v[42:45]
	v_mfma_f32_16x16x32_bf16 v[30:33], v[70:73], v[162:165], v[30:33]
	v_mfma_f32_16x16x32_bf16 v[26:29], v[82:85], v[162:165], v[26:29]
	v_mfma_f32_16x16x32_bf16 v[14:17], v[70:73], v[170:173], v[14:17]
	v_mfma_f32_16x16x32_bf16 v[10:13], v[82:85], v[170:173], v[10:13]
	v_mfma_f32_16x16x32_bf16 v[62:65], v[74:77], v[150:153], v[62:65]
	v_mfma_f32_16x16x32_bf16 v[58:61], v[86:89], v[150:153], v[58:61]
	v_mfma_f32_16x16x32_bf16 v[46:49], v[74:77], v[158:161], v[46:49]
	v_mfma_f32_16x16x32_bf16 v[42:45], v[86:89], v[158:161], v[42:45]
	v_mfma_f32_16x16x32_bf16 v[30:33], v[74:77], v[166:169], v[30:33]
	v_mfma_f32_16x16x32_bf16 v[26:29], v[86:89], v[166:169], v[26:29]
	v_mfma_f32_16x16x32_bf16 v[14:17], v[74:77], v[184:187], v[14:17]
	v_mfma_f32_16x16x32_bf16 v[10:13], v[86:89], v[184:187], v[10:13]
	s_setprio 0
	s_barrier
	s_add_u32 s22, s36, 0x100080
	s_addc_u32 s23, s37, 0
	s_add_i32 s24, s24, s52
	v_lshl_add_u64 v[70:71], s[22:23], 0, v[0:1]
	s_mov_b32 m0, s24
	s_nop 0
	global_load_lds_dwordx4 v[70:71], off
	v_lshl_add_u64 v[70:71], s[22:23], 0, v[174:175]
	s_add_i32 m0, s24, 0x2000
	s_nop 0
	global_load_lds_dwordx4 v[70:71], off
	s_waitcnt vmcnt(8)
	s_barrier
	s_setprio 1
	v_mfma_f32_16x16x32_bf16 v[54:57], v[194:197], v[146:149], v[54:57]
	v_mfma_f32_16x16x32_bf16 v[50:53], v[202:205], v[146:149], v[50:53]
	v_mfma_f32_16x16x32_bf16 v[38:41], v[194:197], v[154:157], v[38:41]
	v_mfma_f32_16x16x32_bf16 v[34:37], v[202:205], v[154:157], v[34:37]
	v_mfma_f32_16x16x32_bf16 v[22:25], v[194:197], v[162:165], v[22:25]
	v_mfma_f32_16x16x32_bf16 v[18:21], v[202:205], v[162:165], v[18:21]
	v_mfma_f32_16x16x32_bf16 v[6:9], v[194:197], v[170:173], v[6:9]
	v_mfma_f32_16x16x32_bf16 v[2:5], v[202:205], v[170:173], v[2:5]
	v_mfma_f32_16x16x32_bf16 v[54:57], v[198:201], v[150:153], v[54:57]
	v_mfma_f32_16x16x32_bf16 v[50:53], v[212:215], v[150:153], v[50:53]
	v_mfma_f32_16x16x32_bf16 v[38:41], v[198:201], v[158:161], v[38:41]
	v_mfma_f32_16x16x32_bf16 v[34:37], v[212:215], v[158:161], v[34:37]
	v_mfma_f32_16x16x32_bf16 v[22:25], v[198:201], v[166:169], v[22:25]
	v_mfma_f32_16x16x32_bf16 v[18:21], v[212:215], v[166:169], v[18:21]
	v_mfma_f32_16x16x32_bf16 v[6:9], v[198:201], v[184:187], v[6:9]
	v_mfma_f32_16x16x32_bf16 v[2:5], v[212:215], v[184:187], v[2:5]
	s_setprio 0
	s_add_i32 s64, s64, 2
	s_add_u32 s62, s62, 0x100
	s_addc_u32 s63, s63, 0
	s_cmp_gt_u32 s64, 61
	s_mov_b64 s[22:23], s[26:27]
	s_barrier
	s_cbranch_scc0 .LBB0_359
	v_lshl_add_u32 v198, s44, 8, v208
	v_lshl_or_b32 v194, s45, 8, v210
	v_ashrrev_i32_e32 v199, 31, v198
	v_ashrrev_i32_e32 v195, 31, v194
	v_lshlrev_b64 v[204:205], 13, v[198:199]
	v_or_b32_e32 v202, 16, v198
	v_lshlrev_b64 v[196:197], 2, v[194:195]
	v_lshl_add_u64 v[146:147], s[0:1], 0, v[204:205]
	v_ashrrev_i32_e32 v203, 31, v202
	v_lshl_add_u64 v[70:71], s[4:5], 0, v[196:197]
	v_lshl_add_u64 v[146:147], v[146:147], 0, v[196:197]
	v_lshlrev_b64 v[200:201], 13, v[202:203]
	global_load_dwordx4 v[86:89], v[70:71], off
	global_load_dwordx4 v[82:85], v[70:71], off offset:64
	global_load_dwordx4 v[74:77], v[70:71], off offset:512
	s_nop 0
	global_load_dwordx4 v[70:73], v[70:71], off offset:576
	s_nop 0
	global_load_dwordx4 v[184:187], v[146:147], off
	global_load_dwordx4 v[170:173], v[146:147], off offset:64
	global_load_dwordx4 v[166:169], v[146:147], off offset:512
	global_load_dwordx4 v[162:165], v[146:147], off offset:576
	v_lshl_add_u64 v[146:147], s[0:1], 0, v[200:201]
	v_lshl_add_u64 v[146:147], v[146:147], 0, v[196:197]
	global_load_dwordx4 v[158:161], v[146:147], off
	global_load_dwordx4 v[154:157], v[146:147], off offset:64
	global_load_dwordx4 v[150:153], v[146:147], off offset:512
	s_nop 0
	global_load_dwordx4 v[146:149], v[146:147], off offset:576
	v_cndmask_b32_e64 v206, 0, 1, s[10:11]
	v_lshlrev_b64 v[212:213], 11, v[198:199]
	v_lshl_add_u64 v[204:205], s[48:49], 0, v[204:205]
	v_cmp_ne_u32_e64 s[44:45], 1, v206
	s_andn2_b64 vcc, exec, s[10:11]
	v_lshl_add_u64 v[206:207], v[204:205], 0, v[196:197]
	v_lshl_add_u64 v[204:205], v[212:213], 1, s[50:51]
	s_waitcnt vmcnt(0)
	v_pk_add_f32 v[144:145], v[144:145], v[186:187]
	v_pk_add_f32 v[142:143], v[142:143], v[184:185]
	global_store_dwordx4 v[206:207], v[142:145], off
	s_cbranch_vccnz .LBB0_362
	v_pk_mul_f32 v[184:185], v[88:89], v[144:145]
	v_pk_mul_f32 v[186:187], v[86:87], v[142:143]
	s_nop 0
	v_cvt_pk_bf16_f32 v186, v186, v187
	v_cvt_pk_bf16_f32 v187, v184, v185
	v_lshl_add_u64 v[184:185], v[194:195], 1, v[204:205]
	global_store_dwordx2 v[184:185], v[186:187], off

; #define PG8_STAGE(bufoff, gbase, voff) do { _Pragma("unroll") for (int _i = 0; _i < 2; ++_i) \
;         __builtin_amdgcn_global_load_lds((const unsigned*)((const char*)(gbase) + (voff)[_i]), (LAS unsigned*)(lds + (bufoff) + ldsw + _i * 8192), 16, 0, 0); } while (0)
; #define PG8_LDA(dst, b, h) do { _Pragma("unroll") for (int m = 0; m < 4; ++m) _Pragma("unroll") for (int k = 0; k < 2; ++k) dst[m][k] = *(const LAS bf16x8*)(lds + PG8_SA(b, h) + aoff + m * 2048 + k * 1024); } while (0)
; #define PG8_LDB(dst, b, h) do { _Pragma("unroll") for (int n = 0; n < 2; ++n) _Pragma("unroll") for (int k = 0; k < 2; ++k) dst[n][k] = *(const LAS bf16x8*)(lds + PG8_SB(b, h) + boff + n * 2048 + k * 1024); } while (0)
; #define PG8_MMA(ai, bj, At, Bt) do { __builtin_amdgcn_s_setprio(1); _Pragma("unroll") for (int m = 0; m < 4; ++m) _Pragma("unroll") for (int n = 0; n < 2; ++n) _Pragma("unroll") for (int k = 0; k < 2; ++k) \
;         acc[ai][bj][m][n] = __builtin_amdgcn_mfma_f32_16x16x32_bf16(Bt[n][k], At[m][k], acc[ai][bj][m][n], 0, 0, 0); __builtin_amdgcn_s_setprio(0); } while (0)
; #define PG8_WAIT_V(n) asm volatile("s_waitcnt vmcnt(" #n ")" ::: "memory")
; #define PG8_WAIT_L(n) asm volatile("s_waitcnt lgkmcnt(" #n ")" ::: "memory")
; template <class Epi>
; __device__ __forceinline__ void gemm_phase(LAS unsigned char* lds, const Gemm g, const StaticOrder& S, const Epi& E) {
;     ...
;         for (int t = 0; t < nt; t += 2) {
;             const bool last = (t == nt - 2);
;             const char* a1 = cA + (size_t)(t + 1) * kstepA;
;             const char* a2 = last ? nA : cA + (size_t)(t + 2) * kstepA; const char* b2 = last ? nB : cB + (size_t)(t + 2) * kstep;
;             const char* a3 = a2 + kstepA; const char* b3 = b2 + kstep;
;             PG8_LDB(B0, 0, 0); PG8_SCHED; PG8_LDA(At, 0, 0); PG8_STAGE(PG8_SA(1, 1), a1 + hstepA, voffA);
;             PG8_WAIT_L(8); PG8_BAR; PG8_WAIT_L(0); PG8_MMA(0, 0, At, B0); PG8_BAR; PG8_SCHED;
;             PG8_LDB(B1, 0, 1); PG8_STAGE(PG8_SB(0, 0), b2, voffB);
;             PG8_BAR; PG8_WAIT_L(0); PG8_MMA(0, 1, At, B1); PG8_BAR;
;             PG8_LDA(At, 0, 1); PG8_STAGE(PG8_SA(0, 0), a2, voffA);
;             PG8_BAR; PG8_WAIT_L(0); PG8_MMA(1, 0, At, B0); PG8_BAR; PG8_SCHED;
;             PG8_STAGE(PG8_SB(0, 1), b2 + hstepB, voffB);
;             PG8_WAIT_V(6); PG8_BAR; PG8_MMA(1, 1, At, B1); PG8_BAR;
.LBB0_472:
	s_add_u32 s22, s4, s20
	s_addc_u32 s23, s5, s21
	s_add_u32 s22, s22, 0x100
	s_addc_u32 s23, s23, 0
	s_add_u32 s62, s17, s20
	s_addc_u32 s63, s58, s21
	s_add_i32 s64, 0, 0x10000
	v_add_u32_e32 v160, s64, v146
	ds_read_b128 v[148:151], v160
	ds_read_b128 v[152:155], v160 offset:1024
	ds_read_b128 v[156:159], v160 offset:2048
	ds_read_b128 v[160:163], v160 offset:3072
	s_cmpk_eq_i32 s20, 0x1f00
	s_cselect_b32 s25, s11, s23
	s_cselect_b32 s24, s59, s22
	s_cselect_b32 s23, s9, s63
	s_cselect_b32 s22, s60, s62
	v_lshl_add_u64 v[176:177], v[140:141], 0, s[20:21]
	s_add_i32 m0, s48, 0xc000
	ds_read_b128 v[164:167], v147
	ds_read_b128 v[168:171], v147 offset:1024
	ds_read_b128 v[172:175], v147 offset:2048
	ds_read_b128 v[184:187], v147 offset:3072
	ds_read_b128 v[188:191], v147 offset:4096
	ds_read_b128 v[192:195], v147 offset:5120
	ds_read_b128 v[196:199], v147 offset:6144
	ds_read_b128 v[200:203], v147 offset:7168
	global_load_lds_dwordx4 v[176:177], off
	v_lshl_add_u64 v[176:177], v[142:143], 0, s[20:21]
	s_add_i32 m0, s48, 0xe000
	s_nop 0
	global_load_lds_dwordx4 v[176:177], off
	s_waitcnt lgkmcnt(8)
	s_barrier
	s_waitcnt lgkmcnt(0)
	s_setprio 1
	s_waitcnt lgkmcnt(0)
	v_mfma_f32_16x16x32_bf16 v[126:129], v[148:151], v[164:167], v[126:129]
	v_mfma_f32_16x16x32_bf16 v[122:125], v[156:159], v[164:167], v[122:125]
	v_mfma_f32_16x16x32_bf16 v[110:113], v[148:151], v[172:175], v[110:113]
	v_mfma_f32_16x16x32_bf16 v[106:109], v[156:159], v[172:175], v[106:109]
	v_mfma_f32_16x16x32_bf16 v[94:97], v[148:151], v[188:191], v[94:97]
	v_mfma_f32_16x16x32_bf16 v[90:93], v[156:159], v[188:191], v[90:93]
	v_mfma_f32_16x16x32_bf16 v[78:81], v[148:151], v[196:199], v[78:81]
	v_mfma_f32_16x16x32_bf16 v[74:77], v[156:159], v[196:199], v[74:77]
	v_mfma_f32_16x16x32_bf16 v[126:129], v[152:155], v[168:171], v[126:129]
	v_mfma_f32_16x16x32_bf16 v[122:125], v[160:163], v[168:171], v[122:125]
	v_mfma_f32_16x16x32_bf16 v[110:113], v[152:155], v[184:187], v[110:113]
	v_mfma_f32_16x16x32_bf16 v[106:109], v[160:163], v[184:187], v[106:109]
	v_mfma_f32_16x16x32_bf16 v[94:97], v[152:155], v[192:195], v[94:97]
	v_mfma_f32_16x16x32_bf16 v[90:93], v[160:163], v[192:195], v[90:93]
	v_mfma_f32_16x16x32_bf16 v[78:81], v[152:155], v[200:203], v[78:81]
	v_mfma_f32_16x16x32_bf16 v[74:77], v[160:163], v[200:203], v[74:77]
	s_setprio 0
	s_barrier
	s_add_i32 s65, 0, 0x14000
	v_add_u32_e32 v176, s65, v146
	s_add_i32 s62, s64, s39
	ds_read_b128 v[204:207], v176
	ds_read_b128 v[208:211], v176 offset:1024
	ds_read_b128 v[212:215], v176 offset:2048
	ds_read_b128 v[216:219], v176 offset:3072
	v_lshl_add_u64 v[176:177], s[22:23], 0, v[0:1]
	s_mov_b32 m0, s62
	v_lshl_add_u64 v[220:221], s[22:23], 0, v[130:131]
	global_load_lds_dwordx4 v[176:177], off
	s_add_i32 m0, s62, 0x2000
	s_nop 0
	global_load_lds_dwordx4 v[220:221], off
	s_waitcnt vmcnt(10)
	s_barrier
	s_waitcnt lgkmcnt(0)
	s_setprio 1
	s_waitcnt lgkmcnt(0)
	v_mfma_f32_16x16x32_bf16 v[118:121], v[204:207], v[164:167], v[118:121]
	v_mfma_f32_16x16x32_bf16 v[114:117], v[212:215], v[164:167], v[114:117]
	v_mfma_f32_16x16x32_bf16 v[102:105], v[204:207], v[172:175], v[102:105]
	v_mfma_f32_16x16x32_bf16 v[98:101], v[212:215], v[172:175], v[98:101]
	v_mfma_f32_16x16x32_bf16 v[86:89], v[204:207], v[188:191], v[86:89]
	v_mfma_f32_16x16x32_bf16 v[82:85], v[212:215], v[188:191], v[82:85]
	v_mfma_f32_16x16x32_bf16 v[70:73], v[204:207], v[196:199], v[70:73]
	v_mfma_f32_16x16x32_bf16 v[66:69], v[212:215], v[196:199], v[66:69]
	v_mfma_f32_16x16x32_bf16 v[118:121], v[208:211], v[168:171], v[118:121]
	v_mfma_f32_16x16x32_bf16 v[114:117], v[216:219], v[168:171], v[114:117]
	v_mfma_f32_16x16x32_bf16 v[102:105], v[208:211], v[184:187], v[102:105]
	v_mfma_f32_16x16x32_bf16 v[98:101], v[216:219], v[184:187], v[98:101]
	v_mfma_f32_16x16x32_bf16 v[86:89], v[208:211], v[192:195], v[86:89]
	v_mfma_f32_16x16x32_bf16 v[82:85], v[216:219], v[192:195], v[82:85]
	v_mfma_f32_16x16x32_bf16 v[70:73], v[208:211], v[200:203], v[70:73]
	v_mfma_f32_16x16x32_bf16 v[66:69], v[216:219], v[200:203], v[66:69]
	s_setprio 0
	s_mov_b32 m0, s48
	v_lshl_add_u64 v[222:223], s[24:25], 0, v[134:135]
	s_barrier
	ds_read_b128 v[164:167], v147 offset:16384
	ds_read_b128 v[168:171], v147 offset:17408
	ds_read_b128 v[172:175], v147 offset:18432
	ds_read_b128 v[184:187], v147 offset:19456
	ds_read_b128 v[188:191], v147 offset:20480
	ds_read_b128 v[192:195], v147 offset:21504
	ds_read_b128 v[196:199], v147 offset:22528
	ds_read_b128 v[200:203], v147 offset:23552
	global_load_lds_dwordx4 v[222:223], off
	v_lshl_add_u64 v[224:225], s[24:25], 0, v[132:133]
	s_mov_b32 m0, s49
	s_nop 0
	global_load_lds_dwordx4 v[224:225], off
	s_barrier
	s_waitcnt lgkmcnt(0)
	s_setprio 1
	s_waitcnt lgkmcnt(0)
	v_mfma_f32_16x16x32_bf16 v[62:65], v[148:151], v[164:167], v[62:65]
	v_mfma_f32_16x16x32_bf16 v[58:61], v[156:159], v[164:167], v[58:61]
	v_mfma_f32_16x16x32_bf16 v[46:49], v[148:151], v[172:175], v[46:49]
	v_mfma_f32_16x16x32_bf16 v[42:45], v[156:159], v[172:175], v[42:45]
	v_mfma_f32_16x16x32_bf16 v[30:33], v[148:151], v[188:191], v[30:33]
	v_mfma_f32_16x16x32_bf16 v[26:29], v[156:159], v[188:191], v[26:29]
	v_mfma_f32_16x16x32_bf16 v[18:21], v[148:151], v[196:199], v[18:21]
	v_mfma_f32_16x16x32_bf16 v[10:13], v[156:159], v[196:199], v[10:13]
	v_mfma_f32_16x16x32_bf16 v[62:65], v[152:155], v[168:171], v[62:65]
	v_mfma_f32_16x16x32_bf16 v[58:61], v[160:163], v[168:171], v[58:61]
	v_mfma_f32_16x16x32_bf16 v[46:49], v[152:155], v[184:187], v[46:49]
	v_mfma_f32_16x16x32_bf16 v[42:45], v[160:163], v[184:187], v[42:45]
	v_mfma_f32_16x16x32_bf16 v[30:33], v[152:155], v[192:195], v[30:33]
	v_mfma_f32_16x16x32_bf16 v[26:29], v[160:163], v[192:195], v[26:29]
	v_mfma_f32_16x16x32_bf16 v[18:21], v[152:155], v[200:203], v[18:21]
	v_mfma_f32_16x16x32_bf16 v[10:13], v[160:163], v[200:203], v[10:13]
	s_setprio 0
	s_barrier
; #define PG8_STAGE(bufoff, gbase, voff) do { _Pragma("unroll") for (int _i = 0; _i < 2; ++_i) \
;         __builtin_amdgcn_global_load_lds((const unsigned*)((const char*)(gbase) + (voff)[_i]), (LAS unsigned*)(lds + (bufoff) + ldsw + _i * 8192), 16, 0, 0); } while (0)
; #define PG8_LDA(dst, b, h) do { _Pragma("unroll") for (int m = 0; m < 4; ++m) _Pragma("unroll") for (int k = 0; k < 2; ++k) dst[m][k] = *(const LAS bf16x8*)(lds + PG8_SA(b, h) + aoff + m * 2048 + k * 1024); } while (0)
; #define PG8_LDB(dst, b, h) do { _Pragma("unroll") for (int n = 0; n < 2; ++n) _Pragma("unroll") for (int k = 0; k < 2; ++k) dst[n][k] = *(const LAS bf16x8*)(lds + PG8_SB(b, h) + boff + n * 2048 + k * 1024); } while (0)
; #define PG8_MMA(ai, bj, At, Bt) do { __builtin_amdgcn_s_setprio(1); _Pragma("unroll") for (int m = 0; m < 4; ++m) _Pragma("unroll") for (int n = 0; n < 2; ++n) _Pragma("unroll") for (int k = 0; k < 2; ++k) \
;         acc[ai][bj][m][n] = __builtin_amdgcn_mfma_f32_16x16x32_bf16(Bt[n][k], At[m][k], acc[ai][bj][m][n], 0, 0, 0); __builtin_amdgcn_s_setprio(0); } while (0)
; #define PG8_WAIT_V(n) asm volatile("s_waitcnt vmcnt(" #n ")" ::: "memory")
; #define PG8_WAIT_L(n) asm volatile("s_waitcnt lgkmcnt(" #n ")" ::: "memory")
; #define PG8_BAR __builtin_amdgcn_s_barrier()
; #define PG8_SCHED __builtin_amdgcn_sched_barrier(0)
; template <class Epi>
; __device__ __forceinline__ void gemm_phase(LAS unsigned char* lds, const Gemm g, const StaticOrder& S, const Epi& E) {
;     ...
;             PG8_WAIT_V(6); PG8_BAR; PG8_MMA(1, 1, At, B1); PG8_BAR;
;             PG8_LDB(B0, 1, 0); PG8_SCHED; PG8_LDA(At, 1, 0); PG8_STAGE(PG8_SA(0, 1), a2 + hstepA, voffA);
;             PG8_WAIT_L(8); PG8_BAR; PG8_WAIT_L(0); PG8_MMA(0, 0, At, B0); PG8_BAR; PG8_SCHED;
;             PG8_LDB(B1, 1, 1); PG8_STAGE(PG8_SB(1, 0), b3, voffB);
;             PG8_BAR; PG8_WAIT_L(0); PG8_MMA(0, 1, At, B1); PG8_BAR;
;             PG8_LDA(At, 1, 1); PG8_STAGE(PG8_SA(1, 0), a3, voffA);
;             PG8_BAR; PG8_WAIT_L(0); PG8_MMA(1, 0, At, B0); PG8_BAR; PG8_SCHED;
	s_add_u32 s62, s22, 0x100000
	s_addc_u32 s63, s23, 0
	s_add_i32 s64, s65, s39
	v_lshl_add_u64 v[148:149], s[62:63], 0, v[0:1]
	s_mov_b32 m0, s64
	s_nop 0
	global_load_lds_dwordx4 v[148:149], off
	v_lshl_add_u64 v[148:149], s[62:63], 0, v[130:131]
	s_add_i32 m0, s64, 0x2000
	s_nop 0
	global_load_lds_dwordx4 v[148:149], off
	s_waitcnt vmcnt(8)
	s_barrier
	s_setprio 1
	v_mfma_f32_16x16x32_bf16 v[54:57], v[204:207], v[164:167], v[54:57]
	v_mfma_f32_16x16x32_bf16 v[50:53], v[212:215], v[164:167], v[50:53]
	v_mfma_f32_16x16x32_bf16 v[38:41], v[204:207], v[172:175], v[38:41]
	v_mfma_f32_16x16x32_bf16 v[34:37], v[212:215], v[172:175], v[34:37]
	v_mfma_f32_16x16x32_bf16 v[22:25], v[204:207], v[188:191], v[22:25]
	v_mfma_f32_16x16x32_bf16 v[14:17], v[212:215], v[188:191], v[14:17]
	v_mfma_f32_16x16x32_bf16 v[6:9], v[204:207], v[196:199], v[6:9]
	v_mfma_f32_16x16x32_bf16 v[2:5], v[212:215], v[196:199], v[2:5]
	v_mfma_f32_16x16x32_bf16 v[54:57], v[208:211], v[168:171], v[54:57]
	v_mfma_f32_16x16x32_bf16 v[50:53], v[216:219], v[168:171], v[50:53]
	v_mfma_f32_16x16x32_bf16 v[38:41], v[208:211], v[184:187], v[38:41]
	v_mfma_f32_16x16x32_bf16 v[34:37], v[216:219], v[184:187], v[34:37]
	v_mfma_f32_16x16x32_bf16 v[22:25], v[208:211], v[192:195], v[22:25]
	v_mfma_f32_16x16x32_bf16 v[14:17], v[216:219], v[192:195], v[14:17]
	v_mfma_f32_16x16x32_bf16 v[6:9], v[208:211], v[200:203], v[6:9]
	v_mfma_f32_16x16x32_bf16 v[2:5], v[216:219], v[200:203], v[2:5]
	s_setprio 0
	s_add_i32 s62, 0, 0x18000
	v_add_u32_e32 v160, s62, v146
	s_barrier
	ds_read_b128 v[148:151], v160
	ds_read_b128 v[152:155], v160 offset:1024
	ds_read_b128 v[156:159], v160 offset:2048
	ds_read_b128 v[160:163], v160 offset:3072
	s_add_u32 s24, s24, 0x100000
	s_addc_u32 s25, s25, 0
	s_mov_b32 m0, s50
	v_lshl_add_u64 v[204:205], s[24:25], 0, v[134:135]
	ds_read_b128 v[164:167], v147 offset:32768
	ds_read_b128 v[168:171], v147 offset:33792
	ds_read_b128 v[172:175], v147 offset:34816
	ds_read_b128 v[184:187], v147 offset:35840
	ds_read_b128 v[188:191], v147 offset:36864
	ds_read_b128 v[192:195], v147 offset:37888
	ds_read_b128 v[196:199], v147 offset:38912
	ds_read_b128 v[200:203], v147 offset:39936
	global_load_lds_dwordx4 v[204:205], off
	v_lshl_add_u64 v[204:205], s[24:25], 0, v[132:133]
	s_mov_b32 m0, s51
	s_nop 0
	global_load_lds_dwordx4 v[204:205], off
	s_waitcnt lgkmcnt(8)
	s_barrier
	s_waitcnt lgkmcnt(0)
	s_setprio 1
	s_waitcnt lgkmcnt(0)
	v_mfma_f32_16x16x32_bf16 v[126:129], v[148:151], v[164:167], v[126:129]
	v_mfma_f32_16x16x32_bf16 v[122:125], v[156:159], v[164:167], v[122:125]
	v_mfma_f32_16x16x32_bf16 v[110:113], v[148:151], v[172:175], v[110:113]
	v_mfma_f32_16x16x32_bf16 v[106:109], v[156:159], v[172:175], v[106:109]
	v_mfma_f32_16x16x32_bf16 v[94:97], v[148:151], v[188:191], v[94:97]
	v_mfma_f32_16x16x32_bf16 v[90:93], v[156:159], v[188:191], v[90:93]
	v_mfma_f32_16x16x32_bf16 v[78:81], v[148:151], v[196:199], v[78:81]
	v_mfma_f32_16x16x32_bf16 v[74:77], v[156:159], v[196:199], v[74:77]
	v_mfma_f32_16x16x32_bf16 v[126:129], v[152:155], v[168:171], v[126:129]
	v_mfma_f32_16x16x32_bf16 v[122:125], v[160:163], v[168:171], v[122:125]
	v_mfma_f32_16x16x32_bf16 v[110:113], v[152:155], v[184:187], v[110:113]
	v_mfma_f32_16x16x32_bf16 v[106:109], v[160:163], v[184:187], v[106:109]
	v_mfma_f32_16x16x32_bf16 v[94:97], v[152:155], v[192:195], v[94:97]
	v_mfma_f32_16x16x32_bf16 v[90:93], v[160:163], v[192:195], v[90:93]
	v_mfma_f32_16x16x32_bf16 v[78:81], v[152:155], v[200:203], v[78:81]
	v_mfma_f32_16x16x32_bf16 v[74:77], v[160:163], v[200:203], v[74:77]
	s_setprio 0
	s_barrier
	s_add_i32 s24, 0, 0x1c000
	s_add_i32 s25, s62, s39
	v_add_u32_e32 v216, s24, v146
	v_lshl_add_u64 v[176:177], v[176:177], 0, s[6:7]
	s_mov_b32 m0, s25
	ds_read_b128 v[204:207], v216
	ds_read_b128 v[208:211], v216 offset:1024
	ds_read_b128 v[212:215], v216 offset:2048
	ds_read_b128 v[216:219], v216 offset:3072
	global_load_lds_dwordx4 v[176:177], off
	v_lshl_add_u64 v[176:177], v[220:221], 0, s[6:7]
	s_add_i32 m0, s25, 0x2000
	s_nop 0
	global_load_lds_dwordx4 v[176:177], off
	s_waitcnt vmcnt(10)
	s_barrier
	s_waitcnt lgkmcnt(0)
	s_setprio 1
	s_waitcnt lgkmcnt(0)
	v_mfma_f32_16x16x32_bf16 v[118:121], v[204:207], v[164:167], v[118:121]
	v_mfma_f32_16x16x32_bf16 v[114:117], v[212:215], v[164:167], v[114:117]
	v_mfma_f32_16x16x32_bf16 v[102:105], v[204:207], v[172:175], v[102:105]
	v_mfma_f32_16x16x32_bf16 v[98:101], v[212:215], v[172:175], v[98:101]
	v_mfma_f32_16x16x32_bf16 v[86:89], v[204:207], v[188:191], v[86:89]
	v_mfma_f32_16x16x32_bf16 v[82:85], v[212:215], v[188:191], v[82:85]
	v_mfma_f32_16x16x32_bf16 v[70:73], v[204:207], v[196:199], v[70:73]
	v_mfma_f32_16x16x32_bf16 v[66:69], v[212:215], v[196:199], v[66:69]
	v_mfma_f32_16x16x32_bf16 v[118:121], v[208:211], v[168:171], v[118:121]
	v_mfma_f32_16x16x32_bf16 v[114:117], v[216:219], v[168:171], v[114:117]
	v_mfma_f32_16x16x32_bf16 v[102:105], v[208:211], v[184:187], v[102:105]
	v_mfma_f32_16x16x32_bf16 v[98:101], v[216:219], v[184:187], v[98:101]
	v_mfma_f32_16x16x32_bf16 v[86:89], v[208:211], v[192:195], v[86:89]
	v_mfma_f32_16x16x32_bf16 v[82:85], v[216:219], v[192:195], v[82:85]
	v_mfma_f32_16x16x32_bf16 v[70:73], v[208:211], v[200:203], v[70:73]
	v_mfma_f32_16x16x32_bf16 v[66:69], v[216:219], v[200:203], v[66:69]
	s_setprio 0
	s_mov_b32 m0, s54
	v_lshl_add_u64 v[176:177], v[222:223], 0, s[6:7]
	s_barrier
; #define PG8_STAGE(bufoff, gbase, voff) do { _Pragma("unroll") for (int _i = 0; _i < 2; ++_i) \
;         __builtin_amdgcn_global_load_lds((const unsigned*)((const char*)(gbase) + (voff)[_i]), (LAS unsigned*)(lds + (bufoff) + ldsw + _i * 8192), 16, 0, 0); } while (0)
; #define PG8_LDA(dst, b, h) do { _Pragma("unroll") for (int m = 0; m < 4; ++m) _Pragma("unroll") for (int k = 0; k < 2; ++k) dst[m][k] = *(const LAS bf16x8*)(lds + PG8_SA(b, h) + aoff + m * 2048 + k * 1024); } while (0)
; #define PG8_MMA(ai, bj, At, Bt) do { __builtin_amdgcn_s_setprio(1); _Pragma("unroll") for (int m = 0; m < 4; ++m) _Pragma("unroll") for (int n = 0; n < 2; ++n) _Pragma("unroll") for (int k = 0; k < 2; ++k) \
;         acc[ai][bj][m][n] = __builtin_amdgcn_mfma_f32_16x16x32_bf16(Bt[n][k], At[m][k], acc[ai][bj][m][n], 0, 0, 0); __builtin_amdgcn_s_setprio(0); } while (0)
; #define PG8_WAIT_V(n) asm volatile("s_waitcnt vmcnt(" #n ")" ::: "memory")
; #define PG8_WAIT_L(n) asm volatile("s_waitcnt lgkmcnt(" #n ")" ::: "memory")
; #define PG8_BAR __builtin_amdgcn_s_barrier()
; #define PG8_SCHED __builtin_amdgcn_sched_barrier(0)
; template <class Epi>
; __device__ __forceinline__ void gemm_phase(LAS unsigned char* lds, const Gemm g, const StaticOrder& S, const Epi& E) {
;     ...
;             PG8_LDA(At, 1, 1); PG8_STAGE(PG8_SA(1, 0), a3, voffA);
;             PG8_BAR; PG8_WAIT_L(0); PG8_MMA(1, 0, At, B0); PG8_BAR; PG8_SCHED;
;             PG8_STAGE(PG8_SB(1, 1), b3 + hstepB, voffB);
;             PG8_WAIT_V(6); PG8_BAR; PG8_MMA(1, 1, At, B1); PG8_BAR;
;         }
;         if constexpr (!Epi::AFTER_DRAIN) E(acc, cur, wr, wc, fr, fq, pre);
;         if (!has_next) break;
; #pragma unroll
;         for (int a = 0; a < 2; ++a)
; #pragma unroll
;             for (int b = 0; b < 2; ++b)
; #pragma unroll
;                 for (int m = 0; m < 4; ++m)
; #pragma unroll
;                     for (int n = 0; n < 2; ++n) acc[a][b][m][n] = (f32x4){0.f, 0.f, 0.f, 0.f};
	ds_read_b128 v[164:167], v147 offset:49152
	ds_read_b128 v[168:171], v147 offset:50176
	ds_read_b128 v[172:175], v147 offset:51200
	ds_read_b128 v[184:187], v147 offset:52224
	ds_read_b128 v[188:191], v147 offset:53248
	ds_read_b128 v[192:195], v147 offset:54272
	ds_read_b128 v[196:199], v147 offset:55296
	ds_read_b128 v[200:203], v147 offset:56320
	global_load_lds_dwordx4 v[176:177], off
	v_lshl_add_u64 v[176:177], v[224:225], 0, s[6:7]
	s_mov_b32 m0, s55
	s_nop 0
	global_load_lds_dwordx4 v[176:177], off
	s_barrier
	s_waitcnt lgkmcnt(0)
	s_setprio 1
	s_waitcnt lgkmcnt(0)
	v_mfma_f32_16x16x32_bf16 v[62:65], v[148:151], v[164:167], v[62:65]
	v_mfma_f32_16x16x32_bf16 v[58:61], v[156:159], v[164:167], v[58:61]
	v_mfma_f32_16x16x32_bf16 v[46:49], v[148:151], v[172:175], v[46:49]
	v_mfma_f32_16x16x32_bf16 v[42:45], v[156:159], v[172:175], v[42:45]
	v_mfma_f32_16x16x32_bf16 v[30:33], v[148:151], v[188:191], v[30:33]
	v_mfma_f32_16x16x32_bf16 v[26:29], v[156:159], v[188:191], v[26:29]
	v_mfma_f32_16x16x32_bf16 v[18:21], v[148:151], v[196:199], v[18:21]
	v_mfma_f32_16x16x32_bf16 v[10:13], v[156:159], v[196:199], v[10:13]
	v_mfma_f32_16x16x32_bf16 v[62:65], v[152:155], v[168:171], v[62:65]
	v_mfma_f32_16x16x32_bf16 v[58:61], v[160:163], v[168:171], v[58:61]
	v_mfma_f32_16x16x32_bf16 v[46:49], v[152:155], v[184:187], v[46:49]
	v_mfma_f32_16x16x32_bf16 v[42:45], v[160:163], v[184:187], v[42:45]
	v_mfma_f32_16x16x32_bf16 v[30:33], v[152:155], v[192:195], v[30:33]
	v_mfma_f32_16x16x32_bf16 v[26:29], v[160:163], v[192:195], v[26:29]
	v_mfma_f32_16x16x32_bf16 v[18:21], v[152:155], v[200:203], v[18:21]
	v_mfma_f32_16x16x32_bf16 v[10:13], v[160:163], v[200:203], v[10:13]
	s_setprio 0
	s_barrier
	s_add_u32 s22, s22, 0x100080
	s_addc_u32 s23, s23, 0
	s_add_i32 s24, s24, s39
	v_lshl_add_u64 v[148:149], s[22:23], 0, v[0:1]
	s_mov_b32 m0, s24
	s_nop 0
	global_load_lds_dwordx4 v[148:149], off
	v_lshl_add_u64 v[148:149], s[22:23], 0, v[130:131]
	s_add_i32 m0, s24, 0x2000
	s_nop 0
	global_load_lds_dwordx4 v[148:149], off
	s_waitcnt vmcnt(8)
	s_barrier
	s_setprio 1
	v_mfma_f32_16x16x32_bf16 v[54:57], v[204:207], v[164:167], v[54:57]
	v_mfma_f32_16x16x32_bf16 v[50:53], v[212:215], v[164:167], v[50:53]
	v_mfma_f32_16x16x32_bf16 v[38:41], v[204:207], v[172:175], v[38:41]
	v_mfma_f32_16x16x32_bf16 v[34:37], v[212:215], v[172:175], v[34:37]
	v_mfma_f32_16x16x32_bf16 v[22:25], v[204:207], v[188:191], v[22:25]
	v_mfma_f32_16x16x32_bf16 v[14:17], v[212:215], v[188:191], v[14:17]
	v_mfma_f32_16x16x32_bf16 v[6:9], v[204:207], v[196:199], v[6:9]
	v_mfma_f32_16x16x32_bf16 v[2:5], v[212:215], v[196:199], v[2:5]
	v_mfma_f32_16x16x32_bf16 v[54:57], v[208:211], v[168:171], v[54:57]
	v_mfma_f32_16x16x32_bf16 v[50:53], v[216:219], v[168:171], v[50:53]
	v_mfma_f32_16x16x32_bf16 v[38:41], v[208:211], v[184:187], v[38:41]
	v_mfma_f32_16x16x32_bf16 v[34:37], v[216:219], v[184:187], v[34:37]
	v_mfma_f32_16x16x32_bf16 v[22:25], v[208:211], v[192:195], v[22:25]
	v_mfma_f32_16x16x32_bf16 v[14:17], v[216:219], v[192:195], v[14:17]
	v_mfma_f32_16x16x32_bf16 v[6:9], v[208:211], v[200:203], v[6:9]
	v_mfma_f32_16x16x32_bf16 v[2:5], v[216:219], v[200:203], v[2:5]
	s_setprio 0
	s_add_i32 s61, s61, 2
	s_add_u32 s20, s20, 0x100
	s_addc_u32 s21, s21, 0
	s_cmp_gt_u32 s61, 61
	s_barrier
	s_cbranch_scc0 .LBB0_472
	s_add_u32 s20, s17, 0xffffff00
	s_addc_u32 s21, s58, -1
	s_andn2_b64 vcc, exec, s[42:43]
	s_cbranch_vccnz .LBB0_463
	v_mov_b32_e32 v2, 0
	s_mov_b32 s57, s8
	s_mov_b32 s26, s10
	s_mov_b64 s[4:5], s[18:19]
	s_mov_b32 s56, s16
	v_mov_b32_e32 v3, v2
	v_mov_b32_e32 v4, v2
	v_mov_b32_e32 v5, v2
	v_mov_b32_e32 v6, v2
	v_mov_b32_e32 v7, v2
	v_mov_b32_e32 v8, v2
	v_mov_b32_e32 v9, v2
	v_mov_b32_e32 v14, v2
	v_mov_b32_e32 v15, v2
	v_mov_b32_e32 v16, v2
	v_mov_b32_e32 v17, v2
	v_mov_b32_e32 v22, v2
	v_mov_b32_e32 v23, v2
	v_mov_b32_e32 v24, v2
	v_mov_b32_e32 v25, v2
	v_mov_b32_e32 v34, v2
	v_mov_b32_e32 v35, v2
	v_mov_b32_e32 v36, v2
	v_mov_b32_e32 v37, v2
	v_mov_b32_e32 v38, v2
	v_mov_b32_e32 v39, v2
	v_mov_b32_e32 v40, v2
	v_mov_b32_e32 v41, v2
	v_mov_b32_e32 v50, v2
	v_mov_b32_e32 v51, v2
	v_mov_b32_e32 v52, v2
	v_mov_b32_e32 v53, v2
	v_mov_b32_e32 v54, v2
	v_mov_b32_e32 v55, v2
	v_mov_b32_e32 v56, v2
	v_mov_b32_e32 v57, v2
	v_mov_b32_e32 v10, v2
	v_mov_b32_e32 v11, v2
	v_mov_b32_e32 v12, v2
	v_mov_b32_e32 v13, v2
	v_mov_b32_e32 v18, v2
	v_mov_b32_e32 v19, v2
	v_mov_b32_e32 v20, v2
	v_mov_b32_e32 v21, v2
	v_mov_b32_e32 v26, v2
	v_mov_b32_e32 v27, v2
	v_mov_b32_e32 v28, v2
	v_mov_b32_e32 v29, v2
	v_mov_b32_e32 v30, v2
	v_mov_b32_e32 v31, v2
	v_mov_b32_e32 v32, v2
	v_mov_b32_e32 v33, v2
	v_mov_b32_e32 v42, v2
	v_mov_b32_e32 v43, v2
	v_mov_b32_e32 v44, v2
	v_mov_b32_e32 v45, v2
	v_mov_b32_e32 v46, v2
	v_mov_b32_e32 v47, v2
	v_mov_b32_e32 v48, v2
	v_mov_b32_e32 v49, v2
	v_mov_b32_e32 v58, v2
	v_mov_b32_e32 v59, v2
	v_mov_b32_e32 v60, v2
	v_mov_b32_e32 v61, v2
	v_mov_b32_e32 v62, v2
	v_mov_b32_e32 v63, v2
	v_mov_b32_e32 v64, v2
	v_mov_b32_e32 v65, v2
	v_mov_b32_e32 v66, v2
	v_mov_b32_e32 v67, v2
	v_mov_b32_e32 v68, v2
	v_mov_b32_e32 v69, v2
	v_mov_b32_e32 v70, v2
	v_mov_b32_e32 v71, v2
	v_mov_b32_e32 v72, v2
	v_mov_b32_e32 v73, v2
	v_mov_b32_e32 v82, v2
	v_mov_b32_e32 v83, v2
	v_mov_b32_e32 v84, v2
	v_mov_b32_e32 v85, v2
	v_mov_b32_e32 v86, v2
	v_mov_b32_e32 v87, v2
	v_mov_b32_e32 v88, v2
	v_mov_b32_e32 v89, v2
	v_mov_b32_e32 v98, v2
	v_mov_b32_e32 v99, v2
	v_mov_b32_e32 v100, v2
	v_mov_b32_e32 v101, v2
	v_mov_b32_e32 v102, v2
	v_mov_b32_e32 v103, v2
	v_mov_b32_e32 v104, v2
	v_mov_b32_e32 v105, v2
	v_mov_b32_e32 v114, v2
	v_mov_b32_e32 v115, v2
	v_mov_b32_e32 v116, v2
	v_mov_b32_e32 v117, v2
	v_mov_b32_e32 v118, v2
	v_mov_b32_e32 v119, v2
	v_mov_b32_e32 v120, v2
	v_mov_b32_e32 v121, v2
	v_mov_b32_e32 v74, v2
	v_mov_b32_e32 v75, v2
	v_mov_b32_e32 v76, v2
	v_mov_b32_e32 v77, v2
	v_mov_b32_e32 v78, v2
	v_mov_b32_e32 v79, v2
	v_mov_b32_e32 v80, v2
	v_mov_b32_e32 v81, v2
	v_mov_b32_e32 v90, v2
	v_mov_b32_e32 v91, v2
	v_mov_b32_e32 v92, v2
	v_mov_b32_e32 v93, v2
	v_mov_b32_e32 v94, v2
	v_mov_b32_e32 v95, v2
	v_mov_b32_e32 v96, v2
	v_mov_b32_e32 v97, v2
	v_mov_b32_e32 v106, v2
	v_mov_b32_e32 v107, v2
	v_mov_b32_e32 v108, v2
	v_mov_b32_e32 v109, v2
	v_mov_b32_e32 v110, v2
	v_mov_b32_e32 v111, v2
	v_mov_b32_e32 v112, v2
	v_mov_b32_e32 v113, v2
	v_mov_b32_e32 v122, v2
	v_mov_b32_e32 v123, v2
	v_mov_b32_e32 v124, v2
	v_mov_b32_e32 v125, v2
	v_mov_b32_e32 v126, v2
	v_mov_b32_e32 v127, v2
	v_mov_b32_e32 v128, v2
	v_mov_b32_e32 v129, v2
	s_andn2_b64 vcc, exec, s[40:41]
	s_cbranch_vccnz .LBB0_464

; #define PG8_STAGE(bufoff, gbase, voff) do { _Pragma("unroll") for (int _i = 0; _i < 2; ++_i) \
;         __builtin_amdgcn_global_load_lds((const unsigned*)((const char*)(gbase) + (voff)[_i]), (LAS unsigned*)(lds + (bufoff) + ldsw + _i * 8192), 16, 0, 0); } while (0)
; #define PG8_LDA(dst, b, h) do { _Pragma("unroll") for (int m = 0; m < 4; ++m) _Pragma("unroll") for (int k = 0; k < 2; ++k) dst[m][k] = *(const LAS bf16x8*)(lds + PG8_SA(b, h) + aoff + m * 2048 + k * 1024); } while (0)
; #define PG8_LDB(dst, b, h) do { _Pragma("unroll") for (int n = 0; n < 2; ++n) _Pragma("unroll") for (int k = 0; k < 2; ++k) dst[n][k] = *(const LAS bf16x8*)(lds + PG8_SB(b, h) + boff + n * 2048 + k * 1024); } while (0)
; #define PG8_MMA(ai, bj, At, Bt) do { __builtin_amdgcn_s_setprio(1); _Pragma("unroll") for (int m = 0; m < 4; ++m) _Pragma("unroll") for (int n = 0; n < 2; ++n) _Pragma("unroll") for (int k = 0; k < 2; ++k) \
;         acc[ai][bj][m][n] = __builtin_amdgcn_mfma_f32_16x16x32_bf16(Bt[n][k], At[m][k], acc[ai][bj][m][n], 0, 0, 0); __builtin_amdgcn_s_setprio(0); } while (0)
; #define PG8_WAIT_V(n) asm volatile("s_waitcnt vmcnt(" #n ")" ::: "memory")
; #define PG8_WAIT_L(n) asm volatile("s_waitcnt lgkmcnt(" #n ")" ::: "memory")
; template <class Epi>
; __device__ __forceinline__ void gemm_phase(LAS unsigned char* lds, const Gemm g, const StaticOrder& S, const Epi& E) {
;     ...
;         for (int t = 0; t < nt; t += 2) {
;             const bool last = (t == nt - 2);
;             const char* a1 = cA + (size_t)(t + 1) * kstepA;
;             const char* a2 = last ? nA : cA + (size_t)(t + 2) * kstepA; const char* b2 = last ? nB : cB + (size_t)(t + 2) * kstep;
;             const char* a3 = a2 + kstepA; const char* b3 = b2 + kstep;
;             PG8_LDB(B0, 0, 0); PG8_SCHED; PG8_LDA(At, 0, 0); PG8_STAGE(PG8_SA(1, 1), a1 + hstepA, voffA);
;             PG8_WAIT_L(8); PG8_BAR; PG8_WAIT_L(0); PG8_MMA(0, 0, At, B0); PG8_BAR; PG8_SCHED;
;             PG8_LDB(B1, 0, 1); PG8_STAGE(PG8_SB(0, 0), b2, voffB);
;             PG8_BAR; PG8_WAIT_L(0); PG8_MMA(0, 1, At, B1); PG8_BAR;
;             PG8_LDA(At, 0, 1); PG8_STAGE(PG8_SA(0, 0), a2, voffA);
;             PG8_BAR; PG8_WAIT_L(0); PG8_MMA(1, 0, At, B0); PG8_BAR; PG8_SCHED;
;             PG8_STAGE(PG8_SB(0, 1), b2 + hstepB, voffB);
;             PG8_WAIT_V(6); PG8_BAR; PG8_MMA(1, 1, At, B1); PG8_BAR;
.LBB0_603:
	s_add_u32 s8, s0, 0x100
	s_addc_u32 s9, s1, 0
	s_add_i32 s60, 0, 0x10000
	v_add_u32_e32 v102, s60, v229
	ds_read_b128 v[34:37], v102
	ds_read_b128 v[38:41], v102 offset:1024
	ds_read_b128 v[98:101], v102 offset:2048
	ds_read_b128 v[102:105], v102 offset:3072
	s_cmp_eq_u32 s59, 12
	s_cselect_b32 s11, s35, s9
	s_cselect_b32 s10, s36, s8
	s_cselect_b32 s5, s37, s58
	s_cselect_b32 s4, s51, s53
	v_lshl_add_u64 v[184:185], s[0:1], 0, v[194:195]
	s_add_i32 m0, s20, 0xc000
	ds_read_b128 v[106:109], v231
	ds_read_b128 v[118:121], v231 offset:1024
	ds_read_b128 v[130:133], v231 offset:2048
	ds_read_b128 v[142:145], v231 offset:3072
	ds_read_b128 v[154:157], v231 offset:4096
	ds_read_b128 v[158:161], v231 offset:5120
	ds_read_b128 v[170:173], v231 offset:6144
	ds_read_b128 v[174:177], v231 offset:7168
	global_load_lds_dwordx4 v[184:185], off
	v_lshl_add_u64 v[184:185], s[0:1], 0, v[196:197]
	s_add_i32 m0, s20, 0xe000
	s_nop 0
	global_load_lds_dwordx4 v[184:185], off
	s_waitcnt lgkmcnt(8)
	s_barrier
	s_waitcnt lgkmcnt(0)
	s_setprio 1
	s_waitcnt lgkmcnt(0)
	v_mfma_f32_16x16x32_bf16 v[166:169], v[34:37], v[106:109], v[166:169]
	v_mfma_f32_16x16x32_bf16 v[162:165], v[98:101], v[106:109], v[162:165]
	v_mfma_f32_16x16x32_bf16 v[150:153], v[34:37], v[130:133], v[150:153]
	v_mfma_f32_16x16x32_bf16 v[146:149], v[98:101], v[130:133], v[146:149]
	v_mfma_f32_16x16x32_bf16 v[138:141], v[34:37], v[154:157], v[138:141]
	v_mfma_f32_16x16x32_bf16 v[134:137], v[98:101], v[154:157], v[134:137]
	v_mfma_f32_16x16x32_bf16 v[126:129], v[34:37], v[170:173], v[126:129]
	v_mfma_f32_16x16x32_bf16 v[122:125], v[98:101], v[170:173], v[122:125]
	v_mfma_f32_16x16x32_bf16 v[166:169], v[38:41], v[118:121], v[166:169]
	v_mfma_f32_16x16x32_bf16 v[162:165], v[102:105], v[118:121], v[162:165]
	v_mfma_f32_16x16x32_bf16 v[150:153], v[38:41], v[142:145], v[150:153]
	v_mfma_f32_16x16x32_bf16 v[146:149], v[102:105], v[142:145], v[146:149]
	v_mfma_f32_16x16x32_bf16 v[138:141], v[38:41], v[158:161], v[138:141]
	v_mfma_f32_16x16x32_bf16 v[134:137], v[102:105], v[158:161], v[134:137]
	v_mfma_f32_16x16x32_bf16 v[126:129], v[38:41], v[174:177], v[126:129]
	v_mfma_f32_16x16x32_bf16 v[122:125], v[102:105], v[174:177], v[122:125]
	s_setprio 0
	s_barrier
	s_add_i32 s61, 0, 0x14000
	v_add_u32_e32 v184, s61, v229
	s_add_i32 s0, s60, s19
	ds_read_b128 v[198:201], v184
	ds_read_b128 v[202:205], v184 offset:1024
	ds_read_b128 v[206:209], v184 offset:2048
	ds_read_b128 v[210:213], v184 offset:3072
	v_lshl_add_u64 v[184:185], s[4:5], 0, v[0:1]
	s_mov_b32 m0, s0
	v_lshl_add_u64 v[186:187], s[4:5], 0, v[188:189]
	global_load_lds_dwordx4 v[184:185], off
	s_add_i32 m0, s0, 0x2000
	s_nop 0
	global_load_lds_dwordx4 v[186:187], off
	s_waitcnt vmcnt(10)
	s_barrier
	s_waitcnt lgkmcnt(0)
	s_setprio 1
	s_waitcnt lgkmcnt(0)
	v_mfma_f32_16x16x32_bf16 v[70:73], v[198:201], v[106:109], v[70:73]
	v_mfma_f32_16x16x32_bf16 v[66:69], v[206:209], v[106:109], v[66:69]
	v_mfma_f32_16x16x32_bf16 v[62:65], v[198:201], v[130:133], v[62:65]
	v_mfma_f32_16x16x32_bf16 v[58:61], v[206:209], v[130:133], v[58:61]
	v_mfma_f32_16x16x32_bf16 v[54:57], v[198:201], v[154:157], v[54:57]
	v_mfma_f32_16x16x32_bf16 v[50:53], v[206:209], v[154:157], v[50:53]
	v_mfma_f32_16x16x32_bf16 v[46:49], v[198:201], v[170:173], v[46:49]
	v_mfma_f32_16x16x32_bf16 v[42:45], v[206:209], v[170:173], v[42:45]
	v_mfma_f32_16x16x32_bf16 v[70:73], v[202:205], v[118:121], v[70:73]
	v_mfma_f32_16x16x32_bf16 v[66:69], v[210:213], v[118:121], v[66:69]
	v_mfma_f32_16x16x32_bf16 v[62:65], v[202:205], v[142:145], v[62:65]
	v_mfma_f32_16x16x32_bf16 v[58:61], v[210:213], v[142:145], v[58:61]
	v_mfma_f32_16x16x32_bf16 v[54:57], v[202:205], v[158:161], v[54:57]
	v_mfma_f32_16x16x32_bf16 v[50:53], v[210:213], v[158:161], v[50:53]
	v_mfma_f32_16x16x32_bf16 v[46:49], v[202:205], v[174:177], v[46:49]
	v_mfma_f32_16x16x32_bf16 v[42:45], v[210:213], v[174:177], v[42:45]
	s_setprio 0
	s_mov_b32 m0, s20
	v_lshl_add_u64 v[214:215], s[10:11], 0, v[192:193]
	s_barrier
	ds_read_b128 v[106:109], v231 offset:16384
	ds_read_b128 v[118:121], v231 offset:17408
	ds_read_b128 v[130:133], v231 offset:18432
	ds_read_b128 v[142:145], v231 offset:19456
	ds_read_b128 v[154:157], v231 offset:20480
	ds_read_b128 v[158:161], v231 offset:21504
	ds_read_b128 v[170:173], v231 offset:22528
	ds_read_b128 v[174:177], v231 offset:23552
	global_load_lds_dwordx4 v[214:215], off
	v_lshl_add_u64 v[216:217], s[10:11], 0, v[190:191]
	s_mov_b32 m0, s21
	s_nop 0
	global_load_lds_dwordx4 v[216:217], off
	s_barrier
	s_waitcnt lgkmcnt(0)
	s_setprio 1
	s_waitcnt lgkmcnt(0)
	v_mfma_f32_16x16x32_bf16 v[114:117], v[34:37], v[106:109], v[114:117]
	v_mfma_f32_16x16x32_bf16 v[110:113], v[98:101], v[106:109], v[110:113]
	v_mfma_f32_16x16x32_bf16 v[94:97], v[34:37], v[130:133], v[94:97]
	v_mfma_f32_16x16x32_bf16 v[90:93], v[98:101], v[130:133], v[90:93]
	v_mfma_f32_16x16x32_bf16 v[86:89], v[34:37], v[154:157], v[86:89]
	v_mfma_f32_16x16x32_bf16 v[82:85], v[98:101], v[154:157], v[82:85]
	v_mfma_f32_16x16x32_bf16 v[34:37], v[34:37], v[170:173], v[78:81]
	v_mfma_f32_16x16x32_bf16 v[114:117], v[38:41], v[118:121], v[114:117]
	v_mfma_f32_16x16x32_bf16 v[110:113], v[102:105], v[118:121], v[110:113]
	v_mfma_f32_16x16x32_bf16 v[94:97], v[38:41], v[142:145], v[94:97]
	v_mfma_f32_16x16x32_bf16 v[90:93], v[102:105], v[142:145], v[90:93]
	v_mfma_f32_16x16x32_bf16 v[86:89], v[38:41], v[158:161], v[86:89]
	v_mfma_f32_16x16x32_bf16 v[82:85], v[102:105], v[158:161], v[82:85]
	v_mfma_f32_16x16x32_bf16 v[34:37], v[38:41], v[174:177], v[34:37]
	v_mfma_f32_16x16x32_bf16 v[38:41], v[98:101], v[170:173], v[74:77]
	v_mfma_f32_16x16x32_bf16 v[38:41], v[102:105], v[174:177], v[38:41]
	s_setprio 0
	s_barrier
; #define PG8_STAGE(bufoff, gbase, voff) do { _Pragma("unroll") for (int _i = 0; _i < 2; ++_i) \
;         __builtin_amdgcn_global_load_lds((const unsigned*)((const char*)(gbase) + (voff)[_i]), (LAS unsigned*)(lds + (bufoff) + ldsw + _i * 8192), 16, 0, 0); } while (0)
; #define PG8_LDA(dst, b, h) do { _Pragma("unroll") for (int m = 0; m < 4; ++m) _Pragma("unroll") for (int k = 0; k < 2; ++k) dst[m][k] = *(const LAS bf16x8*)(lds + PG8_SA(b, h) + aoff + m * 2048 + k * 1024); } while (0)
; #define PG8_LDB(dst, b, h) do { _Pragma("unroll") for (int n = 0; n < 2; ++n) _Pragma("unroll") for (int k = 0; k < 2; ++k) dst[n][k] = *(const LAS bf16x8*)(lds + PG8_SB(b, h) + boff + n * 2048 + k * 1024); } while (0)
; #define PG8_MMA(ai, bj, At, Bt) do { __builtin_amdgcn_s_setprio(1); _Pragma("unroll") for (int m = 0; m < 4; ++m) _Pragma("unroll") for (int n = 0; n < 2; ++n) _Pragma("unroll") for (int k = 0; k < 2; ++k) \
;         acc[ai][bj][m][n] = __builtin_amdgcn_mfma_f32_16x16x32_bf16(Bt[n][k], At[m][k], acc[ai][bj][m][n], 0, 0, 0); __builtin_amdgcn_s_setprio(0); } while (0)
; #define PG8_WAIT_V(n) asm volatile("s_waitcnt vmcnt(" #n ")" ::: "memory")
; #define PG8_WAIT_L(n) asm volatile("s_waitcnt lgkmcnt(" #n ")" ::: "memory")
; #define PG8_BAR __builtin_amdgcn_s_barrier()
; #define PG8_SCHED __builtin_amdgcn_sched_barrier(0)
; template <class Epi>
; __device__ __forceinline__ void gemm_phase(LAS unsigned char* lds, const Gemm g, const StaticOrder& S, const Epi& E) {
;     ...
;             PG8_STAGE(PG8_SB(0, 1), b2 + hstepB, voffB);
;             PG8_WAIT_V(6); PG8_BAR; PG8_MMA(1, 1, At, B1); PG8_BAR;
;             PG8_LDB(B0, 1, 0); PG8_SCHED; PG8_LDA(At, 1, 0); PG8_STAGE(PG8_SA(0, 1), a2 + hstepA, voffA);
;             PG8_WAIT_L(8); PG8_BAR; PG8_WAIT_L(0); PG8_MMA(0, 0, At, B0); PG8_BAR; PG8_SCHED;
;             PG8_LDB(B1, 1, 1); PG8_STAGE(PG8_SB(1, 0), b3, voffB);
;             PG8_BAR; PG8_WAIT_L(0); PG8_MMA(0, 1, At, B1); PG8_BAR;
;             PG8_LDA(At, 1, 1); PG8_STAGE(PG8_SA(1, 0), a3, voffA);
;             PG8_BAR; PG8_WAIT_L(0); PG8_MMA(1, 0, At, B0); PG8_BAR; PG8_SCHED;
	s_add_u32 s0, s4, 0x40000
	s_addc_u32 s1, s5, 0
	s_add_i32 s60, s61, s19
	v_lshl_add_u64 v[74:75], s[0:1], 0, v[0:1]
	s_mov_b32 m0, s60
	s_nop 0
	global_load_lds_dwordx4 v[74:75], off
	v_lshl_add_u64 v[74:75], s[0:1], 0, v[188:189]
	s_add_i32 m0, s60, 0x2000
	s_nop 0
	global_load_lds_dwordx4 v[74:75], off
	s_waitcnt vmcnt(8)
	s_barrier
	s_setprio 1
	v_mfma_f32_16x16x32_bf16 v[30:33], v[198:201], v[106:109], v[30:33]
	v_mfma_f32_16x16x32_bf16 v[26:29], v[206:209], v[106:109], v[26:29]
	v_mfma_f32_16x16x32_bf16 v[22:25], v[198:201], v[130:133], v[22:25]
	v_mfma_f32_16x16x32_bf16 v[18:21], v[206:209], v[130:133], v[18:21]
	v_mfma_f32_16x16x32_bf16 v[14:17], v[198:201], v[154:157], v[14:17]
	v_mfma_f32_16x16x32_bf16 v[10:13], v[206:209], v[154:157], v[10:13]
	v_mfma_f32_16x16x32_bf16 v[6:9], v[198:201], v[170:173], v[6:9]
	v_mfma_f32_16x16x32_bf16 v[2:5], v[206:209], v[170:173], v[2:5]
	v_mfma_f32_16x16x32_bf16 v[30:33], v[202:205], v[118:121], v[30:33]
	v_mfma_f32_16x16x32_bf16 v[26:29], v[210:213], v[118:121], v[26:29]
	v_mfma_f32_16x16x32_bf16 v[22:25], v[202:205], v[142:145], v[22:25]
	v_mfma_f32_16x16x32_bf16 v[18:21], v[210:213], v[142:145], v[18:21]
	v_mfma_f32_16x16x32_bf16 v[14:17], v[202:205], v[158:161], v[14:17]
	v_mfma_f32_16x16x32_bf16 v[10:13], v[210:213], v[158:161], v[10:13]
	v_mfma_f32_16x16x32_bf16 v[6:9], v[202:205], v[174:177], v[6:9]
	v_mfma_f32_16x16x32_bf16 v[2:5], v[210:213], v[174:177], v[2:5]
	s_setprio 0
	s_add_i32 s60, 0, 0x18000
	v_add_u32_e32 v102, s60, v229
	s_barrier
	ds_read_b128 v[74:77], v102
	ds_read_b128 v[78:81], v102 offset:1024
	ds_read_b128 v[98:101], v102 offset:2048
	ds_read_b128 v[102:105], v102 offset:3072
	s_add_u32 s0, s10, 0x100000
	s_addc_u32 s1, s11, 0
	s_mov_b32 m0, s22
	v_lshl_add_u64 v[198:199], s[0:1], 0, v[192:193]
	ds_read_b128 v[106:109], v231 offset:32768
	ds_read_b128 v[118:121], v231 offset:33792
	ds_read_b128 v[130:133], v231 offset:34816
	ds_read_b128 v[142:145], v231 offset:35840
	ds_read_b128 v[154:157], v231 offset:36864
	ds_read_b128 v[158:161], v231 offset:37888
	ds_read_b128 v[170:173], v231 offset:38912
	ds_read_b128 v[174:177], v231 offset:39936
	global_load_lds_dwordx4 v[198:199], off
	v_lshl_add_u64 v[198:199], s[0:1], 0, v[190:191]
	s_mov_b32 m0, s23
	s_nop 0
	global_load_lds_dwordx4 v[198:199], off
	s_waitcnt lgkmcnt(8)
	s_barrier
	s_waitcnt lgkmcnt(0)
	s_setprio 1
	s_waitcnt lgkmcnt(0)
	v_mfma_f32_16x16x32_bf16 v[166:169], v[74:77], v[106:109], v[166:169]
	v_mfma_f32_16x16x32_bf16 v[162:165], v[98:101], v[106:109], v[162:165]
	v_mfma_f32_16x16x32_bf16 v[150:153], v[74:77], v[130:133], v[150:153]
	v_mfma_f32_16x16x32_bf16 v[146:149], v[98:101], v[130:133], v[146:149]
	v_mfma_f32_16x16x32_bf16 v[138:141], v[74:77], v[154:157], v[138:141]
	v_mfma_f32_16x16x32_bf16 v[134:137], v[98:101], v[154:157], v[134:137]
	v_mfma_f32_16x16x32_bf16 v[126:129], v[74:77], v[170:173], v[126:129]
	v_mfma_f32_16x16x32_bf16 v[122:125], v[98:101], v[170:173], v[122:125]
	v_mfma_f32_16x16x32_bf16 v[166:169], v[78:81], v[118:121], v[166:169]
	v_mfma_f32_16x16x32_bf16 v[162:165], v[102:105], v[118:121], v[162:165]
	v_mfma_f32_16x16x32_bf16 v[150:153], v[78:81], v[142:145], v[150:153]
	v_mfma_f32_16x16x32_bf16 v[146:149], v[102:105], v[142:145], v[146:149]
	v_mfma_f32_16x16x32_bf16 v[138:141], v[78:81], v[158:161], v[138:141]
	v_mfma_f32_16x16x32_bf16 v[134:137], v[102:105], v[158:161], v[134:137]
	v_mfma_f32_16x16x32_bf16 v[126:129], v[78:81], v[174:177], v[126:129]
	v_mfma_f32_16x16x32_bf16 v[122:125], v[102:105], v[174:177], v[122:125]
	s_setprio 0
	s_barrier
	s_add_i32 s10, 0, 0x1c000
	s_add_i32 s0, s60, s19
	v_add_u32_e32 v210, s10, v229
	v_lshl_add_u64 v[184:185], v[184:185], 0, s[6:7]
	s_mov_b32 m0, s0
	ds_read_b128 v[198:201], v210
	ds_read_b128 v[202:205], v210 offset:1024
	ds_read_b128 v[206:209], v210 offset:2048
	ds_read_b128 v[210:213], v210 offset:3072
	global_load_lds_dwordx4 v[184:185], off
	v_lshl_add_u64 v[184:185], v[186:187], 0, s[6:7]
	s_add_i32 m0, s0, 0x2000
	s_nop 0
	global_load_lds_dwordx4 v[184:185], off
	s_waitcnt vmcnt(10)
	s_barrier
	s_waitcnt lgkmcnt(0)
	s_setprio 1
	s_waitcnt lgkmcnt(0)
	v_mfma_f32_16x16x32_bf16 v[70:73], v[198:201], v[106:109], v[70:73]
	v_mfma_f32_16x16x32_bf16 v[66:69], v[206:209], v[106:109], v[66:69]
	v_mfma_f32_16x16x32_bf16 v[62:65], v[198:201], v[130:133], v[62:65]
	v_mfma_f32_16x16x32_bf16 v[58:61], v[206:209], v[130:133], v[58:61]
	v_mfma_f32_16x16x32_bf16 v[54:57], v[198:201], v[154:157], v[54:57]
	v_mfma_f32_16x16x32_bf16 v[50:53], v[206:209], v[154:157], v[50:53]
	v_mfma_f32_16x16x32_bf16 v[46:49], v[198:201], v[170:173], v[46:49]
	v_mfma_f32_16x16x32_bf16 v[42:45], v[206:209], v[170:173], v[42:45]
	v_mfma_f32_16x16x32_bf16 v[70:73], v[202:205], v[118:121], v[70:73]
	v_mfma_f32_16x16x32_bf16 v[66:69], v[210:213], v[118:121], v[66:69]
	v_mfma_f32_16x16x32_bf16 v[62:65], v[202:205], v[142:145], v[62:65]
	v_mfma_f32_16x16x32_bf16 v[58:61], v[210:213], v[142:145], v[58:61]
	v_mfma_f32_16x16x32_bf16 v[54:57], v[202:205], v[158:161], v[54:57]
	v_mfma_f32_16x16x32_bf16 v[50:53], v[210:213], v[158:161], v[50:53]
	v_mfma_f32_16x16x32_bf16 v[46:49], v[202:205], v[174:177], v[46:49]
	v_mfma_f32_16x16x32_bf16 v[42:45], v[210:213], v[174:177], v[42:45]
	s_setprio 0
	s_mov_b32 m0, s24
	v_lshl_add_u64 v[184:185], v[214:215], 0, s[6:7]
	s_barrier
	ds_read_b128 v[106:109], v231 offset:49152
	ds_read_b128 v[118:121], v231 offset:50176
	ds_read_b128 v[130:133], v231 offset:51200
	ds_read_b128 v[142:145], v231 offset:52224
	ds_read_b128 v[154:157], v231 offset:53248
	ds_read_b128 v[158:161], v231 offset:54272
	ds_read_b128 v[170:173], v231 offset:55296
	ds_read_b128 v[174:177], v231 offset:56320
	global_load_lds_dwordx4 v[184:185], off
	v_lshl_add_u64 v[184:185], v[216:217], 0, s[6:7]
	s_mov_b32 m0, s25
	s_nop 0
	global_load_lds_dwordx4 v[184:185], off
	s_barrier
; #define PG8_STAGE(bufoff, gbase, voff) do { _Pragma("unroll") for (int _i = 0; _i < 2; ++_i) \
;         __builtin_amdgcn_global_load_lds((const unsigned*)((const char*)(gbase) + (voff)[_i]), (LAS unsigned*)(lds + (bufoff) + ldsw + _i * 8192), 16, 0, 0); } while (0)
; #define PG8_MMA(ai, bj, At, Bt) do { __builtin_amdgcn_s_setprio(1); _Pragma("unroll") for (int m = 0; m < 4; ++m) _Pragma("unroll") for (int n = 0; n < 2; ++n) _Pragma("unroll") for (int k = 0; k < 2; ++k) \
;         acc[ai][bj][m][n] = __builtin_amdgcn_mfma_f32_16x16x32_bf16(Bt[n][k], At[m][k], acc[ai][bj][m][n], 0, 0, 0); __builtin_amdgcn_s_setprio(0); } while (0)
; #define PG8_WAIT_V(n) asm volatile("s_waitcnt vmcnt(" #n ")" ::: "memory")
; #define PG8_WAIT_L(n) asm volatile("s_waitcnt lgkmcnt(" #n ")" ::: "memory")
; #define PG8_BAR __builtin_amdgcn_s_barrier()
; #define PG8_SCHED __builtin_amdgcn_sched_barrier(0)
; template <class Epi>
; __device__ __forceinline__ void gemm_phase(LAS unsigned char* lds, const Gemm g, const StaticOrder& S, const Epi& E) {
;     ...
;             PG8_BAR; PG8_WAIT_L(0); PG8_MMA(1, 0, At, B0); PG8_BAR; PG8_SCHED;
;             PG8_STAGE(PG8_SB(1, 1), b3 + hstepB, voffB);
;             PG8_WAIT_V(6); PG8_BAR; PG8_MMA(1, 1, At, B1); PG8_BAR;
;     __device__ __forceinline__ void operator()(const f32x4 (&acc)[2][2][4][2], const Unit& u, int wr, int wc, int fr, int fq, const Pre&) const {
;         const int row0 = u.pm * BM + wr * 64 + fr, col0 = u.pn * BM + wc * 32 + 8 * fq;
;         f32x4 sc[2][2];
; #pragma unroll
;         for (int bj = 0; bj < 2; ++bj) { sc[bj][0] = *(const f32x4*)(scale + col0 + bj * HALF); sc[bj][1] = *(const f32x4*)(scale + col0 + bj * HALF + 4); }
; #pragma unroll
;         for (int bj = 0; bj < 2; ++bj) { const int c = col0 + bj * HALF;
;             u32x4 zv[8];
; #pragma unroll
;             for (int g8 = 0; g8 < 8; ++g8) zv[g8] = *(const u32x4*)(Z + (size_t)(row0 + (g8 >> 2) * HALF + (g8 & 3) * 16) * DE2 + c);
	s_waitcnt lgkmcnt(0)
	s_setprio 1
	s_waitcnt lgkmcnt(0)
	v_mfma_f32_16x16x32_bf16 v[114:117], v[74:77], v[106:109], v[114:117]
	v_mfma_f32_16x16x32_bf16 v[94:97], v[74:77], v[130:133], v[94:97]
	v_mfma_f32_16x16x32_bf16 v[86:89], v[74:77], v[154:157], v[86:89]
	v_mfma_f32_16x16x32_bf16 v[34:37], v[74:77], v[170:173], v[34:37]
	v_mfma_f32_16x16x32_bf16 v[114:117], v[78:81], v[118:121], v[114:117]
	v_mfma_f32_16x16x32_bf16 v[110:113], v[98:101], v[106:109], v[110:113]
	v_mfma_f32_16x16x32_bf16 v[94:97], v[78:81], v[142:145], v[94:97]
	v_mfma_f32_16x16x32_bf16 v[90:93], v[98:101], v[130:133], v[90:93]
	v_mfma_f32_16x16x32_bf16 v[86:89], v[78:81], v[158:161], v[86:89]
	v_mfma_f32_16x16x32_bf16 v[82:85], v[98:101], v[154:157], v[82:85]
	v_mfma_f32_16x16x32_bf16 v[78:81], v[78:81], v[174:177], v[34:37]
	v_mfma_f32_16x16x32_bf16 v[34:37], v[98:101], v[170:173], v[38:41]
	v_mfma_f32_16x16x32_bf16 v[110:113], v[102:105], v[118:121], v[110:113]
	v_mfma_f32_16x16x32_bf16 v[90:93], v[102:105], v[142:145], v[90:93]
	v_mfma_f32_16x16x32_bf16 v[82:85], v[102:105], v[158:161], v[82:85]
	v_mfma_f32_16x16x32_bf16 v[74:77], v[102:105], v[174:177], v[34:37]
	s_setprio 0
	s_barrier
	s_add_u32 s0, s4, 0x40080
	s_addc_u32 s1, s5, 0
	s_add_i32 s4, s10, s19
	v_lshl_add_u64 v[34:35], s[0:1], 0, v[0:1]
	s_mov_b32 m0, s4
	s_nop 0
	global_load_lds_dwordx4 v[34:35], off
	v_lshl_add_u64 v[34:35], s[0:1], 0, v[188:189]
	s_add_i32 m0, s4, 0x2000
	s_nop 0
	global_load_lds_dwordx4 v[34:35], off
	s_waitcnt vmcnt(8)
	s_barrier
	s_setprio 1
	v_mfma_f32_16x16x32_bf16 v[30:33], v[198:201], v[106:109], v[30:33]
	v_mfma_f32_16x16x32_bf16 v[26:29], v[206:209], v[106:109], v[26:29]
	v_mfma_f32_16x16x32_bf16 v[22:25], v[198:201], v[130:133], v[22:25]
	v_mfma_f32_16x16x32_bf16 v[18:21], v[206:209], v[130:133], v[18:21]
	v_mfma_f32_16x16x32_bf16 v[14:17], v[198:201], v[154:157], v[14:17]
	v_mfma_f32_16x16x32_bf16 v[10:13], v[206:209], v[154:157], v[10:13]
	v_mfma_f32_16x16x32_bf16 v[6:9], v[198:201], v[170:173], v[6:9]
	v_mfma_f32_16x16x32_bf16 v[2:5], v[206:209], v[170:173], v[2:5]
	v_mfma_f32_16x16x32_bf16 v[30:33], v[202:205], v[118:121], v[30:33]
	v_mfma_f32_16x16x32_bf16 v[26:29], v[210:213], v[118:121], v[26:29]
	v_mfma_f32_16x16x32_bf16 v[22:25], v[202:205], v[142:145], v[22:25]
	v_mfma_f32_16x16x32_bf16 v[18:21], v[210:213], v[142:145], v[18:21]
	v_mfma_f32_16x16x32_bf16 v[14:17], v[202:205], v[158:161], v[14:17]
	v_mfma_f32_16x16x32_bf16 v[10:13], v[210:213], v[158:161], v[10:13]
	v_mfma_f32_16x16x32_bf16 v[6:9], v[202:205], v[174:177], v[6:9]
	v_mfma_f32_16x16x32_bf16 v[2:5], v[210:213], v[174:177], v[2:5]
	s_setprio 0
	s_add_i32 s59, s59, 2
	s_add_u32 s53, s53, 0x100
	s_addc_u32 s58, s58, 0
	s_cmp_gt_u32 s59, 13
	s_mov_b64 s[0:1], s[8:9]
	s_barrier
	s_cbranch_scc0 .LBB0_603
	v_lshl_or_b32 v200, s34, 8, v230
	v_ashrrev_i32_e32 v201, 31, v200
	v_lshl_add_u32 v226, s27, 8, v228
	v_lshlrev_b64 v[216:217], 1, v[200:201]
	v_ashrrev_i32_e32 v227, 31, v226
	v_lshl_add_u64 v[106:107], s[46:47], 0, v[216:217]
	v_lshlrev_b64 v[204:205], 14, v[226:227]
	v_lshl_add_u64 v[38:39], v[200:201], 2, s[48:49]
	v_lshl_add_u64 v[108:109], v[106:107], 0, v[204:205]
	global_load_dwordx4 v[98:101], v[38:39], off offset:16
	global_load_dwordx4 v[102:105], v[38:39], off
	global_load_dwordx4 v[34:37], v[38:39], off offset:528
	s_nop 0
	global_load_dwordx4 v[38:41], v[38:39], off offset:512
	v_or_b32_e32 v224, 16, v226
	global_load_dwordx4 v[174:177], v[108:109], off
	v_ashrrev_i32_e32 v225, 31, v224
	v_or_b32_e32 v222, 32, v226
	v_lshlrev_b64 v[198:199], 14, v[224:225]
	v_ashrrev_i32_e32 v223, 31, v222
	v_or_b32_e32 v220, 48, v226
	v_lshl_add_u64 v[108:109], v[106:107], 0, v[198:199]
	v_lshlrev_b64 v[202:203], 14, v[222:223]
	v_ashrrev_i32_e32 v221, 31, v220
	v_add_u32_e32 v218, 0x80, v226
	global_load_dwordx4 v[170:173], v[108:109], off
	v_lshl_add_u64 v[108:109], v[106:107], 0, v[202:203]
	v_lshlrev_b64 v[206:207], 14, v[220:221]
	v_ashrrev_i32_e32 v219, 31, v218
	global_load_dwordx4 v[158:161], v[108:109], off
	v_lshl_add_u64 v[108:109], v[106:107], 0, v[206:207]
	v_lshlrev_b64 v[208:209], 14, v[218:219]
	global_load_dwordx4 v[154:157], v[108:109], off
	v_lshl_add_u64 v[108:109], v[106:107], 0, v[208:209]
	global_load_dwordx4 v[142:145], v[108:109], off
	v_add_u32_e32 v108, 0x90, v226
	v_ashrrev_i32_e32 v109, 31, v108
	v_lshlrev_b64 v[210:211], 14, v[108:109]
	v_lshl_add_u64 v[108:109], v[106:107], 0, v[210:211]
	global_load_dwordx4 v[130:133], v[108:109], off
	v_add_u32_e32 v108, 0xa0, v226
	v_ashrrev_i32_e32 v109, 31, v108
	v_lshlrev_b64 v[212:213], 14, v[108:109]
	v_lshl_add_u64 v[108:109], v[106:107], 0, v[212:213]
	global_load_dwordx4 v[118:121], v[108:109], off
	v_add_u32_e32 v108, 0xb0, v226
	v_ashrrev_i32_e32 v109, 31, v108
	v_lshlrev_b64 v[214:215], 14, v[108:109]
	v_lshl_add_u64 v[106:107], v[106:107], 0, v[214:215]
	global_load_dwordx4 v[106:109], v[106:107], off
	s_mov_b64 s[0:1], 0x120000
	s_mov_b32 s27, s52
	s_mov_b32 s34, s50
	s_mov_b64 s[8:9], s[56:57]
	s_waitcnt vmcnt(0)
; __device__ __forceinline__ unsigned cvt_pk_bf16(float lo, float hi) { unsigned r; asm volatile("v_cvt_pk_bf16_f32 %0, %1, %2" : "=v"(r) : "v"(lo), "v"(hi)); return r; }
; __device__ __forceinline__ float bf_lo(unsigned w) { return __uint_as_float(w << 16); }
; __device__ __forceinline__ float bf_hi(unsigned w) { return __uint_as_float(w & 0xffff0000u); }
; __device__ __forceinline__ float fast_rcp(float x) { return __builtin_amdgcn_rcpf(x); }
; __device__ __forceinline__ float silu_f(float z) { return z * fast_rcp(1.0f + __builtin_amdgcn_exp2f(z * -1.44269504f)); }
;     __device__ __forceinline__ void operator()(const f32x4 (&acc)[2][2][4][2], const Unit& u, int wr, int wc, int fr, int fq, const Pre&) const {
;     ...
;             for (int ai = 0; ai < 2; ++ai)
; #pragma unroll
;                 for (int m = 0; m < 4; ++m) { const int r = row0 + ai * HALF + m * 16;
;                     const u32x4 zw = zv[ai * 4 + m];
;                     const f32x4 a0 = acc[ai][bj][m][0] * sc[bj][0], a1 = acc[ai][bj][m][1] * sc[bj][1];
;                     u32x4 w;
;                     w.x = cvt_pk_bf16(a0[0] * silu_f(bf_lo(zw.x)), a0[1] * silu_f(bf_hi(zw.x)));
;                     w.y = cvt_pk_bf16(a0[2] * silu_f(bf_lo(zw.y)), a0[3] * silu_f(bf_hi(zw.y)));
;                     w.z = cvt_pk_bf16(a1[0] * silu_f(bf_lo(zw.z)), a1[1] * silu_f(bf_hi(zw.z)));
;                     w.w = cvt_pk_bf16(a1[2] * silu_f(bf_lo(zw.w)), a1[3] * silu_f(bf_hi(zw.w)));
;                     *(u32x4*)(O + (size_t)r * DE + c) = w; } }
	v_pk_mul_f32 v[146:147], v[146:147], v[98:99]
	v_pk_mul_f32 v[184:185], v[166:167], v[102:103]
	v_pk_mul_f32 v[166:167], v[164:165], v[100:101]
	v_pk_mul_f32 v[164:165], v[162:163], v[98:99]
	v_pk_mul_f32 v[168:169], v[168:169], v[104:105]
	v_lshlrev_b32_e32 v162, 16, v174
	v_mul_f32_e32 v163, 0xbfb8aa3b, v162
	v_exp_f32_e32 v163, v163
	v_pk_mul_f32 v[150:151], v[150:151], v[102:103]
	v_pk_mul_f32 v[152:153], v[152:153], v[104:105]
	v_pk_mul_f32 v[148:149], v[148:149], v[100:101]
	v_add_f32_e32 v163, 1.0, v163
	v_rcp_f32_e32 v163, v163
	v_pk_mul_f32 v[138:139], v[138:139], v[102:103]
	v_pk_mul_f32 v[140:141], v[140:141], v[104:105]
	v_pk_mul_f32 v[134:135], v[134:135], v[98:99]
	v_mul_f32_e32 v162, v163, v162
	v_and_b32_e32 v163, 0xffff0000, v174
	v_mul_f32_e32 v174, 0xbfb8aa3b, v163
	v_exp_f32_e32 v174, v174
	v_mul_f32_e32 v162, v184, v162
	v_pk_mul_f32 v[136:137], v[136:137], v[100:101]
	v_pk_mul_f32 v[126:127], v[126:127], v[102:103]
	v_add_f32_e32 v174, 1.0, v174
	v_rcp_f32_e32 v174, v174
	v_pk_mul_f32 v[128:129], v[128:129], v[104:105]
	v_pk_mul_f32 v[122:123], v[122:123], v[98:99]
	v_pk_mul_f32 v[124:125], v[124:125], v[100:101]
	v_mul_f32_e32 v163, v174, v163
	v_mul_f32_e32 v163, v185, v163
	v_cvt_pk_bf16_f32 v162, v162, v163
	v_lshlrev_b32_e32 v163, 16, v175
	v_mul_f32_e32 v174, 0xbfb8aa3b, v163
	v_exp_f32_e32 v174, v174
	v_pk_mul_f32 v[114:115], v[114:115], v[102:103]
	v_pk_mul_f32 v[116:117], v[116:117], v[104:105]
	v_pk_mul_f32 v[110:111], v[110:111], v[98:99]
	v_add_f32_e32 v174, 1.0, v174
	v_rcp_f32_e32 v174, v174
	v_pk_mul_f32 v[112:113], v[112:113], v[100:101]
	v_pk_mul_f32 v[94:95], v[94:95], v[102:103]
	v_pk_mul_f32 v[96:97], v[96:97], v[104:105]
	v_mul_f32_e32 v163, v174, v163
	v_mul_f32_e32 v163, v168, v163
	v_and_b32_e32 v168, 0xffff0000, v175
	v_mul_f32_e32 v174, 0xbfb8aa3b, v168
	v_exp_f32_e32 v174, v174
	v_pk_mul_f32 v[90:91], v[90:91], v[98:99]
	v_pk_mul_f32 v[92:93], v[92:93], v[100:101]
	v_pk_mul_f32 v[86:87], v[86:87], v[102:103]
	v_add_f32_e32 v174, 1.0, v174
	v_rcp_f32_e32 v174, v174
	v_pk_mul_f32 v[88:89], v[88:89], v[104:105]
	v_pk_mul_f32 v[82:83], v[82:83], v[98:99]
	v_pk_mul_f32 v[84:85], v[84:85], v[100:101]
	v_mul_f32_e32 v168, v174, v168
	v_mul_f32_e32 v168, v169, v168
	v_cvt_pk_bf16_f32 v163, v163, v168
	v_lshlrev_b32_e32 v168, 16, v176
	v_mul_f32_e32 v169, 0xbfb8aa3b, v168
	v_exp_f32_e32 v169, v169
	v_pk_mul_f32 v[78:79], v[78:79], v[102:103]
	v_pk_mul_f32 v[80:81], v[80:81], v[104:105]
	v_pk_mul_f32 v[74:75], v[74:75], v[98:99]
	v_add_f32_e32 v169, 1.0, v169
	v_rcp_f32_e32 v169, v169
	v_pk_mul_f32 v[76:77], v[76:77], v[100:101]
	v_pk_mul_f32 v[70:71], v[70:71], v[38:39]
	v_pk_mul_f32 v[72:73], v[72:73], v[40:41]
	v_mul_f32_e32 v168, v169, v168
	v_mul_f32_e32 v164, v164, v168
	v_and_b32_e32 v168, 0xffff0000, v176
	v_mul_f32_e32 v169, 0xbfb8aa3b, v168
	v_exp_f32_e32 v169, v169
	v_pk_mul_f32 v[66:67], v[66:67], v[34:35]
	v_pk_mul_f32 v[68:69], v[68:69], v[36:37]
	v_pk_mul_f32 v[62:63], v[62:63], v[38:39]
	v_add_f32_e32 v169, 1.0, v169
	v_rcp_f32_e32 v169, v169
	v_pk_mul_f32 v[64:65], v[64:65], v[40:41]
	v_pk_mul_f32 v[58:59], v[58:59], v[34:35]
	v_pk_mul_f32 v[60:61], v[60:61], v[36:37]
	v_mul_f32_e32 v168, v169, v168
	v_mul_f32_e32 v165, v165, v168
	v_cvt_pk_bf16_f32 v164, v164, v165
	v_lshlrev_b32_e32 v165, 16, v177
	v_mul_f32_e32 v168, 0xbfb8aa3b, v165
	v_exp_f32_e32 v168, v168
	v_pk_mul_f32 v[54:55], v[54:55], v[38:39]
	v_pk_mul_f32 v[56:57], v[56:57], v[40:41]
	v_pk_mul_f32 v[50:51], v[50:51], v[34:35]
	v_add_f32_e32 v168, 1.0, v168
	v_rcp_f32_e32 v168, v168
	v_pk_mul_f32 v[52:53], v[52:53], v[36:37]
	v_pk_mul_f32 v[46:47], v[46:47], v[38:39]
	v_pk_mul_f32 v[48:49], v[48:49], v[40:41]
	v_mul_f32_e32 v165, v168, v165
	v_mul_f32_e32 v165, v166, v165
	v_and_b32_e32 v166, 0xffff0000, v177
	v_mul_f32_e32 v168, 0xbfb8aa3b, v166
	v_exp_f32_e32 v168, v168
	v_pk_mul_f32 v[42:43], v[42:43], v[34:35]
	v_pk_mul_f32 v[44:45], v[44:45], v[36:37]
	v_pk_mul_f32 v[30:31], v[30:31], v[38:39]
	v_add_f32_e32 v168, 1.0, v168
	v_rcp_f32_e32 v168, v168
	v_pk_mul_f32 v[32:33], v[32:33], v[40:41]
	v_pk_mul_f32 v[26:27], v[26:27], v[34:35]
	v_pk_mul_f32 v[28:29], v[28:29], v[36:37]
	v_mul_f32_e32 v166, v168, v166
	v_mul_f32_e32 v166, v167, v166
	v_cvt_pk_bf16_f32 v165, v165, v166
	v_lshlrev_b64 v[166:167], 13, v[226:227]
	v_lshl_add_u64 v[166:167], s[44:45], 0, v[166:167]
	v_lshl_add_u64 v[166:167], v[166:167], 0, v[216:217]
	global_store_dwordx4 v[166:167], v[162:165], off
	v_pk_mul_f32 v[22:23], v[22:23], v[38:39]
	v_pk_mul_f32 v[24:25], v[24:25], v[40:41]
	v_lshlrev_b32_e32 v162, 16, v170
	v_mul_f32_e32 v163, 0xbfb8aa3b, v162
	v_exp_f32_e32 v163, v163
	v_pk_mul_f32 v[18:19], v[18:19], v[34:35]
	v_pk_mul_f32 v[20:21], v[20:21], v[36:37]
	v_pk_mul_f32 v[14:15], v[14:15], v[38:39]
	v_add_f32_e32 v163, 1.0, v163
	v_rcp_f32_e32 v163, v163
	v_pk_mul_f32 v[16:17], v[16:17], v[40:41]
	v_pk_mul_f32 v[10:11], v[10:11], v[34:35]
	v_pk_mul_f32 v[12:13], v[12:13], v[36:37]
	v_mul_f32_e32 v162, v163, v162
	v_mul_f32_e32 v150, v150, v162
	v_and_b32_e32 v162, 0xffff0000, v170
	v_mul_f32_e32 v163, 0xbfb8aa3b, v162
	v_exp_f32_e32 v163, v163
	v_pk_mul_f32 v[6:7], v[6:7], v[38:39]
	v_pk_mul_f32 v[8:9], v[8:9], v[40:41]
	v_pk_mul_f32 v[2:3], v[2:3], v[34:35]
	v_add_f32_e32 v163, 1.0, v163
	v_rcp_f32_e32 v163, v163
	v_pk_mul_f32 v[4:5], v[4:5], v[36:37]
	v_mul_f32_e32 v162, v163, v162
	v_mul_f32_e32 v151, v151, v162
	v_cvt_pk_bf16_f32 v150, v150, v151
	v_lshlrev_b32_e32 v151, 16, v171
	v_mul_f32_e32 v162, 0xbfb8aa3b, v151
	v_exp_f32_e32 v162, v162
	s_nop 0
	v_add_f32_e32 v162, 1.0, v162
	v_rcp_f32_e32 v162, v162
	s_nop 0
; __device__ __forceinline__ unsigned cvt_pk_bf16(float lo, float hi) { unsigned r; asm volatile("v_cvt_pk_bf16_f32 %0, %1, %2" : "=v"(r) : "v"(lo), "v"(hi)); return r; }
; __device__ __forceinline__ float bf_lo(unsigned w) { return __uint_as_float(w << 16); }
; __device__ __forceinline__ float bf_hi(unsigned w) { return __uint_as_float(w & 0xffff0000u); }
; __device__ __forceinline__ float fast_rcp(float x) { return __builtin_amdgcn_rcpf(x); }
; __device__ __forceinline__ float silu_f(float z) { return z * fast_rcp(1.0f + __builtin_amdgcn_exp2f(z * -1.44269504f)); }
;     __device__ __forceinline__ void operator()(const f32x4 (&acc)[2][2][4][2], const Unit& u, int wr, int wc, int fr, int fq, const Pre&) const {
;     ...
;             for (int ai = 0; ai < 2; ++ai)
; #pragma unroll
;                 for (int m = 0; m < 4; ++m) { const int r = row0 + ai * HALF + m * 16;
;                     const u32x4 zw = zv[ai * 4 + m];
;                     const f32x4 a0 = acc[ai][bj][m][0] * sc[bj][0], a1 = acc[ai][bj][m][1] * sc[bj][1];
;                     u32x4 w;
;                     w.x = cvt_pk_bf16(a0[0] * silu_f(bf_lo(zw.x)), a0[1] * silu_f(bf_hi(zw.x)));
;                     w.y = cvt_pk_bf16(a0[2] * silu_f(bf_lo(zw.y)), a0[3] * silu_f(bf_hi(zw.y)));
;                     w.z = cvt_pk_bf16(a1[0] * silu_f(bf_lo(zw.z)), a1[1] * silu_f(bf_hi(zw.z)));
;                     w.w = cvt_pk_bf16(a1[2] * silu_f(bf_lo(zw.w)), a1[3] * silu_f(bf_hi(zw.w)));
;                     *(u32x4*)(O + (size_t)r * DE + c) = w; } }
	v_mul_f32_e32 v151, v162, v151
	v_mul_f32_e32 v151, v152, v151
	v_and_b32_e32 v152, 0xffff0000, v171
	v_mul_f32_e32 v162, 0xbfb8aa3b, v152
	v_exp_f32_e32 v162, v162
	s_nop 0
	v_add_f32_e32 v162, 1.0, v162
	v_rcp_f32_e32 v162, v162
	s_nop 0
	v_mul_f32_e32 v152, v162, v152
	v_mul_f32_e32 v152, v153, v152
	v_cvt_pk_bf16_f32 v151, v151, v152
	v_lshlrev_b32_e32 v152, 16, v172
	v_mul_f32_e32 v153, 0xbfb8aa3b, v152
	v_exp_f32_e32 v153, v153
	s_nop 0
	v_add_f32_e32 v153, 1.0, v153
	v_rcp_f32_e32 v153, v153
	s_nop 0
	v_mul_f32_e32 v152, v153, v152
	v_mul_f32_e32 v146, v146, v152
	v_and_b32_e32 v152, 0xffff0000, v172
	v_mul_f32_e32 v153, 0xbfb8aa3b, v152
	v_exp_f32_e32 v153, v153
	s_nop 0
	v_add_f32_e32 v153, 1.0, v153
	v_rcp_f32_e32 v153, v153
	s_nop 0
	v_mul_f32_e32 v152, v153, v152
	v_mul_f32_e32 v147, v147, v152
	v_cvt_pk_bf16_f32 v152, v146, v147
	v_lshlrev_b32_e32 v146, 16, v173
	v_mul_f32_e32 v147, 0xbfb8aa3b, v146
	v_exp_f32_e32 v147, v147
	s_nop 0
	v_add_f32_e32 v147, 1.0, v147
	v_rcp_f32_e32 v147, v147
	s_nop 0
	v_mul_f32_e32 v146, v147, v146
	v_and_b32_e32 v147, 0xffff0000, v173
	v_mul_f32_e32 v146, v148, v146
	v_mul_f32_e32 v148, 0xbfb8aa3b, v147
	v_exp_f32_e32 v148, v148
	s_nop 0
	v_add_f32_e32 v148, 1.0, v148
	v_rcp_f32_e32 v148, v148
	s_nop 0
	v_mul_f32_e32 v147, v148, v147
	v_lshlrev_b32_e32 v148, 16, v158
	v_mul_f32_e32 v147, v149, v147
	v_mul_f32_e32 v149, 0xbfb8aa3b, v148
	v_exp_f32_e32 v149, v149
	v_cvt_pk_bf16_f32 v153, v146, v147
	v_lshlrev_b64 v[146:147], 13, v[224:225]
	v_lshl_add_u64 v[146:147], s[44:45], 0, v[146:147]
	v_add_f32_e32 v149, 1.0, v149
	v_rcp_f32_e32 v149, v149
	v_lshl_add_u64 v[146:147], v[146:147], 0, v[216:217]
	global_store_dwordx4 v[146:147], v[150:153], off
	v_mul_f32_e32 v148, v149, v148
	v_mul_f32_e32 v138, v138, v148
	v_and_b32_e32 v148, 0xffff0000, v158
	v_mul_f32_e32 v149, 0xbfb8aa3b, v148
	v_exp_f32_e32 v149, v149
	s_nop 0
	v_add_f32_e32 v149, 1.0, v149
	v_rcp_f32_e32 v149, v149
	s_nop 0
	v_mul_f32_e32 v148, v149, v148
	v_mul_f32_e32 v139, v139, v148
	v_cvt_pk_bf16_f32 v138, v138, v139
	v_lshlrev_b32_e32 v139, 16, v159
	v_mul_f32_e32 v148, 0xbfb8aa3b, v139
	v_exp_f32_e32 v148, v148
	s_nop 0
	v_add_f32_e32 v148, 1.0, v148
	v_rcp_f32_e32 v148, v148
	s_nop 0
	v_mul_f32_e32 v139, v148, v139
	v_mul_f32_e32 v139, v140, v139
	v_and_b32_e32 v140, 0xffff0000, v159
	v_mul_f32_e32 v148, 0xbfb8aa3b, v140
	v_exp_f32_e32 v148, v148
	s_nop 0
	v_add_f32_e32 v148, 1.0, v148
	v_rcp_f32_e32 v148, v148
	s_nop 0
	v_mul_f32_e32 v140, v148, v140
	v_mul_f32_e32 v140, v141, v140
	v_cvt_pk_bf16_f32 v139, v139, v140
	v_lshlrev_b32_e32 v140, 16, v160
	v_mul_f32_e32 v141, 0xbfb8aa3b, v140
	v_exp_f32_e32 v141, v141
	s_nop 0
	v_add_f32_e32 v141, 1.0, v141
	v_rcp_f32_e32 v141, v141
	s_nop 0
	v_mul_f32_e32 v140, v141, v140
	v_mul_f32_e32 v134, v134, v140
	v_and_b32_e32 v140, 0xffff0000, v160
	v_mul_f32_e32 v141, 0xbfb8aa3b, v140
	v_exp_f32_e32 v141, v141
	s_nop 0
	v_add_f32_e32 v141, 1.0, v141
	v_rcp_f32_e32 v141, v141
	s_nop 0
	v_mul_f32_e32 v140, v141, v140
	v_mul_f32_e32 v135, v135, v140
	v_cvt_pk_bf16_f32 v140, v134, v135
	v_lshlrev_b32_e32 v134, 16, v161
	v_mul_f32_e32 v135, 0xbfb8aa3b, v134
	v_exp_f32_e32 v135, v135
	s_nop 0
	v_add_f32_e32 v135, 1.0, v135
	v_rcp_f32_e32 v135, v135
	s_nop 0
	v_mul_f32_e32 v134, v135, v134
	v_and_b32_e32 v135, 0xffff0000, v161
	v_mul_f32_e32 v134, v136, v134
	v_mul_f32_e32 v136, 0xbfb8aa3b, v135
	v_exp_f32_e32 v136, v136
	s_nop 0
	v_add_f32_e32 v136, 1.0, v136
	v_rcp_f32_e32 v136, v136
	s_nop 0
	v_mul_f32_e32 v135, v136, v135
	v_lshlrev_b32_e32 v136, 16, v154
	v_mul_f32_e32 v135, v137, v135
	v_mul_f32_e32 v137, 0xbfb8aa3b, v136
	v_exp_f32_e32 v137, v137
	v_cvt_pk_bf16_f32 v141, v134, v135
	v_lshlrev_b64 v[134:135], 13, v[222:223]
	v_lshl_add_u64 v[134:135], s[44:45], 0, v[134:135]
	v_add_f32_e32 v137, 1.0, v137
	v_rcp_f32_e32 v137, v137
	v_lshl_add_u64 v[134:135], v[134:135], 0, v[216:217]
	global_store_dwordx4 v[134:135], v[138:141], off
	v_mul_f32_e32 v136, v137, v136
	v_mul_f32_e32 v126, v126, v136
	v_and_b32_e32 v136, 0xffff0000, v154
	v_mul_f32_e32 v137, 0xbfb8aa3b, v136
	v_exp_f32_e32 v137, v137
	s_nop 0
	v_add_f32_e32 v137, 1.0, v137
	v_rcp_f32_e32 v137, v137
	s_nop 0
	v_mul_f32_e32 v136, v137, v136
	v_mul_f32_e32 v127, v127, v136
	v_cvt_pk_bf16_f32 v126, v126, v127
	v_lshlrev_b32_e32 v127, 16, v155
	v_mul_f32_e32 v136, 0xbfb8aa3b, v127
	v_exp_f32_e32 v136, v136
	s_nop 0
	v_add_f32_e32 v136, 1.0, v136
	v_rcp_f32_e32 v136, v136
	s_nop 0
	v_mul_f32_e32 v127, v136, v127
	v_mul_f32_e32 v127, v128, v127
	v_and_b32_e32 v128, 0xffff0000, v155
	v_mul_f32_e32 v136, 0xbfb8aa3b, v128
	v_exp_f32_e32 v136, v136
	s_nop 0
	v_add_f32_e32 v136, 1.0, v136
	v_rcp_f32_e32 v136, v136
	s_nop 0
	v_mul_f32_e32 v128, v136, v128
	v_mul_f32_e32 v128, v129, v128
	v_cvt_pk_bf16_f32 v127, v127, v128
	v_lshlrev_b32_e32 v128, 16, v156
	v_mul_f32_e32 v129, 0xbfb8aa3b, v128
	v_exp_f32_e32 v129, v129
	s_nop 0
	v_add_f32_e32 v129, 1.0, v129
	v_rcp_f32_e32 v129, v129
	s_nop 0
	v_mul_f32_e32 v128, v129, v128
	v_mul_f32_e32 v122, v122, v128
	v_and_b32_e32 v128, 0xffff0000, v156
	v_mul_f32_e32 v129, 0xbfb8aa3b, v128
	v_exp_f32_e32 v129, v129
	s_nop 0
	v_add_f32_e32 v129, 1.0, v129
	v_rcp_f32_e32 v129, v129
	s_nop 0
	v_mul_f32_e32 v128, v129, v128
	v_mul_f32_e32 v123, v123, v128
	v_cvt_pk_bf16_f32 v128, v122, v123
	v_lshlrev_b32_e32 v122, 16, v157
	v_mul_f32_e32 v123, 0xbfb8aa3b, v122
	v_exp_f32_e32 v123, v123
	s_nop 0
	v_add_f32_e32 v123, 1.0, v123
	v_rcp_f32_e32 v123, v123
	s_nop 0
	v_mul_f32_e32 v122, v123, v122
	v_and_b32_e32 v123, 0xffff0000, v157
	v_mul_f32_e32 v122, v124, v122
	v_mul_f32_e32 v124, 0xbfb8aa3b, v123
; __device__ __forceinline__ unsigned cvt_pk_bf16(float lo, float hi) { unsigned r; asm volatile("v_cvt_pk_bf16_f32 %0, %1, %2" : "=v"(r) : "v"(lo), "v"(hi)); return r; }
; __device__ __forceinline__ float bf_lo(unsigned w) { return __uint_as_float(w << 16); }
; __device__ __forceinline__ float bf_hi(unsigned w) { return __uint_as_float(w & 0xffff0000u); }
; __device__ __forceinline__ float fast_rcp(float x) { return __builtin_amdgcn_rcpf(x); }
; __device__ __forceinline__ float silu_f(float z) { return z * fast_rcp(1.0f + __builtin_amdgcn_exp2f(z * -1.44269504f)); }
;     __device__ __forceinline__ void operator()(const f32x4 (&acc)[2][2][4][2], const Unit& u, int wr, int wc, int fr, int fq, const Pre&) const {
;     ...
;             for (int ai = 0; ai < 2; ++ai)
; #pragma unroll
;                 for (int m = 0; m < 4; ++m) { const int r = row0 + ai * HALF + m * 16;
;                     const u32x4 zw = zv[ai * 4 + m];
;                     const f32x4 a0 = acc[ai][bj][m][0] * sc[bj][0], a1 = acc[ai][bj][m][1] * sc[bj][1];
;                     u32x4 w;
;                     w.x = cvt_pk_bf16(a0[0] * silu_f(bf_lo(zw.x)), a0[1] * silu_f(bf_hi(zw.x)));
;                     w.y = cvt_pk_bf16(a0[2] * silu_f(bf_lo(zw.y)), a0[3] * silu_f(bf_hi(zw.y)));
;                     w.z = cvt_pk_bf16(a1[0] * silu_f(bf_lo(zw.z)), a1[1] * silu_f(bf_hi(zw.z)));
;                     w.w = cvt_pk_bf16(a1[2] * silu_f(bf_lo(zw.w)), a1[3] * silu_f(bf_hi(zw.w)));
;                     *(u32x4*)(O + (size_t)r * DE + c) = w; } }
	v_exp_f32_e32 v124, v124
	s_nop 0
	v_add_f32_e32 v124, 1.0, v124
	v_rcp_f32_e32 v124, v124
	s_nop 0
	v_mul_f32_e32 v123, v124, v123
	v_lshlrev_b32_e32 v124, 16, v142
	v_mul_f32_e32 v123, v125, v123
	v_mul_f32_e32 v125, 0xbfb8aa3b, v124
	v_exp_f32_e32 v125, v125
	v_cvt_pk_bf16_f32 v129, v122, v123
	v_lshlrev_b64 v[122:123], 13, v[220:221]
	v_lshl_add_u64 v[122:123], s[44:45], 0, v[122:123]
	v_add_f32_e32 v125, 1.0, v125
	v_rcp_f32_e32 v125, v125
	v_lshl_add_u64 v[122:123], v[122:123], 0, v[216:217]
	global_store_dwordx4 v[122:123], v[126:129], off
	v_mul_f32_e32 v124, v125, v124
	v_mul_f32_e32 v114, v114, v124
	v_and_b32_e32 v124, 0xffff0000, v142
	v_mul_f32_e32 v125, 0xbfb8aa3b, v124
	v_exp_f32_e32 v125, v125
	s_nop 0
	v_add_f32_e32 v125, 1.0, v125
	v_rcp_f32_e32 v125, v125
	s_nop 0
	v_mul_f32_e32 v124, v125, v124
	v_mul_f32_e32 v115, v115, v124
	v_cvt_pk_bf16_f32 v114, v114, v115
	v_lshlrev_b32_e32 v115, 16, v143
	v_mul_f32_e32 v124, 0xbfb8aa3b, v115
	v_exp_f32_e32 v124, v124
	s_nop 0
	v_add_f32_e32 v124, 1.0, v124
	v_rcp_f32_e32 v124, v124
	s_nop 0
	v_mul_f32_e32 v115, v124, v115
	v_mul_f32_e32 v115, v116, v115
	v_and_b32_e32 v116, 0xffff0000, v143
	v_mul_f32_e32 v124, 0xbfb8aa3b, v116
	v_exp_f32_e32 v124, v124
	s_nop 0
	v_add_f32_e32 v124, 1.0, v124
	v_rcp_f32_e32 v124, v124
	s_nop 0
	v_mul_f32_e32 v116, v124, v116
	v_mul_f32_e32 v116, v117, v116
	v_cvt_pk_bf16_f32 v115, v115, v116
	v_lshlrev_b32_e32 v116, 16, v144
	v_mul_f32_e32 v117, 0xbfb8aa3b, v116
	v_exp_f32_e32 v117, v117
	s_nop 0
	v_add_f32_e32 v117, 1.0, v117
	v_rcp_f32_e32 v117, v117
	s_nop 0
	v_mul_f32_e32 v116, v117, v116
	v_mul_f32_e32 v110, v110, v116
	v_and_b32_e32 v116, 0xffff0000, v144
	v_mul_f32_e32 v117, 0xbfb8aa3b, v116
	v_exp_f32_e32 v117, v117
	s_nop 0
	v_add_f32_e32 v117, 1.0, v117
	v_rcp_f32_e32 v117, v117
	s_nop 0
	v_mul_f32_e32 v116, v117, v116
	v_mul_f32_e32 v111, v111, v116
	v_cvt_pk_bf16_f32 v116, v110, v111
	v_lshlrev_b32_e32 v110, 16, v145
	v_mul_f32_e32 v111, 0xbfb8aa3b, v110
	v_exp_f32_e32 v111, v111
	s_nop 0
	v_add_f32_e32 v111, 1.0, v111
	v_rcp_f32_e32 v111, v111
	s_nop 0
	v_mul_f32_e32 v110, v111, v110
	v_and_b32_e32 v111, 0xffff0000, v145
	v_mul_f32_e32 v110, v112, v110
	v_mul_f32_e32 v112, 0xbfb8aa3b, v111
	v_exp_f32_e32 v112, v112
	s_nop 0
	v_add_f32_e32 v112, 1.0, v112
	v_rcp_f32_e32 v112, v112
	s_nop 0
	v_mul_f32_e32 v111, v112, v111
	v_mul_f32_e32 v111, v113, v111
	v_cvt_pk_bf16_f32 v117, v110, v111
	v_lshlrev_b64 v[110:111], 13, v[218:219]
	v_lshl_add_u64 v[110:111], s[44:45], 0, v[110:111]
	v_lshl_add_u64 v[112:113], v[110:111], 0, v[216:217]
	v_lshlrev_b32_e32 v110, 16, v130
	v_mul_f32_e32 v111, 0xbfb8aa3b, v110
	v_exp_f32_e32 v111, v111
	global_store_dwordx4 v[112:113], v[114:117], off
	v_add_f32_e32 v111, 1.0, v111
	v_rcp_f32_e32 v111, v111
	s_nop 0
	v_mul_f32_e32 v110, v111, v110
	v_mul_f32_e32 v94, v94, v110
	v_and_b32_e32 v110, 0xffff0000, v130
	v_mul_f32_e32 v111, 0xbfb8aa3b, v110
	v_exp_f32_e32 v111, v111
	s_nop 0
	v_add_f32_e32 v111, 1.0, v111
	v_rcp_f32_e32 v111, v111
	s_nop 0
	v_mul_f32_e32 v110, v111, v110
	v_mul_f32_e32 v95, v95, v110
	v_cvt_pk_bf16_f32 v94, v94, v95
	v_lshlrev_b32_e32 v95, 16, v131
	v_mul_f32_e32 v110, 0xbfb8aa3b, v95
	v_exp_f32_e32 v110, v110
	s_nop 0
	v_add_f32_e32 v110, 1.0, v110
	v_rcp_f32_e32 v110, v110
	s_nop 0
	v_mul_f32_e32 v95, v110, v95
	v_mul_f32_e32 v95, v96, v95
	v_and_b32_e32 v96, 0xffff0000, v131
	v_mul_f32_e32 v110, 0xbfb8aa3b, v96
	v_exp_f32_e32 v110, v110
	s_nop 0
	v_add_f32_e32 v110, 1.0, v110
	v_rcp_f32_e32 v110, v110
	s_nop 0
	v_mul_f32_e32 v96, v110, v96
	v_mul_f32_e32 v96, v97, v96
	v_cvt_pk_bf16_f32 v95, v95, v96
	v_lshlrev_b32_e32 v96, 16, v132
	v_mul_f32_e32 v97, 0xbfb8aa3b, v96
	v_exp_f32_e32 v97, v97
	v_lshl_add_u64 v[110:111], v[166:167], 0, s[0:1]
	s_mov_b64 s[0:1], 0x140000
	v_lshl_add_u64 v[114:115], v[166:167], 0, s[0:1]
	v_add_f32_e32 v97, 1.0, v97
	v_rcp_f32_e32 v97, v97
	s_mov_b64 s[0:1], 0x160000
	v_mul_f32_e32 v96, v97, v96
	v_mul_f32_e32 v90, v90, v96
	v_and_b32_e32 v96, 0xffff0000, v132
	v_mul_f32_e32 v97, 0xbfb8aa3b, v96
	v_exp_f32_e32 v97, v97
	s_nop 0
	v_add_f32_e32 v97, 1.0, v97
	v_rcp_f32_e32 v97, v97
	s_nop 0
	v_mul_f32_e32 v96, v97, v96
	v_mul_f32_e32 v91, v91, v96
	v_cvt_pk_bf16_f32 v96, v90, v91
	v_lshlrev_b32_e32 v90, 16, v133
	v_mul_f32_e32 v91, 0xbfb8aa3b, v90
	v_exp_f32_e32 v91, v91
	s_nop 0
	v_add_f32_e32 v91, 1.0, v91
	v_rcp_f32_e32 v91, v91
	s_nop 0
	v_mul_f32_e32 v90, v91, v90
	v_and_b32_e32 v91, 0xffff0000, v133
	v_mul_f32_e32 v90, v92, v90
	v_mul_f32_e32 v92, 0xbfb8aa3b, v91
	v_exp_f32_e32 v92, v92
	s_nop 0
	v_add_f32_e32 v92, 1.0, v92
	v_rcp_f32_e32 v92, v92
	s_nop 0
	v_mul_f32_e32 v91, v92, v91
	v_mul_f32_e32 v91, v93, v91
	v_cvt_pk_bf16_f32 v97, v90, v91
	v_add_co_u32_e32 v90, vcc, s41, v166
	s_nop 1
	v_addc_co_u32_e32 v91, vcc, 0, v167, vcc
	global_store_dwordx4 v[90:91], v[94:97], off
	v_lshlrev_b32_e32 v90, 16, v118
	v_mul_f32_e32 v91, 0xbfb8aa3b, v90
	v_exp_f32_e32 v91, v91
	s_nop 0
	v_add_f32_e32 v91, 1.0, v91
	v_rcp_f32_e32 v91, v91
	s_nop 0
	v_mul_f32_e32 v90, v91, v90
	v_mul_f32_e32 v86, v86, v90
	v_and_b32_e32 v90, 0xffff0000, v118
	v_mul_f32_e32 v91, 0xbfb8aa3b, v90
	v_exp_f32_e32 v91, v91
	s_nop 0
	v_add_f32_e32 v91, 1.0, v91
	v_rcp_f32_e32 v91, v91
	s_nop 0
	v_mul_f32_e32 v90, v91, v90
	v_mul_f32_e32 v87, v87, v90
	v_cvt_pk_bf16_f32 v86, v86, v87
	v_lshlrev_b32_e32 v87, 16, v119
	v_mul_f32_e32 v90, 0xbfb8aa3b, v87
	v_exp_f32_e32 v90, v90
	s_nop 0
	v_add_f32_e32 v90, 1.0, v90
	v_rcp_f32_e32 v90, v90
	s_nop 0
	v_mul_f32_e32 v87, v90, v87
	v_mul_f32_e32 v87, v88, v87
	v_and_b32_e32 v88, 0xffff0000, v119
	v_mul_f32_e32 v90, 0xbfb8aa3b, v88
; __device__ __forceinline__ unsigned cvt_pk_bf16(float lo, float hi) { unsigned r; asm volatile("v_cvt_pk_bf16_f32 %0, %1, %2" : "=v"(r) : "v"(lo), "v"(hi)); return r; }
; __device__ __forceinline__ float bf_lo(unsigned w) { return __uint_as_float(w << 16); }
; __device__ __forceinline__ float bf_hi(unsigned w) { return __uint_as_float(w & 0xffff0000u); }
; __device__ __forceinline__ float silu_f(float z) { return z * fast_rcp(1.0f + __builtin_amdgcn_exp2f(z * -1.44269504f)); }
;     __device__ __forceinline__ void operator()(const f32x4 (&acc)[2][2][4][2], const Unit& u, int wr, int wc, int fr, int fq, const Pre&) const {
;     ...
;         for (int bj = 0; bj < 2; ++bj) { const int c = col0 + bj * HALF;
;             u32x4 zv[8];
; #pragma unroll
;             for (int g8 = 0; g8 < 8; ++g8) zv[g8] = *(const u32x4*)(Z + (size_t)(row0 + (g8 >> 2) * HALF + (g8 & 3) * 16) * DE2 + c);
; #pragma unroll
;             for (int ai = 0; ai < 2; ++ai)
; #pragma unroll
;                 for (int m = 0; m < 4; ++m) { const int r = row0 + ai * HALF + m * 16;
;                     const u32x4 zw = zv[ai * 4 + m];
;                     const f32x4 a0 = acc[ai][bj][m][0] * sc[bj][0], a1 = acc[ai][bj][m][1] * sc[bj][1];
;                     u32x4 w;
;                     w.x = cvt_pk_bf16(a0[0] * silu_f(bf_lo(zw.x)), a0[1] * silu_f(bf_hi(zw.x)));
;                     w.y = cvt_pk_bf16(a0[2] * silu_f(bf_lo(zw.y)), a0[3] * silu_f(bf_hi(zw.y)));
;                     w.z = cvt_pk_bf16(a1[0] * silu_f(bf_lo(zw.z)), a1[1] * silu_f(bf_hi(zw.z)));
;                     w.w = cvt_pk_bf16(a1[2] * silu_f(bf_lo(zw.w)), a1[3] * silu_f(bf_hi(zw.w)));
;                     *(u32x4*)(O + (size_t)r * DE + c) = w; } }
	v_exp_f32_e32 v90, v90
	s_nop 0
	v_add_f32_e32 v90, 1.0, v90
	v_rcp_f32_e32 v90, v90
	s_nop 0
	v_mul_f32_e32 v88, v90, v88
	v_mul_f32_e32 v88, v89, v88
	v_cvt_pk_bf16_f32 v87, v87, v88
	v_lshlrev_b32_e32 v88, 16, v120
	v_mul_f32_e32 v89, 0xbfb8aa3b, v88
	v_exp_f32_e32 v89, v89
	s_nop 0
	v_add_f32_e32 v89, 1.0, v89
	v_rcp_f32_e32 v89, v89
	s_nop 0
	v_mul_f32_e32 v88, v89, v88
	v_mul_f32_e32 v82, v82, v88
	v_and_b32_e32 v88, 0xffff0000, v120
	v_mul_f32_e32 v89, 0xbfb8aa3b, v88
	v_exp_f32_e32 v89, v89
	s_nop 0
	v_add_f32_e32 v89, 1.0, v89
	v_rcp_f32_e32 v89, v89
	s_nop 0
	v_mul_f32_e32 v88, v89, v88
	v_mul_f32_e32 v83, v83, v88
	v_cvt_pk_bf16_f32 v88, v82, v83
	v_lshlrev_b32_e32 v82, 16, v121
	v_mul_f32_e32 v83, 0xbfb8aa3b, v82
	v_exp_f32_e32 v83, v83
	s_nop 0
	v_add_f32_e32 v83, 1.0, v83
	v_rcp_f32_e32 v83, v83
	s_nop 0
	v_mul_f32_e32 v82, v83, v82
	v_and_b32_e32 v83, 0xffff0000, v121
	v_mul_f32_e32 v82, v84, v82
	v_mul_f32_e32 v84, 0xbfb8aa3b, v83
	v_exp_f32_e32 v84, v84
	s_nop 0
	v_add_f32_e32 v84, 1.0, v84
	v_rcp_f32_e32 v84, v84
	s_nop 0
	v_mul_f32_e32 v83, v84, v83
	v_mul_f32_e32 v83, v85, v83
	v_cvt_pk_bf16_f32 v89, v82, v83
	v_add_co_u32_e32 v82, vcc, s65, v166
	s_nop 1
	v_addc_co_u32_e32 v83, vcc, 0, v167, vcc
	global_store_dwordx4 v[82:83], v[86:89], off
	v_lshlrev_b32_e32 v82, 16, v106
	v_mul_f32_e32 v83, 0xbfb8aa3b, v82
	v_exp_f32_e32 v83, v83
	s_nop 0
	v_add_f32_e32 v83, 1.0, v83
	v_rcp_f32_e32 v83, v83
	s_nop 0
	v_mul_f32_e32 v82, v83, v82
	v_mul_f32_e32 v78, v78, v82
	v_and_b32_e32 v82, 0xffff0000, v106
	v_mul_f32_e32 v83, 0xbfb8aa3b, v82
	v_exp_f32_e32 v83, v83
	s_nop 0
	v_add_f32_e32 v83, 1.0, v83
	v_rcp_f32_e32 v83, v83
	s_nop 0
	v_mul_f32_e32 v82, v83, v82
	v_mul_f32_e32 v79, v79, v82
	v_cvt_pk_bf16_f32 v78, v78, v79
	v_lshlrev_b32_e32 v79, 16, v107
	v_mul_f32_e32 v82, 0xbfb8aa3b, v79
	v_exp_f32_e32 v82, v82
	s_nop 0
	v_add_f32_e32 v82, 1.0, v82
	v_rcp_f32_e32 v82, v82
	s_nop 0
	v_mul_f32_e32 v79, v82, v79
	v_mul_f32_e32 v79, v80, v79
	v_and_b32_e32 v80, 0xffff0000, v107
	v_mul_f32_e32 v82, 0xbfb8aa3b, v80
	v_exp_f32_e32 v82, v82
	v_lshl_add_u64 v[106:107], v[166:167], 0, s[0:1]
	s_mov_b64 s[0:1], s[54:55]
	v_add_f32_e32 v82, 1.0, v82
	v_rcp_f32_e32 v82, v82
	s_nop 0
	v_mul_f32_e32 v80, v82, v80
	v_mul_f32_e32 v80, v81, v80
	v_cvt_pk_bf16_f32 v79, v79, v80
	v_lshlrev_b32_e32 v80, 16, v108
	v_mul_f32_e32 v81, 0xbfb8aa3b, v80
	v_exp_f32_e32 v81, v81
	s_nop 0
	v_add_f32_e32 v81, 1.0, v81
	v_rcp_f32_e32 v81, v81
	s_nop 0
	v_mul_f32_e32 v80, v81, v80
	v_mul_f32_e32 v74, v74, v80
	v_and_b32_e32 v80, 0xffff0000, v108
	v_mul_f32_e32 v81, 0xbfb8aa3b, v80
	v_exp_f32_e32 v81, v81
	s_nop 0
	v_add_f32_e32 v81, 1.0, v81
	v_rcp_f32_e32 v81, v81
	s_nop 0
	v_mul_f32_e32 v80, v81, v80
	v_mul_f32_e32 v75, v75, v80
	v_cvt_pk_bf16_f32 v80, v74, v75
	v_lshlrev_b32_e32 v74, 16, v109
	v_mul_f32_e32 v75, 0xbfb8aa3b, v74
	v_exp_f32_e32 v75, v75
	s_nop 0
	v_add_f32_e32 v75, 1.0, v75
	v_rcp_f32_e32 v75, v75
	s_nop 0
	v_mul_f32_e32 v74, v75, v74
	v_and_b32_e32 v75, 0xffff0000, v109
	v_mul_f32_e32 v74, v76, v74
	v_mul_f32_e32 v76, 0xbfb8aa3b, v75
	v_exp_f32_e32 v76, v76
	s_nop 0
	v_add_f32_e32 v76, 1.0, v76
	v_rcp_f32_e32 v76, v76
	s_nop 0
	v_mul_f32_e32 v75, v76, v75
	v_mul_f32_e32 v75, v77, v75
	v_cvt_pk_bf16_f32 v81, v74, v75
	v_add_co_u32_e32 v74, vcc, s70, v166
	v_lshl_add_u64 v[76:77], s[46:47], 0, v[204:205]
	s_nop 0
	v_addc_co_u32_e32 v75, vcc, 0, v167, vcc
	global_store_dwordx4 v[74:75], v[78:81], off
	v_or_b32_e32 v74, 0x80, v200
	v_ashrrev_i32_e32 v75, 31, v74
	v_lshlrev_b64 v[74:75], 1, v[74:75]
	v_lshl_add_u64 v[76:77], v[76:77], 0, v[74:75]
	global_load_dwordx4 v[102:105], v[76:77], off
	v_lshl_add_u64 v[76:77], s[46:47], 0, v[198:199]
	v_lshl_add_u64 v[76:77], v[76:77], 0, v[74:75]
	global_load_dwordx4 v[98:101], v[76:77], off
	v_lshl_add_u64 v[76:77], s[46:47], 0, v[202:203]
	v_lshl_add_u64 v[76:77], v[76:77], 0, v[74:75]
	global_load_dwordx4 v[94:97], v[76:77], off
	v_lshl_add_u64 v[76:77], s[46:47], 0, v[206:207]
	v_lshl_add_u64 v[76:77], v[76:77], 0, v[74:75]
	global_load_dwordx4 v[90:93], v[76:77], off
	v_lshl_add_u64 v[76:77], s[46:47], 0, v[208:209]
	v_lshl_add_u64 v[76:77], v[76:77], 0, v[74:75]
	global_load_dwordx4 v[86:89], v[76:77], off
	v_lshl_add_u64 v[76:77], s[46:47], 0, v[210:211]
	v_lshl_add_u64 v[76:77], v[76:77], 0, v[74:75]
	global_load_dwordx4 v[82:85], v[76:77], off
	v_lshl_add_u64 v[76:77], s[46:47], 0, v[212:213]
	v_lshl_add_u64 v[76:77], v[76:77], 0, v[74:75]
	global_load_dwordx4 v[78:81], v[76:77], off
	v_lshl_add_u64 v[76:77], s[46:47], 0, v[214:215]
	v_lshl_add_u64 v[74:75], v[76:77], 0, v[74:75]
	global_load_dwordx4 v[74:77], v[74:75], off
	s_and_b64 vcc, exec, s[42:43]
	s_waitcnt vmcnt(0)
; __device__ __forceinline__ unsigned cvt_pk_bf16(float lo, float hi) { unsigned r; asm volatile("v_cvt_pk_bf16_f32 %0, %1, %2" : "=v"(r) : "v"(lo), "v"(hi)); return r; }
; __device__ __forceinline__ float bf_lo(unsigned w) { return __uint_as_float(w << 16); }
; __device__ __forceinline__ float bf_hi(unsigned w) { return __uint_as_float(w & 0xffff0000u); }
; __device__ __forceinline__ float fast_rcp(float x) { return __builtin_amdgcn_rcpf(x); }
; __device__ __forceinline__ float silu_f(float z) { return z * fast_rcp(1.0f + __builtin_amdgcn_exp2f(z * -1.44269504f)); }
;     __device__ __forceinline__ void operator()(const f32x4 (&acc)[2][2][4][2], const Unit& u, int wr, int wc, int fr, int fq, const Pre&) const {
;     ...
;             for (int ai = 0; ai < 2; ++ai)
; #pragma unroll
;                 for (int m = 0; m < 4; ++m) { const int r = row0 + ai * HALF + m * 16;
;                     const u32x4 zw = zv[ai * 4 + m];
;                     const f32x4 a0 = acc[ai][bj][m][0] * sc[bj][0], a1 = acc[ai][bj][m][1] * sc[bj][1];
;                     u32x4 w;
;                     w.x = cvt_pk_bf16(a0[0] * silu_f(bf_lo(zw.x)), a0[1] * silu_f(bf_hi(zw.x)));
;                     w.y = cvt_pk_bf16(a0[2] * silu_f(bf_lo(zw.y)), a0[3] * silu_f(bf_hi(zw.y)));
;                     w.z = cvt_pk_bf16(a1[0] * silu_f(bf_lo(zw.z)), a1[1] * silu_f(bf_hi(zw.z)));
;                     w.w = cvt_pk_bf16(a1[2] * silu_f(bf_lo(zw.w)), a1[3] * silu_f(bf_hi(zw.w)));
;                     *(u32x4*)(O + (size_t)r * DE + c) = w; } }
	v_lshlrev_b32_e32 v108, 16, v102
	v_mul_f32_e32 v109, 0xbfb8aa3b, v108
	v_exp_f32_e32 v109, v109
	v_and_b32_e32 v102, 0xffff0000, v102
	v_add_f32_e32 v109, 1.0, v109
	v_rcp_f32_e32 v109, v109
	s_nop 0
	v_mul_f32_e32 v108, v109, v108
	v_mul_f32_e32 v70, v70, v108
	v_mul_f32_e32 v108, 0xbfb8aa3b, v102
	v_exp_f32_e32 v108, v108
	s_nop 0
	v_add_f32_e32 v108, 1.0, v108
	v_rcp_f32_e32 v108, v108
	s_nop 0
	v_mul_f32_e32 v102, v108, v102
	v_mul_f32_e32 v71, v71, v102
	v_cvt_pk_bf16_f32 v70, v70, v71
	v_lshlrev_b32_e32 v71, 16, v103
	v_mul_f32_e32 v102, 0xbfb8aa3b, v71
	v_exp_f32_e32 v102, v102
	s_nop 0
	v_add_f32_e32 v102, 1.0, v102
	v_rcp_f32_e32 v102, v102
	s_nop 0
	v_mul_f32_e32 v71, v102, v71
	v_mul_f32_e32 v71, v72, v71
	v_and_b32_e32 v72, 0xffff0000, v103
	v_mul_f32_e32 v102, 0xbfb8aa3b, v72
	v_exp_f32_e32 v102, v102
	s_nop 0
	v_add_f32_e32 v102, 1.0, v102
	v_rcp_f32_e32 v102, v102
	s_nop 0
	v_mul_f32_e32 v72, v102, v72
	v_mul_f32_e32 v72, v73, v72
	v_cvt_pk_bf16_f32 v71, v71, v72
	v_lshlrev_b32_e32 v72, 16, v104
	v_mul_f32_e32 v73, 0xbfb8aa3b, v72
	v_exp_f32_e32 v73, v73
	s_nop 0
	v_add_f32_e32 v73, 1.0, v73
	v_rcp_f32_e32 v73, v73
	s_nop 0
	v_mul_f32_e32 v72, v73, v72
	v_mul_f32_e32 v66, v66, v72
	v_and_b32_e32 v72, 0xffff0000, v104
	v_mul_f32_e32 v73, 0xbfb8aa3b, v72
	v_exp_f32_e32 v73, v73
	s_nop 0
	v_add_f32_e32 v73, 1.0, v73
	v_rcp_f32_e32 v73, v73
	s_nop 0
	v_mul_f32_e32 v72, v73, v72
	v_mul_f32_e32 v67, v67, v72
	v_cvt_pk_bf16_f32 v72, v66, v67
	v_lshlrev_b32_e32 v66, 16, v105
	v_mul_f32_e32 v67, 0xbfb8aa3b, v66
	v_exp_f32_e32 v67, v67
	s_nop 0
	v_add_f32_e32 v67, 1.0, v67
	v_rcp_f32_e32 v67, v67
	s_nop 0
	v_mul_f32_e32 v66, v67, v66
	v_and_b32_e32 v67, 0xffff0000, v105
	v_mul_f32_e32 v66, v68, v66
	v_mul_f32_e32 v68, 0xbfb8aa3b, v67
	v_exp_f32_e32 v68, v68
	s_nop 0
	v_add_f32_e32 v68, 1.0, v68
	v_rcp_f32_e32 v68, v68
	s_nop 0
	v_mul_f32_e32 v67, v68, v67
	v_mul_f32_e32 v67, v69, v67
	v_cvt_pk_bf16_f32 v73, v66, v67
	v_lshlrev_b32_e32 v66, 16, v98
	v_mul_f32_e32 v67, 0xbfb8aa3b, v66
	v_exp_f32_e32 v67, v67
	global_store_dwordx4 v[166:167], v[70:73], off offset:256
	v_add_f32_e32 v67, 1.0, v67
	v_rcp_f32_e32 v67, v67
	s_nop 0
	v_mul_f32_e32 v66, v67, v66
	v_mul_f32_e32 v62, v62, v66
	v_and_b32_e32 v66, 0xffff0000, v98
	v_mul_f32_e32 v67, 0xbfb8aa3b, v66
	v_exp_f32_e32 v67, v67
	s_nop 0
	v_add_f32_e32 v67, 1.0, v67
	v_rcp_f32_e32 v67, v67
	s_nop 0
	v_mul_f32_e32 v66, v67, v66
	v_mul_f32_e32 v63, v63, v66
	v_cvt_pk_bf16_f32 v62, v62, v63
	v_lshlrev_b32_e32 v63, 16, v99
	v_mul_f32_e32 v66, 0xbfb8aa3b, v63
	v_exp_f32_e32 v66, v66
	s_nop 0
	v_add_f32_e32 v66, 1.0, v66
	v_rcp_f32_e32 v66, v66
	s_nop 0
	v_mul_f32_e32 v63, v66, v63
	v_mul_f32_e32 v63, v64, v63
	v_and_b32_e32 v64, 0xffff0000, v99
	v_mul_f32_e32 v66, 0xbfb8aa3b, v64
	v_exp_f32_e32 v66, v66
	s_nop 0
	v_add_f32_e32 v66, 1.0, v66
	v_rcp_f32_e32 v66, v66
	s_nop 0
	v_mul_f32_e32 v64, v66, v64
	v_mul_f32_e32 v64, v65, v64
	v_cvt_pk_bf16_f32 v63, v63, v64
	v_lshlrev_b32_e32 v64, 16, v100
	v_mul_f32_e32 v65, 0xbfb8aa3b, v64
	v_exp_f32_e32 v65, v65
	s_nop 0
	v_add_f32_e32 v65, 1.0, v65
	v_rcp_f32_e32 v65, v65
	s_nop 0
	v_mul_f32_e32 v64, v65, v64
	v_mul_f32_e32 v58, v58, v64
	v_and_b32_e32 v64, 0xffff0000, v100
	v_mul_f32_e32 v65, 0xbfb8aa3b, v64
	v_exp_f32_e32 v65, v65
	s_nop 0
	v_add_f32_e32 v65, 1.0, v65
	v_rcp_f32_e32 v65, v65
	s_nop 0
	v_mul_f32_e32 v64, v65, v64
	v_mul_f32_e32 v59, v59, v64
	v_cvt_pk_bf16_f32 v64, v58, v59
	v_lshlrev_b32_e32 v58, 16, v101
	v_mul_f32_e32 v59, 0xbfb8aa3b, v58
	v_exp_f32_e32 v59, v59
	s_nop 0
	v_add_f32_e32 v59, 1.0, v59
	v_rcp_f32_e32 v59, v59
	s_nop 0
	v_mul_f32_e32 v58, v59, v58
	v_and_b32_e32 v59, 0xffff0000, v101
	v_mul_f32_e32 v58, v60, v58
	v_mul_f32_e32 v60, 0xbfb8aa3b, v59
	v_exp_f32_e32 v60, v60
	s_nop 0
	v_add_f32_e32 v60, 1.0, v60
	v_rcp_f32_e32 v60, v60
	s_nop 0
	v_mul_f32_e32 v59, v60, v59
	v_mul_f32_e32 v59, v61, v59
	v_cvt_pk_bf16_f32 v65, v58, v59
	v_lshlrev_b32_e32 v58, 16, v94
	v_mul_f32_e32 v59, 0xbfb8aa3b, v58
	v_exp_f32_e32 v59, v59
	global_store_dwordx4 v[146:147], v[62:65], off offset:256
	v_add_f32_e32 v59, 1.0, v59
	v_rcp_f32_e32 v59, v59
	s_nop 0
	v_mul_f32_e32 v58, v59, v58
	v_mul_f32_e32 v54, v54, v58
	v_and_b32_e32 v58, 0xffff0000, v94
	v_mul_f32_e32 v59, 0xbfb8aa3b, v58
	v_exp_f32_e32 v59, v59
	s_nop 0
	v_add_f32_e32 v59, 1.0, v59
	v_rcp_f32_e32 v59, v59
	s_nop 0
	v_mul_f32_e32 v58, v59, v58
	v_mul_f32_e32 v55, v55, v58
	v_cvt_pk_bf16_f32 v54, v54, v55
	v_lshlrev_b32_e32 v55, 16, v95
	v_mul_f32_e32 v58, 0xbfb8aa3b, v55
	v_exp_f32_e32 v58, v58
	s_nop 0
	v_add_f32_e32 v58, 1.0, v58
	v_rcp_f32_e32 v58, v58
	s_nop 0
	v_mul_f32_e32 v55, v58, v55
	v_mul_f32_e32 v55, v56, v55
	v_and_b32_e32 v56, 0xffff0000, v95
	v_mul_f32_e32 v58, 0xbfb8aa3b, v56
	v_exp_f32_e32 v58, v58
	s_nop 0
	v_add_f32_e32 v58, 1.0, v58
	v_rcp_f32_e32 v58, v58
	s_nop 0
	v_mul_f32_e32 v56, v58, v56
	v_mul_f32_e32 v56, v57, v56
	v_cvt_pk_bf16_f32 v55, v55, v56
	v_lshlrev_b32_e32 v56, 16, v96
	v_mul_f32_e32 v57, 0xbfb8aa3b, v56
	v_exp_f32_e32 v57, v57
	s_nop 0
	v_add_f32_e32 v57, 1.0, v57
	v_rcp_f32_e32 v57, v57
	s_nop 0
	v_mul_f32_e32 v56, v57, v56
	v_mul_f32_e32 v50, v50, v56
	v_and_b32_e32 v56, 0xffff0000, v96
	v_mul_f32_e32 v57, 0xbfb8aa3b, v56
	v_exp_f32_e32 v57, v57
	s_nop 0
	v_add_f32_e32 v57, 1.0, v57
	v_rcp_f32_e32 v57, v57
	s_nop 0
	v_mul_f32_e32 v56, v57, v56
	v_mul_f32_e32 v51, v51, v56
	v_cvt_pk_bf16_f32 v56, v50, v51
	v_lshlrev_b32_e32 v50, 16, v97
	v_mul_f32_e32 v51, 0xbfb8aa3b, v50
	v_exp_f32_e32 v51, v51
	s_nop 0
	v_add_f32_e32 v51, 1.0, v51
	v_rcp_f32_e32 v51, v51
	s_nop 0
	v_mul_f32_e32 v50, v51, v50
	v_and_b32_e32 v51, 0xffff0000, v97
; __device__ __forceinline__ unsigned cvt_pk_bf16(float lo, float hi) { unsigned r; asm volatile("v_cvt_pk_bf16_f32 %0, %1, %2" : "=v"(r) : "v"(lo), "v"(hi)); return r; }
; __device__ __forceinline__ float bf_lo(unsigned w) { return __uint_as_float(w << 16); }
; __device__ __forceinline__ float bf_hi(unsigned w) { return __uint_as_float(w & 0xffff0000u); }
; __device__ __forceinline__ float fast_rcp(float x) { return __builtin_amdgcn_rcpf(x); }
; __device__ __forceinline__ float silu_f(float z) { return z * fast_rcp(1.0f + __builtin_amdgcn_exp2f(z * -1.44269504f)); }
;     __device__ __forceinline__ void operator()(const f32x4 (&acc)[2][2][4][2], const Unit& u, int wr, int wc, int fr, int fq, const Pre&) const {
;     ...
;             for (int ai = 0; ai < 2; ++ai)
; #pragma unroll
;                 for (int m = 0; m < 4; ++m) { const int r = row0 + ai * HALF + m * 16;
;                     const u32x4 zw = zv[ai * 4 + m];
;                     const f32x4 a0 = acc[ai][bj][m][0] * sc[bj][0], a1 = acc[ai][bj][m][1] * sc[bj][1];
;                     u32x4 w;
;                     w.x = cvt_pk_bf16(a0[0] * silu_f(bf_lo(zw.x)), a0[1] * silu_f(bf_hi(zw.x)));
;                     w.y = cvt_pk_bf16(a0[2] * silu_f(bf_lo(zw.y)), a0[3] * silu_f(bf_hi(zw.y)));
;                     w.z = cvt_pk_bf16(a1[0] * silu_f(bf_lo(zw.z)), a1[1] * silu_f(bf_hi(zw.z)));
;                     w.w = cvt_pk_bf16(a1[2] * silu_f(bf_lo(zw.w)), a1[3] * silu_f(bf_hi(zw.w)));
;                     *(u32x4*)(O + (size_t)r * DE + c) = w; } }
	v_mul_f32_e32 v50, v52, v50
	v_mul_f32_e32 v52, 0xbfb8aa3b, v51
	v_exp_f32_e32 v52, v52
	s_nop 0
	v_add_f32_e32 v52, 1.0, v52
	v_rcp_f32_e32 v52, v52
	s_nop 0
	v_mul_f32_e32 v51, v52, v51
	v_mul_f32_e32 v51, v53, v51
	v_cvt_pk_bf16_f32 v57, v50, v51
	v_lshlrev_b32_e32 v50, 16, v90
	v_mul_f32_e32 v51, 0xbfb8aa3b, v50
	v_exp_f32_e32 v51, v51
	global_store_dwordx4 v[134:135], v[54:57], off offset:256
	v_add_f32_e32 v51, 1.0, v51
	v_rcp_f32_e32 v51, v51
	s_nop 0
	v_mul_f32_e32 v50, v51, v50
	v_mul_f32_e32 v46, v46, v50
	v_and_b32_e32 v50, 0xffff0000, v90
	v_mul_f32_e32 v51, 0xbfb8aa3b, v50
	v_exp_f32_e32 v51, v51
	s_nop 0
	v_add_f32_e32 v51, 1.0, v51
	v_rcp_f32_e32 v51, v51
	s_nop 0
	v_mul_f32_e32 v50, v51, v50
	v_mul_f32_e32 v47, v47, v50
	v_cvt_pk_bf16_f32 v46, v46, v47
	v_lshlrev_b32_e32 v47, 16, v91
	v_mul_f32_e32 v50, 0xbfb8aa3b, v47
	v_exp_f32_e32 v50, v50
	s_nop 0
	v_add_f32_e32 v50, 1.0, v50
	v_rcp_f32_e32 v50, v50
	s_nop 0
	v_mul_f32_e32 v47, v50, v47
	v_mul_f32_e32 v47, v48, v47
	v_and_b32_e32 v48, 0xffff0000, v91
	v_mul_f32_e32 v50, 0xbfb8aa3b, v48
	v_exp_f32_e32 v50, v50
	s_nop 0
	v_add_f32_e32 v50, 1.0, v50
	v_rcp_f32_e32 v50, v50
	s_nop 0
	v_mul_f32_e32 v48, v50, v48
	v_mul_f32_e32 v48, v49, v48
	v_cvt_pk_bf16_f32 v47, v47, v48
	v_lshlrev_b32_e32 v48, 16, v92
	v_mul_f32_e32 v49, 0xbfb8aa3b, v48
	v_exp_f32_e32 v49, v49
	s_nop 0
	v_add_f32_e32 v49, 1.0, v49
	v_rcp_f32_e32 v49, v49
	s_nop 0
	v_mul_f32_e32 v48, v49, v48
	v_mul_f32_e32 v42, v42, v48
	v_and_b32_e32 v48, 0xffff0000, v92
	v_mul_f32_e32 v49, 0xbfb8aa3b, v48
	v_exp_f32_e32 v49, v49
	s_nop 0
	v_add_f32_e32 v49, 1.0, v49
	v_rcp_f32_e32 v49, v49
	s_nop 0
	v_mul_f32_e32 v48, v49, v48
	v_mul_f32_e32 v43, v43, v48
	v_cvt_pk_bf16_f32 v48, v42, v43
	v_lshlrev_b32_e32 v42, 16, v93
	v_mul_f32_e32 v43, 0xbfb8aa3b, v42
	v_exp_f32_e32 v43, v43
	s_nop 0
	v_add_f32_e32 v43, 1.0, v43
	v_rcp_f32_e32 v43, v43
	s_nop 0
	v_mul_f32_e32 v42, v43, v42
	v_and_b32_e32 v43, 0xffff0000, v93
	v_mul_f32_e32 v42, v44, v42
	v_mul_f32_e32 v44, 0xbfb8aa3b, v43
	v_exp_f32_e32 v44, v44
	s_nop 0
	v_add_f32_e32 v44, 1.0, v44
	v_rcp_f32_e32 v44, v44
	s_nop 0
	v_mul_f32_e32 v43, v44, v43
	v_mul_f32_e32 v43, v45, v43
	v_cvt_pk_bf16_f32 v49, v42, v43
	v_lshlrev_b32_e32 v42, 16, v86
	v_mul_f32_e32 v43, 0xbfb8aa3b, v42
	v_exp_f32_e32 v43, v43
	global_store_dwordx4 v[122:123], v[46:49], off offset:256
	v_add_f32_e32 v43, 1.0, v43
	v_rcp_f32_e32 v43, v43
	s_nop 0
	v_mul_f32_e32 v42, v43, v42
	v_mul_f32_e32 v30, v30, v42
	v_and_b32_e32 v42, 0xffff0000, v86
	v_mul_f32_e32 v43, 0xbfb8aa3b, v42
	v_exp_f32_e32 v43, v43
	s_nop 0
	v_add_f32_e32 v43, 1.0, v43
	v_rcp_f32_e32 v43, v43
	s_nop 0
	v_mul_f32_e32 v42, v43, v42
	v_mul_f32_e32 v31, v31, v42
	v_cvt_pk_bf16_f32 v30, v30, v31
	v_lshlrev_b32_e32 v31, 16, v87
	v_mul_f32_e32 v42, 0xbfb8aa3b, v31
	v_exp_f32_e32 v42, v42
	s_nop 0
	v_add_f32_e32 v42, 1.0, v42
	v_rcp_f32_e32 v42, v42
	s_nop 0
	v_mul_f32_e32 v31, v42, v31
	v_mul_f32_e32 v31, v32, v31
	v_and_b32_e32 v32, 0xffff0000, v87
	v_mul_f32_e32 v42, 0xbfb8aa3b, v32
	v_exp_f32_e32 v42, v42
	s_nop 0
	v_add_f32_e32 v42, 1.0, v42
	v_rcp_f32_e32 v42, v42
	s_nop 0
	v_mul_f32_e32 v32, v42, v32
	v_mul_f32_e32 v32, v33, v32
	v_cvt_pk_bf16_f32 v31, v31, v32
	v_lshlrev_b32_e32 v32, 16, v88
	v_mul_f32_e32 v33, 0xbfb8aa3b, v32
	v_exp_f32_e32 v33, v33
	s_nop 0
	v_add_f32_e32 v33, 1.0, v33
	v_rcp_f32_e32 v33, v33
	s_nop 0
	v_mul_f32_e32 v32, v33, v32
	v_mul_f32_e32 v26, v26, v32
	v_and_b32_e32 v32, 0xffff0000, v88
	v_mul_f32_e32 v33, 0xbfb8aa3b, v32
	v_exp_f32_e32 v33, v33
	s_nop 0
	v_add_f32_e32 v33, 1.0, v33
	v_rcp_f32_e32 v33, v33
	s_nop 0
	v_mul_f32_e32 v32, v33, v32
	v_mul_f32_e32 v27, v27, v32
	v_cvt_pk_bf16_f32 v32, v26, v27
	v_lshlrev_b32_e32 v26, 16, v89
	v_mul_f32_e32 v27, 0xbfb8aa3b, v26
	v_exp_f32_e32 v27, v27
	s_nop 0
	v_add_f32_e32 v27, 1.0, v27
	v_rcp_f32_e32 v27, v27
	s_nop 0
	v_mul_f32_e32 v26, v27, v26
	v_and_b32_e32 v27, 0xffff0000, v89
	v_mul_f32_e32 v26, v28, v26
	v_mul_f32_e32 v28, 0xbfb8aa3b, v27
	v_exp_f32_e32 v28, v28
	s_nop 0
	v_add_f32_e32 v28, 1.0, v28
	v_rcp_f32_e32 v28, v28
	s_nop 0
	v_mul_f32_e32 v27, v28, v27
	v_mul_f32_e32 v27, v29, v27
	v_cvt_pk_bf16_f32 v33, v26, v27
	v_lshlrev_b32_e32 v26, 16, v82
	v_mul_f32_e32 v27, 0xbfb8aa3b, v26
	v_exp_f32_e32 v27, v27
	global_store_dwordx4 v[112:113], v[30:33], off offset:256
	v_add_f32_e32 v27, 1.0, v27
	v_rcp_f32_e32 v27, v27
	s_nop 0
	v_mul_f32_e32 v26, v27, v26
	v_mul_f32_e32 v22, v22, v26
	v_and_b32_e32 v26, 0xffff0000, v82
	v_mul_f32_e32 v27, 0xbfb8aa3b, v26
	v_exp_f32_e32 v27, v27
	s_nop 0
	v_add_f32_e32 v27, 1.0, v27
	v_rcp_f32_e32 v27, v27
	s_nop 0
	v_mul_f32_e32 v26, v27, v26
	v_mul_f32_e32 v23, v23, v26
	v_cvt_pk_bf16_f32 v22, v22, v23
	v_lshlrev_b32_e32 v23, 16, v83
	v_mul_f32_e32 v26, 0xbfb8aa3b, v23
	v_exp_f32_e32 v26, v26
	s_nop 0
	v_add_f32_e32 v26, 1.0, v26
	v_rcp_f32_e32 v26, v26
	s_nop 0
	v_mul_f32_e32 v23, v26, v23
	v_mul_f32_e32 v23, v24, v23
	v_and_b32_e32 v24, 0xffff0000, v83
	v_mul_f32_e32 v26, 0xbfb8aa3b, v24
	v_exp_f32_e32 v26, v26
	s_nop 0
	v_add_f32_e32 v26, 1.0, v26
	v_rcp_f32_e32 v26, v26
; __device__ __forceinline__ unsigned cvt_pk_bf16(float lo, float hi) { unsigned r; asm volatile("v_cvt_pk_bf16_f32 %0, %1, %2" : "=v"(r) : "v"(lo), "v"(hi)); return r; }
; __device__ __forceinline__ float bf_lo(unsigned w) { return __uint_as_float(w << 16); }
; __device__ __forceinline__ float bf_hi(unsigned w) { return __uint_as_float(w & 0xffff0000u); }
; __device__ __forceinline__ float silu_f(float z) { return z * fast_rcp(1.0f + __builtin_amdgcn_exp2f(z * -1.44269504f)); }
; #define PG8_WAIT_V(n) asm volatile("s_waitcnt vmcnt(" #n ")" ::: "memory")
; #define PG8_BAR __builtin_amdgcn_s_barrier()
; template <class Epi>
; __device__ __forceinline__ void gemm_phase(LAS unsigned char* lds, const Gemm g, const StaticOrder& S, const Epi& E) {
;     ...
;         if (!has_next) break;
; #pragma unroll
;         for (int a = 0; a < 2; ++a)
; #pragma unroll
;             for (int b = 0; b < 2; ++b)
; #pragma unroll
;                 for (int m = 0; m < 4; ++m)
; #pragma unroll
;                     for (int n = 0; n < 2; ++n) acc[a][b][m][n] = (f32x4){0.f, 0.f, 0.f, 0.f};
;         cur = nxt; cA = nA; cB = nB; ++ui;
;         pre = E.pre(cur, wr, fr);
;     }
;     PG8_WAIT_V(0);
;     if (wr == 0) PG8_BAR;
;     PG8_BAR;
;     __device__ __forceinline__ void operator()(const f32x4 (&acc)[2][2][4][2], const Unit& u, int wr, int wc, int fr, int fq, const Pre&) const {
;     ...
;                 for (int m = 0; m < 4; ++m) { const int r = row0 + ai * HALF + m * 16;
;                     const u32x4 zw = zv[ai * 4 + m];
;                     const f32x4 a0 = acc[ai][bj][m][0] * sc[bj][0], a1 = acc[ai][bj][m][1] * sc[bj][1];
;                     u32x4 w;
;                     w.x = cvt_pk_bf16(a0[0] * silu_f(bf_lo(zw.x)), a0[1] * silu_f(bf_hi(zw.x)));
;                     w.y = cvt_pk_bf16(a0[2] * silu_f(bf_lo(zw.y)), a0[3] * silu_f(bf_hi(zw.y)));
;                     w.z = cvt_pk_bf16(a1[0] * silu_f(bf_lo(zw.z)), a1[1] * silu_f(bf_hi(zw.z)));
;                     w.w = cvt_pk_bf16(a1[2] * silu_f(bf_lo(zw.w)), a1[3] * silu_f(bf_hi(zw.w)));
;                     *(u32x4*)(O + (size_t)r * DE + c) = w; } }
	s_nop 0
	v_mul_f32_e32 v24, v26, v24
	v_mul_f32_e32 v24, v25, v24
	v_cvt_pk_bf16_f32 v23, v23, v24
	v_lshlrev_b32_e32 v24, 16, v84
	v_mul_f32_e32 v25, 0xbfb8aa3b, v24
	v_exp_f32_e32 v25, v25
	s_nop 0
	v_add_f32_e32 v25, 1.0, v25
	v_rcp_f32_e32 v25, v25
	s_nop 0
	v_mul_f32_e32 v24, v25, v24
	v_mul_f32_e32 v18, v18, v24
	v_and_b32_e32 v24, 0xffff0000, v84
	v_mul_f32_e32 v25, 0xbfb8aa3b, v24
	v_exp_f32_e32 v25, v25
	s_nop 0
	v_add_f32_e32 v25, 1.0, v25
	v_rcp_f32_e32 v25, v25
	s_nop 0
	v_mul_f32_e32 v24, v25, v24
	v_mul_f32_e32 v19, v19, v24
	v_cvt_pk_bf16_f32 v24, v18, v19
	v_lshlrev_b32_e32 v18, 16, v85
	v_mul_f32_e32 v19, 0xbfb8aa3b, v18
	v_exp_f32_e32 v19, v19
	s_nop 0
	v_add_f32_e32 v19, 1.0, v19
	v_rcp_f32_e32 v19, v19
	s_nop 0
	v_mul_f32_e32 v18, v19, v18
	v_and_b32_e32 v19, 0xffff0000, v85
	v_mul_f32_e32 v18, v20, v18
	v_mul_f32_e32 v20, 0xbfb8aa3b, v19
	v_exp_f32_e32 v20, v20
	s_nop 0
	v_add_f32_e32 v20, 1.0, v20
	v_rcp_f32_e32 v20, v20
	s_nop 0
	v_mul_f32_e32 v19, v20, v19
	v_mul_f32_e32 v19, v21, v19
	v_cvt_pk_bf16_f32 v25, v18, v19
	v_lshlrev_b32_e32 v18, 16, v78
	v_mul_f32_e32 v19, 0xbfb8aa3b, v18
	v_exp_f32_e32 v19, v19
	global_store_dwordx4 v[110:111], v[22:25], off offset:256
	v_add_f32_e32 v19, 1.0, v19
	v_rcp_f32_e32 v19, v19
	s_nop 0
	v_mul_f32_e32 v18, v19, v18
	v_mul_f32_e32 v14, v14, v18
	v_and_b32_e32 v18, 0xffff0000, v78
	v_mul_f32_e32 v19, 0xbfb8aa3b, v18
	v_exp_f32_e32 v19, v19
	s_nop 0
	v_add_f32_e32 v19, 1.0, v19
	v_rcp_f32_e32 v19, v19
	s_nop 0
	v_mul_f32_e32 v18, v19, v18
	v_mul_f32_e32 v15, v15, v18
	v_cvt_pk_bf16_f32 v14, v14, v15
	v_lshlrev_b32_e32 v15, 16, v79
	v_mul_f32_e32 v18, 0xbfb8aa3b, v15
	v_exp_f32_e32 v18, v18
	s_nop 0
	v_add_f32_e32 v18, 1.0, v18
	v_rcp_f32_e32 v18, v18
	s_nop 0
	v_mul_f32_e32 v15, v18, v15
	v_mul_f32_e32 v15, v16, v15
	v_and_b32_e32 v16, 0xffff0000, v79
	v_mul_f32_e32 v18, 0xbfb8aa3b, v16
	v_exp_f32_e32 v18, v18
	s_nop 0
	v_add_f32_e32 v18, 1.0, v18
	v_rcp_f32_e32 v18, v18
	s_nop 0
	v_mul_f32_e32 v16, v18, v16
	v_mul_f32_e32 v16, v17, v16
	v_cvt_pk_bf16_f32 v15, v15, v16
	v_lshlrev_b32_e32 v16, 16, v80
	v_mul_f32_e32 v17, 0xbfb8aa3b, v16
	v_exp_f32_e32 v17, v17
	s_nop 0
	v_add_f32_e32 v17, 1.0, v17
	v_rcp_f32_e32 v17, v17
	s_nop 0
	v_mul_f32_e32 v16, v17, v16
	v_mul_f32_e32 v10, v10, v16
	v_and_b32_e32 v16, 0xffff0000, v80
	v_mul_f32_e32 v17, 0xbfb8aa3b, v16
	v_exp_f32_e32 v17, v17
	s_nop 0
	v_add_f32_e32 v17, 1.0, v17
	v_rcp_f32_e32 v17, v17
	s_nop 0
	v_mul_f32_e32 v16, v17, v16
	v_mul_f32_e32 v11, v11, v16
	v_cvt_pk_bf16_f32 v16, v10, v11
	v_lshlrev_b32_e32 v10, 16, v81
	v_mul_f32_e32 v11, 0xbfb8aa3b, v10
	v_exp_f32_e32 v11, v11
	s_nop 0
	v_add_f32_e32 v11, 1.0, v11
	v_rcp_f32_e32 v11, v11
	s_nop 0
	v_mul_f32_e32 v10, v11, v10
	v_and_b32_e32 v11, 0xffff0000, v81
	v_mul_f32_e32 v10, v12, v10
	v_mul_f32_e32 v12, 0xbfb8aa3b, v11
	v_exp_f32_e32 v12, v12
	s_nop 0
	v_add_f32_e32 v12, 1.0, v12
	v_rcp_f32_e32 v12, v12
	s_nop 0
	v_mul_f32_e32 v11, v12, v11
	v_mul_f32_e32 v11, v13, v11
	v_cvt_pk_bf16_f32 v17, v10, v11
	v_lshlrev_b32_e32 v10, 16, v74
	v_mul_f32_e32 v11, 0xbfb8aa3b, v10
	v_exp_f32_e32 v11, v11
	global_store_dwordx4 v[114:115], v[14:17], off offset:256
	v_add_f32_e32 v11, 1.0, v11
	v_rcp_f32_e32 v11, v11
	s_nop 0
	v_mul_f32_e32 v10, v11, v10
	v_mul_f32_e32 v6, v6, v10
	v_and_b32_e32 v10, 0xffff0000, v74
	v_mul_f32_e32 v11, 0xbfb8aa3b, v10
	v_exp_f32_e32 v11, v11
	s_nop 0
	v_add_f32_e32 v11, 1.0, v11
	v_rcp_f32_e32 v11, v11
	s_nop 0
	v_mul_f32_e32 v10, v11, v10
	v_mul_f32_e32 v7, v7, v10
	v_cvt_pk_bf16_f32 v6, v6, v7
	v_lshlrev_b32_e32 v7, 16, v75
	v_mul_f32_e32 v10, 0xbfb8aa3b, v7
	v_exp_f32_e32 v10, v10
	s_nop 0
	v_add_f32_e32 v10, 1.0, v10
	v_rcp_f32_e32 v10, v10
	s_nop 0
	v_mul_f32_e32 v7, v10, v7
	v_mul_f32_e32 v7, v8, v7
	v_and_b32_e32 v8, 0xffff0000, v75
	v_mul_f32_e32 v10, 0xbfb8aa3b, v8
	v_exp_f32_e32 v10, v10
	s_nop 0
	v_add_f32_e32 v10, 1.0, v10
	v_rcp_f32_e32 v10, v10
	s_nop 0
	v_mul_f32_e32 v8, v10, v8
	v_mul_f32_e32 v8, v9, v8
	v_cvt_pk_bf16_f32 v7, v7, v8
	v_lshlrev_b32_e32 v8, 16, v76
	v_mul_f32_e32 v9, 0xbfb8aa3b, v8
	v_exp_f32_e32 v9, v9
	s_nop 0
	v_add_f32_e32 v9, 1.0, v9
	v_rcp_f32_e32 v9, v9
	s_nop 0
	v_mul_f32_e32 v8, v9, v8
	v_mul_f32_e32 v2, v2, v8
	v_and_b32_e32 v8, 0xffff0000, v76
	v_mul_f32_e32 v9, 0xbfb8aa3b, v8
	v_exp_f32_e32 v9, v9
	s_nop 0
	v_add_f32_e32 v9, 1.0, v9
	v_rcp_f32_e32 v9, v9
	s_nop 0
	v_mul_f32_e32 v8, v9, v8
	v_mul_f32_e32 v3, v3, v8
	v_cvt_pk_bf16_f32 v8, v2, v3
	v_lshlrev_b32_e32 v2, 16, v77
	v_mul_f32_e32 v3, 0xbfb8aa3b, v2
	v_exp_f32_e32 v3, v3
	s_nop 0
	v_add_f32_e32 v3, 1.0, v3
	v_rcp_f32_e32 v3, v3
	s_nop 0
	v_mul_f32_e32 v2, v3, v2
	v_and_b32_e32 v3, 0xffff0000, v77
	v_mul_f32_e32 v2, v4, v2
	v_mul_f32_e32 v4, 0xbfb8aa3b, v3
	v_exp_f32_e32 v4, v4
	s_nop 0
	v_add_f32_e32 v4, 1.0, v4
	v_rcp_f32_e32 v4, v4
	s_nop 0
	v_mul_f32_e32 v3, v4, v3
	v_mul_f32_e32 v3, v5, v3
	v_cvt_pk_bf16_f32 v9, v2, v3
	global_store_dwordx4 v[106:107], v[6:9], off offset:256
	s_cbranch_vccz .LBB0_596
	s_waitcnt vmcnt(0)
	s_cmpk_gt_u32 s14, 0xff
	s_mov_b64 s[36:37], s[96:97]
	s_cbranch_scc1 .LBB0_607
	s_barrier

; #define PG8_STAGE(bufoff, gbase, voff) do { _Pragma("unroll") for (int _i = 0; _i < 2; ++_i) \
;         __builtin_amdgcn_global_load_lds((const unsigned*)((const char*)(gbase) + (voff)[_i]), (LAS unsigned*)(lds + (bufoff) + ldsw + _i * 8192), 16, 0, 0); } while (0)
; #define PG8_LDA(dst, b, h) do { _Pragma("unroll") for (int m = 0; m < 4; ++m) _Pragma("unroll") for (int k = 0; k < 2; ++k) dst[m][k] = *(const LAS bf16x8*)(lds + PG8_SA(b, h) + aoff + m * 2048 + k * 1024); } while (0)
; #define PG8_LDB(dst, b, h) do { _Pragma("unroll") for (int n = 0; n < 2; ++n) _Pragma("unroll") for (int k = 0; k < 2; ++k) dst[n][k] = *(const LAS bf16x8*)(lds + PG8_SB(b, h) + boff + n * 2048 + k * 1024); } while (0)
; #define PG8_WAIT_V(n) asm volatile("s_waitcnt vmcnt(" #n ")" ::: "memory")
; #define PG8_WAIT_L(n) asm volatile("s_waitcnt lgkmcnt(" #n ")" ::: "memory")
; #define PG8_BAR __builtin_amdgcn_s_barrier()
; template <class Epi>
; __device__ __forceinline__ void gemm_phase(LAS unsigned char* lds, const Gemm g, const StaticOrder& S, const Epi& E) {
;     ...
;         for (int t = 0; t < nt; t += 2) {
;             const bool last = (t == nt - 2);
;             const char* a1 = cA + (size_t)(t + 1) * kstepA;
;             const char* a2 = last ? nA : cA + (size_t)(t + 2) * kstepA; const char* b2 = last ? nB : cB + (size_t)(t + 2) * kstep;
;             const char* a3 = a2 + kstepA; const char* b3 = b2 + kstep;
;             PG8_LDB(B0, 0, 0); PG8_SCHED; PG8_LDA(At, 0, 0); PG8_STAGE(PG8_SA(1, 1), a1 + hstepA, voffA);
;             PG8_WAIT_L(8); PG8_BAR; PG8_WAIT_L(0); PG8_MMA(0, 0, At, B0); PG8_BAR; PG8_SCHED;
;             PG8_LDB(B1, 0, 1); PG8_STAGE(PG8_SB(0, 0), b2, voffB);
;             PG8_BAR; PG8_WAIT_L(0); PG8_MMA(0, 1, At, B1); PG8_BAR;
;             PG8_LDA(At, 0, 1); PG8_STAGE(PG8_SA(0, 0), a2, voffA);
;             PG8_BAR; PG8_WAIT_L(0); PG8_MMA(1, 0, At, B0); PG8_BAR; PG8_SCHED;
;             PG8_STAGE(PG8_SB(0, 1), b2 + hstepB, voffB);
;             PG8_WAIT_V(6); PG8_BAR; PG8_MMA(1, 1, At, B1); PG8_BAR;
;             PG8_LDB(B0, 1, 0); PG8_SCHED; PG8_LDA(At, 1, 0); PG8_STAGE(PG8_SA(0, 1), a2 + hstepA, voffA);
;             PG8_WAIT_L(8); PG8_BAR; PG8_WAIT_L(0); PG8_MMA(0, 0, At, B0); PG8_BAR; PG8_SCHED;
;             PG8_LDB(B1, 1, 1); PG8_STAGE(PG8_SB(1, 0), b3, voffB);
;             PG8_BAR; PG8_WAIT_L(0); PG8_MMA(0, 1, At, B1); PG8_BAR;
.LBB0_796:
	s_add_u32 s4, s8, 0x103400
	s_addc_u32 s5, s9, 0
	s_cmp_eq_u32 s57, 60
	s_cselect_b32 s16, s38, s4
	s_cselect_b32 s17, s37, s5
	s_cselect_b32 s4, s49, s51
	s_cselect_b32 s5, s39, s56
	s_add_u32 s14, s16, 0x104400
	s_addc_u32 s15, s17, 0
	s_add_i32 s58, 0, 0x10000
	v_add_u32_e32 v102, s58, v245
	ds_read_b128 v[26:29], v102
	ds_read_b128 v[30:33], v102 offset:1024
	ds_read_b128 v[98:101], v102 offset:2048
	ds_read_b128 v[102:105], v102 offset:3072
	v_lshl_add_u64 v[184:185], s[8:9], 0, v[196:197]
	s_add_i32 m0, s22, 0xc000
	ds_read_b128 v[130:133], v247
	ds_read_b128 v[142:145], v247 offset:1024
	ds_read_b128 v[146:149], v247 offset:2048
	ds_read_b128 v[150:153], v247 offset:3072
	ds_read_b128 v[154:157], v247 offset:4096
	ds_read_b128 v[166:169], v247 offset:5120
	ds_read_b128 v[170:173], v247 offset:6144
	ds_read_b128 v[174:177], v247 offset:7168
	global_load_lds_dwordx4 v[184:185], off
	v_lshl_add_u64 v[184:185], s[8:9], 0, v[198:199]
	s_add_i32 m0, s22, 0xe000
	s_nop 0
	global_load_lds_dwordx4 v[184:185], off
	s_waitcnt lgkmcnt(8)
	s_barrier
	s_waitcnt lgkmcnt(0)
	s_setprio 1
	s_waitcnt lgkmcnt(0)
	v_mfma_f32_16x16x32_bf16 v[162:165], v[26:29], v[130:133], v[162:165]
	v_mfma_f32_16x16x32_bf16 v[158:161], v[98:101], v[130:133], v[158:161]
	v_mfma_f32_16x16x32_bf16 v[138:141], v[26:29], v[146:149], v[138:141]
	v_mfma_f32_16x16x32_bf16 v[134:137], v[98:101], v[146:149], v[134:137]
	v_mfma_f32_16x16x32_bf16 v[126:129], v[26:29], v[154:157], v[126:129]
	v_mfma_f32_16x16x32_bf16 v[122:125], v[98:101], v[154:157], v[122:125]
	v_mfma_f32_16x16x32_bf16 v[118:121], v[26:29], v[170:173], v[118:121]
	v_mfma_f32_16x16x32_bf16 v[114:117], v[98:101], v[170:173], v[114:117]
	v_mfma_f32_16x16x32_bf16 v[162:165], v[30:33], v[142:145], v[162:165]
	v_mfma_f32_16x16x32_bf16 v[158:161], v[102:105], v[142:145], v[158:161]
	v_mfma_f32_16x16x32_bf16 v[138:141], v[30:33], v[150:153], v[138:141]
	v_mfma_f32_16x16x32_bf16 v[134:137], v[102:105], v[150:153], v[134:137]
	v_mfma_f32_16x16x32_bf16 v[126:129], v[30:33], v[166:169], v[126:129]
	v_mfma_f32_16x16x32_bf16 v[122:125], v[102:105], v[166:169], v[122:125]
	v_mfma_f32_16x16x32_bf16 v[118:121], v[30:33], v[174:177], v[118:121]
	v_mfma_f32_16x16x32_bf16 v[114:117], v[102:105], v[174:177], v[114:117]
	s_setprio 0
	s_barrier
	s_add_i32 s60, 0, 0x14000
	s_add_i32 s58, s58, s21
	v_add_u32_e32 v208, s60, v245
	v_lshl_add_u64 v[212:213], s[4:5], 0, v[0:1]
	s_mov_b32 m0, s58
	ds_read_b128 v[184:187], v208
	ds_read_b128 v[200:203], v208 offset:1024
	ds_read_b128 v[204:207], v208 offset:2048
	ds_read_b128 v[208:211], v208 offset:3072
	global_load_lds_dwordx4 v[212:213], off
	v_lshl_add_u64 v[214:215], s[4:5], 0, v[188:189]
	s_add_i32 m0, s58, 0x2000
	s_nop 0
	global_load_lds_dwordx4 v[214:215], off
	s_waitcnt vmcnt(10)
	s_barrier
	s_waitcnt lgkmcnt(0)
	s_setprio 1
	s_waitcnt lgkmcnt(0)
	v_mfma_f32_16x16x32_bf16 v[70:73], v[184:187], v[130:133], v[70:73]
	v_mfma_f32_16x16x32_bf16 v[66:69], v[204:207], v[130:133], v[66:69]
	v_mfma_f32_16x16x32_bf16 v[62:65], v[184:187], v[146:149], v[62:65]
	v_mfma_f32_16x16x32_bf16 v[58:61], v[204:207], v[146:149], v[58:61]
	v_mfma_f32_16x16x32_bf16 v[54:57], v[184:187], v[154:157], v[54:57]
	v_mfma_f32_16x16x32_bf16 v[50:53], v[204:207], v[154:157], v[50:53]
	v_mfma_f32_16x16x32_bf16 v[46:49], v[184:187], v[170:173], v[46:49]
	v_mfma_f32_16x16x32_bf16 v[42:45], v[204:207], v[170:173], v[42:45]
	v_mfma_f32_16x16x32_bf16 v[70:73], v[200:203], v[142:145], v[70:73]
	v_mfma_f32_16x16x32_bf16 v[66:69], v[208:211], v[142:145], v[66:69]
	v_mfma_f32_16x16x32_bf16 v[62:65], v[200:203], v[150:153], v[62:65]
	v_mfma_f32_16x16x32_bf16 v[58:61], v[208:211], v[150:153], v[58:61]
	v_mfma_f32_16x16x32_bf16 v[54:57], v[200:203], v[166:169], v[54:57]
	v_mfma_f32_16x16x32_bf16 v[50:53], v[208:211], v[166:169], v[50:53]
	v_mfma_f32_16x16x32_bf16 v[46:49], v[200:203], v[174:177], v[46:49]
	v_mfma_f32_16x16x32_bf16 v[42:45], v[208:211], v[174:177], v[42:45]
	s_setprio 0
	s_mov_b32 m0, s22
	v_lshl_add_u64 v[216:217], s[16:17], 0, v[192:193]
	s_barrier
	ds_read_b128 v[130:133], v247 offset:16384
	ds_read_b128 v[142:145], v247 offset:17408
	ds_read_b128 v[146:149], v247 offset:18432
	ds_read_b128 v[150:153], v247 offset:19456
	ds_read_b128 v[154:157], v247 offset:20480
	ds_read_b128 v[166:169], v247 offset:21504
	ds_read_b128 v[170:173], v247 offset:22528
	ds_read_b128 v[174:177], v247 offset:23552
	global_load_lds_dwordx4 v[216:217], off
	v_lshl_add_u64 v[216:217], s[16:17], 0, v[190:191]
	s_mov_b32 m0, s23
	s_nop 0
	global_load_lds_dwordx4 v[216:217], off
	s_barrier
	s_waitcnt lgkmcnt(0)
	s_setprio 1
	s_waitcnt lgkmcnt(0)
	v_mfma_f32_16x16x32_bf16 v[110:113], v[26:29], v[130:133], v[110:113]
	v_mfma_f32_16x16x32_bf16 v[106:109], v[98:101], v[130:133], v[106:109]
	v_mfma_f32_16x16x32_bf16 v[94:97], v[26:29], v[146:149], v[94:97]
	v_mfma_f32_16x16x32_bf16 v[90:93], v[98:101], v[146:149], v[90:93]
	v_mfma_f32_16x16x32_bf16 v[86:89], v[26:29], v[154:157], v[86:89]
	v_mfma_f32_16x16x32_bf16 v[82:85], v[98:101], v[154:157], v[82:85]
	v_mfma_f32_16x16x32_bf16 v[26:29], v[26:29], v[170:173], v[78:81]
	v_mfma_f32_16x16x32_bf16 v[110:113], v[30:33], v[142:145], v[110:113]
	v_mfma_f32_16x16x32_bf16 v[106:109], v[102:105], v[142:145], v[106:109]
	v_mfma_f32_16x16x32_bf16 v[94:97], v[30:33], v[150:153], v[94:97]
	v_mfma_f32_16x16x32_bf16 v[90:93], v[102:105], v[150:153], v[90:93]
	v_mfma_f32_16x16x32_bf16 v[86:89], v[30:33], v[166:169], v[86:89]
	v_mfma_f32_16x16x32_bf16 v[82:85], v[102:105], v[166:169], v[82:85]
	v_mfma_f32_16x16x32_bf16 v[26:29], v[30:33], v[174:177], v[26:29]
	v_mfma_f32_16x16x32_bf16 v[30:33], v[98:101], v[170:173], v[74:77]
	v_mfma_f32_16x16x32_bf16 v[30:33], v[102:105], v[174:177], v[30:33]
	s_setprio 0
	s_barrier
; #define PG8_STAGE(bufoff, gbase, voff) do { _Pragma("unroll") for (int _i = 0; _i < 2; ++_i) \
;         __builtin_amdgcn_global_load_lds((const unsigned*)((const char*)(gbase) + (voff)[_i]), (LAS unsigned*)(lds + (bufoff) + ldsw + _i * 8192), 16, 0, 0); } while (0)
; #define PG8_LDA(dst, b, h) do { _Pragma("unroll") for (int m = 0; m < 4; ++m) _Pragma("unroll") for (int k = 0; k < 2; ++k) dst[m][k] = *(const LAS bf16x8*)(lds + PG8_SA(b, h) + aoff + m * 2048 + k * 1024); } while (0)
; #define PG8_LDB(dst, b, h) do { _Pragma("unroll") for (int n = 0; n < 2; ++n) _Pragma("unroll") for (int k = 0; k < 2; ++k) dst[n][k] = *(const LAS bf16x8*)(lds + PG8_SB(b, h) + boff + n * 2048 + k * 1024); } while (0)
; #define PG8_MMA(ai, bj, At, Bt) do { __builtin_amdgcn_s_setprio(1); _Pragma("unroll") for (int m = 0; m < 4; ++m) _Pragma("unroll") for (int n = 0; n < 2; ++n) _Pragma("unroll") for (int k = 0; k < 2; ++k) \
;         acc[ai][bj][m][n] = __builtin_amdgcn_mfma_f32_16x16x32_bf16(Bt[n][k], At[m][k], acc[ai][bj][m][n], 0, 0, 0); __builtin_amdgcn_s_setprio(0); } while (0)
; #define PG8_WAIT_V(n) asm volatile("s_waitcnt vmcnt(" #n ")" ::: "memory")
; #define PG8_WAIT_L(n) asm volatile("s_waitcnt lgkmcnt(" #n ")" ::: "memory")
; #define PG8_BAR __builtin_amdgcn_s_barrier()
; #define PG8_SCHED __builtin_amdgcn_sched_barrier(0)
; template <class Epi>
; __device__ __forceinline__ void gemm_phase(LAS unsigned char* lds, const Gemm g, const StaticOrder& S, const Epi& E) {
;     ...
;             PG8_STAGE(PG8_SB(0, 1), b2 + hstepB, voffB);
;             PG8_WAIT_V(6); PG8_BAR; PG8_MMA(1, 1, At, B1); PG8_BAR;
;             PG8_LDB(B0, 1, 0); PG8_SCHED; PG8_LDA(At, 1, 0); PG8_STAGE(PG8_SA(0, 1), a2 + hstepA, voffA);
;             PG8_WAIT_L(8); PG8_BAR; PG8_WAIT_L(0); PG8_MMA(0, 0, At, B0); PG8_BAR; PG8_SCHED;
;             PG8_LDB(B1, 1, 1); PG8_STAGE(PG8_SB(1, 0), b3, voffB);
;             PG8_BAR; PG8_WAIT_L(0); PG8_MMA(0, 1, At, B1); PG8_BAR;
;             PG8_LDA(At, 1, 1); PG8_STAGE(PG8_SA(1, 0), a3, voffA);
;             PG8_BAR; PG8_WAIT_L(0); PG8_MMA(1, 0, At, B0); PG8_BAR; PG8_SCHED;
	s_add_u32 s58, s4, 0x100000
	s_addc_u32 s59, s5, 0
	s_add_i32 s60, s60, s21
	v_lshl_add_u64 v[74:75], s[58:59], 0, v[0:1]
	s_mov_b32 m0, s60
	s_nop 0
	global_load_lds_dwordx4 v[74:75], off
	v_lshl_add_u64 v[74:75], s[58:59], 0, v[188:189]
	s_add_i32 m0, s60, 0x2000
	s_nop 0
	global_load_lds_dwordx4 v[74:75], off
	s_waitcnt vmcnt(8)
	s_barrier
	s_setprio 1
	v_mfma_f32_16x16x32_bf16 v[38:41], v[184:187], v[130:133], v[38:41]
	v_mfma_f32_16x16x32_bf16 v[34:37], v[204:207], v[130:133], v[34:37]
	v_mfma_f32_16x16x32_bf16 v[22:25], v[184:187], v[146:149], v[22:25]
	v_mfma_f32_16x16x32_bf16 v[18:21], v[204:207], v[146:149], v[18:21]
	v_mfma_f32_16x16x32_bf16 v[14:17], v[184:187], v[154:157], v[14:17]
	v_mfma_f32_16x16x32_bf16 v[10:13], v[204:207], v[154:157], v[10:13]
	v_mfma_f32_16x16x32_bf16 v[6:9], v[184:187], v[170:173], v[6:9]
	v_mfma_f32_16x16x32_bf16 v[2:5], v[204:207], v[170:173], v[2:5]
	v_mfma_f32_16x16x32_bf16 v[38:41], v[200:203], v[142:145], v[38:41]
	v_mfma_f32_16x16x32_bf16 v[34:37], v[208:211], v[142:145], v[34:37]
	v_mfma_f32_16x16x32_bf16 v[22:25], v[200:203], v[150:153], v[22:25]
	v_mfma_f32_16x16x32_bf16 v[18:21], v[208:211], v[150:153], v[18:21]
	v_mfma_f32_16x16x32_bf16 v[14:17], v[200:203], v[166:169], v[14:17]
	v_mfma_f32_16x16x32_bf16 v[10:13], v[208:211], v[166:169], v[10:13]
	v_mfma_f32_16x16x32_bf16 v[6:9], v[200:203], v[174:177], v[6:9]
	v_mfma_f32_16x16x32_bf16 v[2:5], v[208:211], v[174:177], v[2:5]
	s_setprio 0
	s_add_i32 s58, 0, 0x18000
	v_add_u32_e32 v102, s58, v245
	s_barrier
	ds_read_b128 v[74:77], v102
	ds_read_b128 v[78:81], v102 offset:1024
	ds_read_b128 v[98:101], v102 offset:2048
	ds_read_b128 v[102:105], v102 offset:3072
	s_add_u32 s16, s16, 0x1000
	s_addc_u32 s17, s17, 0
	s_mov_b32 m0, s24
	v_lshl_add_u64 v[184:185], s[16:17], 0, v[192:193]
	ds_read_b128 v[130:133], v247 offset:32768
	ds_read_b128 v[142:145], v247 offset:33792
	ds_read_b128 v[146:149], v247 offset:34816
	ds_read_b128 v[150:153], v247 offset:35840
	ds_read_b128 v[154:157], v247 offset:36864
	ds_read_b128 v[166:169], v247 offset:37888
	ds_read_b128 v[170:173], v247 offset:38912
	ds_read_b128 v[174:177], v247 offset:39936
	global_load_lds_dwordx4 v[184:185], off
	v_lshl_add_u64 v[184:185], s[16:17], 0, v[190:191]
	s_mov_b32 m0, s25
	s_nop 0
	global_load_lds_dwordx4 v[184:185], off
	s_waitcnt lgkmcnt(8)
	s_barrier
	s_waitcnt lgkmcnt(0)
	s_setprio 1
	s_waitcnt lgkmcnt(0)
	v_mfma_f32_16x16x32_bf16 v[162:165], v[74:77], v[130:133], v[162:165]
	v_mfma_f32_16x16x32_bf16 v[158:161], v[98:101], v[130:133], v[158:161]
	v_mfma_f32_16x16x32_bf16 v[138:141], v[74:77], v[146:149], v[138:141]
	v_mfma_f32_16x16x32_bf16 v[134:137], v[98:101], v[146:149], v[134:137]
	v_mfma_f32_16x16x32_bf16 v[126:129], v[74:77], v[154:157], v[126:129]
	v_mfma_f32_16x16x32_bf16 v[122:125], v[98:101], v[154:157], v[122:125]
	v_mfma_f32_16x16x32_bf16 v[118:121], v[74:77], v[170:173], v[118:121]
	v_mfma_f32_16x16x32_bf16 v[114:117], v[98:101], v[170:173], v[114:117]
	v_mfma_f32_16x16x32_bf16 v[162:165], v[78:81], v[142:145], v[162:165]
	v_mfma_f32_16x16x32_bf16 v[158:161], v[102:105], v[142:145], v[158:161]
	v_mfma_f32_16x16x32_bf16 v[138:141], v[78:81], v[150:153], v[138:141]
	v_mfma_f32_16x16x32_bf16 v[134:137], v[102:105], v[150:153], v[134:137]
	v_mfma_f32_16x16x32_bf16 v[126:129], v[78:81], v[166:169], v[126:129]
	v_mfma_f32_16x16x32_bf16 v[122:125], v[102:105], v[166:169], v[122:125]
	v_mfma_f32_16x16x32_bf16 v[118:121], v[78:81], v[174:177], v[118:121]
	v_mfma_f32_16x16x32_bf16 v[114:117], v[102:105], v[174:177], v[114:117]
	s_setprio 0
	s_barrier
	s_add_i32 s16, 0, 0x1c000
	s_add_i32 s17, s58, s21
	v_add_u32_e32 v208, s16, v245
	v_lshl_add_u64 v[212:213], v[212:213], 0, s[6:7]
	s_mov_b32 m0, s17
	ds_read_b128 v[184:187], v208
	ds_read_b128 v[200:203], v208 offset:1024
	ds_read_b128 v[204:207], v208 offset:2048
	ds_read_b128 v[208:211], v208 offset:3072
	global_load_lds_dwordx4 v[212:213], off
	v_lshl_add_u64 v[212:213], v[214:215], 0, s[6:7]
	s_add_i32 m0, s17, 0x2000
	s_nop 0
	global_load_lds_dwordx4 v[212:213], off
	s_waitcnt vmcnt(10)
	s_barrier
	s_waitcnt lgkmcnt(0)
	s_setprio 1
	s_waitcnt lgkmcnt(0)
	v_mfma_f32_16x16x32_bf16 v[70:73], v[184:187], v[130:133], v[70:73]
	v_mfma_f32_16x16x32_bf16 v[66:69], v[204:207], v[130:133], v[66:69]
	v_mfma_f32_16x16x32_bf16 v[62:65], v[184:187], v[146:149], v[62:65]
	v_mfma_f32_16x16x32_bf16 v[58:61], v[204:207], v[146:149], v[58:61]
	v_mfma_f32_16x16x32_bf16 v[54:57], v[184:187], v[154:157], v[54:57]
	v_mfma_f32_16x16x32_bf16 v[50:53], v[204:207], v[154:157], v[50:53]
	v_mfma_f32_16x16x32_bf16 v[46:49], v[184:187], v[170:173], v[46:49]
	v_mfma_f32_16x16x32_bf16 v[42:45], v[204:207], v[170:173], v[42:45]
	v_mfma_f32_16x16x32_bf16 v[70:73], v[200:203], v[142:145], v[70:73]
	v_mfma_f32_16x16x32_bf16 v[66:69], v[208:211], v[142:145], v[66:69]
	v_mfma_f32_16x16x32_bf16 v[62:65], v[200:203], v[150:153], v[62:65]
	v_mfma_f32_16x16x32_bf16 v[58:61], v[208:211], v[150:153], v[58:61]
	v_mfma_f32_16x16x32_bf16 v[54:57], v[200:203], v[166:169], v[54:57]
	v_mfma_f32_16x16x32_bf16 v[50:53], v[208:211], v[166:169], v[50:53]
	v_mfma_f32_16x16x32_bf16 v[46:49], v[200:203], v[174:177], v[46:49]
	v_mfma_f32_16x16x32_bf16 v[42:45], v[208:211], v[174:177], v[42:45]
	s_setprio 0
	s_mov_b32 m0, s26
	v_lshl_add_u64 v[212:213], s[14:15], 0, v[192:193]
	s_barrier
	ds_read_b128 v[130:133], v247 offset:49152
	ds_read_b128 v[142:145], v247 offset:50176
	ds_read_b128 v[146:149], v247 offset:51200
	ds_read_b128 v[150:153], v247 offset:52224
	ds_read_b128 v[154:157], v247 offset:53248
	ds_read_b128 v[166:169], v247 offset:54272
	ds_read_b128 v[170:173], v247 offset:55296
	ds_read_b128 v[174:177], v247 offset:56320
	global_load_lds_dwordx4 v[212:213], off
	v_lshl_add_u64 v[212:213], s[14:15], 0, v[190:191]
	s_mov_b32 m0, s27
	s_nop 0
	global_load_lds_dwordx4 v[212:213], off
	s_barrier
; #define PG8_STAGE(bufoff, gbase, voff) do { _Pragma("unroll") for (int _i = 0; _i < 2; ++_i) \
;         __builtin_amdgcn_global_load_lds((const unsigned*)((const char*)(gbase) + (voff)[_i]), (LAS unsigned*)(lds + (bufoff) + ldsw + _i * 8192), 16, 0, 0); } while (0)
; #define PG8_MMA(ai, bj, At, Bt) do { __builtin_amdgcn_s_setprio(1); _Pragma("unroll") for (int m = 0; m < 4; ++m) _Pragma("unroll") for (int n = 0; n < 2; ++n) _Pragma("unroll") for (int k = 0; k < 2; ++k) \
;         acc[ai][bj][m][n] = __builtin_amdgcn_mfma_f32_16x16x32_bf16(Bt[n][k], At[m][k], acc[ai][bj][m][n], 0, 0, 0); __builtin_amdgcn_s_setprio(0); } while (0)
; #define PG8_WAIT_V(n) asm volatile("s_waitcnt vmcnt(" #n ")" ::: "memory")
; #define PG8_WAIT_L(n) asm volatile("s_waitcnt lgkmcnt(" #n ")" ::: "memory")
; #define PG8_BAR __builtin_amdgcn_s_barrier()
; #define PG8_SCHED __builtin_amdgcn_sched_barrier(0)
; template <class Epi>
; __device__ __forceinline__ void gemm_phase(LAS unsigned char* lds, const Gemm g, const StaticOrder& S, const Epi& E) {
;     ...
;             PG8_BAR; PG8_WAIT_L(0); PG8_MMA(1, 0, At, B0); PG8_BAR; PG8_SCHED;
;             PG8_STAGE(PG8_SB(1, 1), b3 + hstepB, voffB);
;             PG8_WAIT_V(6); PG8_BAR; PG8_MMA(1, 1, At, B1); PG8_BAR;
;     __device__ __forceinline__ void operator()(const f32x4 (&acc)[2][2][4][2], const Unit& u, int wr, int wc, int fr, int fq, const Pre&) const {
;         const int row0 = u.pm * BM + wr * 64 + fr, col0 = u.pn * BM + wc * 32 + 8 * fq;
;         f32x4 bs[2][2];
; #pragma unroll
;         for (int bj = 0; bj < 2; ++bj) { bs[bj][0] = *(const f32x4*)(bias + col0 + bj * HALF); bs[bj][1] = *(const f32x4*)(bias + col0 + bj * HALF + 4); }
; #pragma unroll
;         for (int bj = 0; bj < 2; ++bj) { const int c = col0 + bj * HALF;
; #pragma unroll
;             for (int ai = 0; ai < 2; ++ai) { u32x4 zv[4], gv[4];
; #pragma unroll
;                 for (int m = 0; m < 4; ++m) { const int r = row0 + ai * HALF + m * 16; zv[m] = *(const u32x4*)(Z + (size_t)r * DE2 + c); gv[m] = *(const u32x4*)(Gm + (size_t)(c >> 4) * GSTR + r * 16 + (c & 15)); }
	s_waitcnt lgkmcnt(0)
	s_setprio 1
	s_waitcnt lgkmcnt(0)
	v_mfma_f32_16x16x32_bf16 v[110:113], v[74:77], v[130:133], v[110:113]
	v_mfma_f32_16x16x32_bf16 v[94:97], v[74:77], v[146:149], v[94:97]
	v_mfma_f32_16x16x32_bf16 v[86:89], v[74:77], v[154:157], v[86:89]
	v_mfma_f32_16x16x32_bf16 v[26:29], v[74:77], v[170:173], v[26:29]
	v_mfma_f32_16x16x32_bf16 v[110:113], v[78:81], v[142:145], v[110:113]
	v_mfma_f32_16x16x32_bf16 v[106:109], v[98:101], v[130:133], v[106:109]
	v_mfma_f32_16x16x32_bf16 v[94:97], v[78:81], v[150:153], v[94:97]
	v_mfma_f32_16x16x32_bf16 v[90:93], v[98:101], v[146:149], v[90:93]
	v_mfma_f32_16x16x32_bf16 v[86:89], v[78:81], v[166:169], v[86:89]
	v_mfma_f32_16x16x32_bf16 v[82:85], v[98:101], v[154:157], v[82:85]
	v_mfma_f32_16x16x32_bf16 v[78:81], v[78:81], v[174:177], v[26:29]
	v_mfma_f32_16x16x32_bf16 v[26:29], v[98:101], v[170:173], v[30:33]
	v_mfma_f32_16x16x32_bf16 v[106:109], v[102:105], v[142:145], v[106:109]
	v_mfma_f32_16x16x32_bf16 v[90:93], v[102:105], v[150:153], v[90:93]
	v_mfma_f32_16x16x32_bf16 v[82:85], v[102:105], v[166:169], v[82:85]
	v_mfma_f32_16x16x32_bf16 v[74:77], v[102:105], v[174:177], v[26:29]
	s_setprio 0
	s_barrier
	s_add_u32 s4, s4, 0x100080
	s_addc_u32 s5, s5, 0
	s_add_i32 s14, s16, s21
	v_lshl_add_u64 v[26:27], s[4:5], 0, v[0:1]
	s_mov_b32 m0, s14
	s_nop 0
	global_load_lds_dwordx4 v[26:27], off
	v_lshl_add_u64 v[26:27], s[4:5], 0, v[188:189]
	s_add_i32 m0, s14, 0x2000
	s_nop 0
	global_load_lds_dwordx4 v[26:27], off
	s_waitcnt vmcnt(8)
	s_barrier
	s_setprio 1
	v_mfma_f32_16x16x32_bf16 v[26:29], v[184:187], v[130:133], v[38:41]
	v_mfma_f32_16x16x32_bf16 v[38:41], v[200:203], v[142:145], v[26:29]
	v_mfma_f32_16x16x32_bf16 v[26:29], v[204:207], v[130:133], v[34:37]
	v_mfma_f32_16x16x32_bf16 v[22:25], v[184:187], v[146:149], v[22:25]
	v_mfma_f32_16x16x32_bf16 v[18:21], v[204:207], v[146:149], v[18:21]
	v_mfma_f32_16x16x32_bf16 v[14:17], v[184:187], v[154:157], v[14:17]
	v_mfma_f32_16x16x32_bf16 v[10:13], v[204:207], v[154:157], v[10:13]
	v_mfma_f32_16x16x32_bf16 v[6:9], v[184:187], v[170:173], v[6:9]
	v_mfma_f32_16x16x32_bf16 v[2:5], v[204:207], v[170:173], v[2:5]
	v_mfma_f32_16x16x32_bf16 v[34:37], v[208:211], v[142:145], v[26:29]
	v_mfma_f32_16x16x32_bf16 v[22:25], v[200:203], v[150:153], v[22:25]
	v_mfma_f32_16x16x32_bf16 v[18:21], v[208:211], v[150:153], v[18:21]
	v_mfma_f32_16x16x32_bf16 v[14:17], v[200:203], v[166:169], v[14:17]
	v_mfma_f32_16x16x32_bf16 v[10:13], v[208:211], v[166:169], v[10:13]
	v_mfma_f32_16x16x32_bf16 v[6:9], v[200:203], v[174:177], v[6:9]
	v_mfma_f32_16x16x32_bf16 v[2:5], v[208:211], v[174:177], v[2:5]
	s_setprio 0
	s_add_i32 s57, s57, 2
	s_add_u32 s51, s51, 0x100
	s_addc_u32 s56, s56, 0
	s_add_u32 s8, s8, 0x208800
	s_addc_u32 s9, s9, 0
	s_cmp_gt_u32 s57, 61
	s_barrier
	s_cbranch_scc0 .LBB0_796
	v_lshl_or_b32 v200, s36, 8, v246
	v_ashrrev_i32_e32 v201, 31, v200
	v_lshl_add_u32 v224, s35, 8, v244
	v_lshlrev_b64 v[204:205], 1, v[200:201]
	v_ashrrev_i32_e32 v225, 31, v224
	v_ashrrev_i32_e32 v130, 4, v200
	v_lshl_add_u64 v[222:223], s[46:47], 0, v[204:205]
	v_lshlrev_b64 v[202:203], 14, v[224:225]
	v_lshl_add_u64 v[30:31], v[200:201], 2, s[10:11]
	v_mad_i64_i32 v[220:221], s[4:5], v130, s94, v[194:195]
	v_lshl_add_u64 v[130:131], v[222:223], 0, v[202:203]
	global_load_dwordx4 v[98:101], v[30:31], off offset:16
	global_load_dwordx4 v[102:105], v[30:31], off
	global_load_dwordx4 v[26:29], v[30:31], off offset:528
	s_nop 0
	global_load_dwordx4 v[30:33], v[30:31], off offset:512
	v_or_b32_e32 v226, 48, v224
	global_load_dwordx4 v[170:173], v[130:131], off
	v_lshlrev_b32_e32 v142, 4, v226
	v_ashrrev_i32_e32 v143, 31, v142
	v_lshlrev_b64 v[218:219], 1, v[142:143]
	v_lshl_add_u64 v[142:143], v[220:221], 0, v[218:219]
	global_load_dwordx4 v[142:145], v[142:143], off
	v_lshlrev_b32_e32 v130, 4, v224
	v_ashrrev_i32_e32 v131, 31, v130
	v_lshlrev_b64 v[206:207], 1, v[130:131]
	v_lshl_add_u64 v[130:131], v[220:221], 0, v[206:207]
	global_load_dwordx4 v[174:177], v[130:131], off
	v_or_b32_e32 v230, 16, v224
	v_ashrrev_i32_e32 v231, 31, v230
	v_lshlrev_b64 v[210:211], 14, v[230:231]
	v_lshl_add_u64 v[130:131], v[222:223], 0, v[210:211]
	global_load_dwordx4 v[154:157], v[130:131], off
	v_lshlrev_b32_e32 v130, 4, v230
	v_ashrrev_i32_e32 v131, 31, v130
	v_or_b32_e32 v228, 32, v224
	v_lshlrev_b64 v[208:209], 1, v[130:131]
	v_ashrrev_i32_e32 v229, 31, v228
	v_lshl_add_u64 v[130:131], v[220:221], 0, v[208:209]
	v_lshlrev_b64 v[214:215], 14, v[228:229]
	global_load_dwordx4 v[166:169], v[130:131], off
	v_lshl_add_u64 v[130:131], v[222:223], 0, v[214:215]
	global_load_dwordx4 v[146:149], v[130:131], off
	v_lshlrev_b32_e32 v130, 4, v228
	v_ashrrev_i32_e32 v131, 31, v130
	v_lshlrev_b64 v[212:213], 1, v[130:131]
	v_ashrrev_i32_e32 v227, 31, v226
	v_lshl_add_u64 v[130:131], v[220:221], 0, v[212:213]
	v_lshlrev_b64 v[216:217], 14, v[226:227]
	global_load_dwordx4 v[150:153], v[130:131], off
	v_lshl_add_u64 v[130:131], v[222:223], 0, v[216:217]
	global_load_dwordx4 v[130:133], v[130:131], off
	s_and_b64 vcc, exec, s[40:41]
	s_mov_b32 s35, s50
	s_mov_b32 s36, s48
	s_mov_b64 s[8:9], s[54:55]
	s_mov_b64 s[14:15], s[52:53]
	s_waitcnt vmcnt(0)
; __device__ __forceinline__ unsigned cvt_pk_bf16(float lo, float hi) { unsigned r; asm volatile("v_cvt_pk_bf16_f32 %0, %1, %2" : "=v"(r) : "v"(lo), "v"(hi)); return r; }
; __device__ __forceinline__ float bf_lo(unsigned w) { return __uint_as_float(w << 16); }
; __device__ __forceinline__ float bf_hi(unsigned w) { return __uint_as_float(w & 0xffff0000u); }
; __device__ __forceinline__ float fast_rcp(float x) { return __builtin_amdgcn_rcpf(x); }
; __device__ __forceinline__ float glu_gate_f(float g, float v, float z) {
;     const float ev = __builtin_amdgcn_exp2f(v * -1.44269504f), ez = __builtin_amdgcn_exp2f(z * -1.44269504f);
;     return g * z * fast_rcp((1.0f + ev) * (1.0f + ez));
; }
;     __device__ __forceinline__ void operator()(const f32x4 (&acc)[2][2][4][2], const Unit& u, int wr, int wc, int fr, int fq, const Pre&) const {
;     ...
;             for (int ai = 0; ai < 2; ++ai) { u32x4 zv[4], gv[4];
; #pragma unroll
;                 for (int m = 0; m < 4; ++m) { const int r = row0 + ai * HALF + m * 16; zv[m] = *(const u32x4*)(Z + (size_t)r * DE2 + c); gv[m] = *(const u32x4*)(Gm + (size_t)(c >> 4) * GSTR + r * 16 + (c & 15)); }
; #pragma unroll
;                 for (int m = 0; m < 4; ++m) { const int r = row0 + ai * HALF + m * 16;
;                     const u32x4 zw = zv[m], gw = gv[m];
;                     const f32x4 a0 = acc[ai][bj][m][0] + bs[bj][0], a1 = acc[ai][bj][m][1] + bs[bj][1];
;                     u32x4 w;
;                     w.x = cvt_pk_bf16(glu_gate_f(bf_lo(gw.x), a0[0], bf_lo(zw.x)), glu_gate_f(bf_hi(gw.x), a0[1], bf_hi(zw.x)));
;                     w.y = cvt_pk_bf16(glu_gate_f(bf_lo(gw.y), a0[2], bf_lo(zw.y)), glu_gate_f(bf_hi(gw.y), a0[3], bf_hi(zw.y)));
;                     w.z = cvt_pk_bf16(glu_gate_f(bf_lo(gw.z), a1[0], bf_lo(zw.z)), glu_gate_f(bf_hi(gw.z), a1[1], bf_hi(zw.z)));
;                     w.w = cvt_pk_bf16(glu_gate_f(bf_lo(gw.w), a1[2], bf_lo(zw.w)), glu_gate_f(bf_hi(gw.w), a1[3], bf_hi(zw.w)));
;                     *(u32x4*)(O + (size_t)r * DE + c) = w; } } }
	v_pk_add_f32 v[134:135], v[134:135], v[98:99]
	v_pk_add_f32 v[184:185], v[162:163], v[102:103]
	v_pk_add_f32 v[162:163], v[160:161], v[100:101]
	v_pk_add_f32 v[160:161], v[158:159], v[98:99]
	v_mul_f32_e32 v158, 0xbfb8aa3b, v184
	v_lshlrev_b32_e32 v186, 16, v170
	v_mul_f32_e32 v159, 0xbfb8aa3b, v186
	v_exp_f32_e32 v158, v158
	v_exp_f32_e32 v159, v159
	v_and_b32_e32 v170, 0xffff0000, v170
	v_pk_add_f32 v[164:165], v[164:165], v[104:105]
	v_mul_f32_e32 v160, 0xbfb8aa3b, v160
	v_pk_add_f32 v[158:159], v[158:159], 1.0 op_sel_hi:[1,0]
	v_mul_f32_e32 v164, 0xbfb8aa3b, v164
	v_mul_f32_e32 v158, v158, v159
	v_rcp_f32_e32 v158, v158
	v_lshlrev_b32_e32 v187, 16, v174
	v_mul_f32_e32 v184, v187, v186
	v_mul_f32_e32 v159, 0xbfb8aa3b, v170
	v_mul_f32_e32 v184, v184, v158
	v_mul_f32_e32 v158, 0xbfb8aa3b, v185
	v_exp_f32_e32 v158, v158
	v_exp_f32_e32 v159, v159
	v_and_b32_e32 v174, 0xffff0000, v174
	v_mul_f32_e32 v170, v174, v170
	v_mul_f32_e32 v162, 0xbfb8aa3b, v162
	v_pk_add_f32 v[158:159], v[158:159], 1.0 op_sel_hi:[1,0]
	v_pk_add_f32 v[138:139], v[138:139], v[102:103]
	v_mul_f32_e32 v158, v158, v159
	v_rcp_f32_e32 v158, v158
	v_lshlrev_b32_e32 v159, 16, v171
	v_and_b32_e32 v171, 0xffff0000, v171
	v_mul_f32_e32 v138, 0xbfb8aa3b, v138
	v_mul_f32_e32 v158, v170, v158
	v_cvt_pk_bf16_f32 v158, v184, v158
	v_exp_f32_e32 v184, v164
	v_mul_f32_e32 v164, 0xbfb8aa3b, v159
	v_exp_f32_e32 v185, v164
	v_lshlrev_b32_e32 v170, 16, v175
	v_mul_f32_e32 v159, v170, v159
	v_and_b32_e32 v170, 0xffff0000, v175
	v_pk_add_f32 v[184:185], v[184:185], 1.0 op_sel_hi:[1,0]
	v_mul_f32_e32 v170, v170, v171
	v_mul_f32_e32 v164, v184, v185
	v_rcp_f32_e32 v164, v164
	v_pk_add_f32 v[140:141], v[140:141], v[104:105]
	v_mul_f32_e32 v134, 0xbfb8aa3b, v134
	v_mul_f32_e32 v140, 0xbfb8aa3b, v140
	v_mul_f32_e32 v159, v159, v164
	v_mul_f32_e32 v164, 0xbfb8aa3b, v165
	v_mul_f32_e32 v165, 0xbfb8aa3b, v171
	v_exp_f32_e32 v164, v164
	v_exp_f32_e32 v165, v165
	v_lshlrev_b32_e32 v171, 16, v176
	v_pk_add_f32 v[136:137], v[136:137], v[100:101]
	v_pk_add_f32 v[126:127], v[126:127], v[102:103]
	v_pk_add_f32 v[164:165], v[164:165], 1.0 op_sel_hi:[1,0]
	v_mul_f32_e32 v126, 0xbfb8aa3b, v126
	v_mul_f32_e32 v164, v164, v165
	v_rcp_f32_e32 v164, v164
	v_pk_add_f32 v[128:129], v[128:129], v[104:105]
	v_pk_add_f32 v[122:123], v[122:123], v[98:99]
	v_mul_f32_e32 v128, 0xbfb8aa3b, v128
	v_mul_f32_e32 v164, v170, v164
	v_lshlrev_b32_e32 v170, 16, v172
	v_cvt_pk_bf16_f32 v159, v159, v164
	v_exp_f32_e32 v164, v160
	v_mul_f32_e32 v160, 0xbfb8aa3b, v170
	v_exp_f32_e32 v165, v160
	v_mul_f32_e32 v160, v171, v170
	v_and_b32_e32 v170, 0xffff0000, v172
	v_mul_f32_e32 v122, 0xbfb8aa3b, v122
	v_pk_add_f32 v[164:165], v[164:165], 1.0 op_sel_hi:[1,0]
	v_pk_add_f32 v[124:125], v[124:125], v[100:101]
	v_mul_f32_e32 v164, v164, v165
	v_rcp_f32_e32 v164, v164
	v_and_b32_e32 v165, 0xffff0000, v176
	v_mul_f32_e32 v165, v165, v170
	v_pk_add_f32 v[118:119], v[118:119], v[102:103]
	v_mul_f32_e32 v164, v160, v164
	v_mul_f32_e32 v160, 0xbfb8aa3b, v161
	v_mul_f32_e32 v161, 0xbfb8aa3b, v170
	v_exp_f32_e32 v160, v160
	v_exp_f32_e32 v161, v161
	v_lshlrev_b32_e32 v170, 16, v177
	v_mul_f32_e32 v118, 0xbfb8aa3b, v118
	v_pk_add_f32 v[120:121], v[120:121], v[104:105]
	v_pk_add_f32 v[160:161], v[160:161], 1.0 op_sel_hi:[1,0]
	v_mul_f32_e32 v120, 0xbfb8aa3b, v120
	v_mul_f32_e32 v160, v160, v161
	v_rcp_f32_e32 v160, v160
	v_lshlrev_b32_e32 v161, 16, v173
	v_pk_add_f32 v[114:115], v[114:115], v[98:99]
	v_pk_add_f32 v[116:117], v[116:117], v[100:101]
	v_mul_f32_e32 v160, v165, v160
	v_cvt_pk_bf16_f32 v160, v164, v160
	v_exp_f32_e32 v164, v162
	v_mul_f32_e32 v162, 0xbfb8aa3b, v161
	v_exp_f32_e32 v165, v162
	v_mul_f32_e32 v161, v170, v161
	v_mul_f32_e32 v114, 0xbfb8aa3b, v114
	v_add_u32_e32 v176, 0x80, v224
	v_pk_add_f32 v[164:165], v[164:165], 1.0 op_sel_hi:[1,0]
	v_add_u32_e32 v170, 0xb0, v224
	v_mul_f32_e32 v162, v164, v165
	v_rcp_f32_e32 v162, v162
	v_and_b32_e32 v165, 0xffff0000, v173
	v_and_b32_e32 v164, 0xffff0000, v177
	v_mul_f32_e32 v164, v164, v165
	v_mul_f32_e32 v161, v161, v162
	v_mul_f32_e32 v162, 0xbfb8aa3b, v163
	v_mul_f32_e32 v163, 0xbfb8aa3b, v165
	v_exp_f32_e32 v162, v162
	v_exp_f32_e32 v163, v163
	v_ashrrev_i32_e32 v177, 31, v176
	v_pk_add_f32 v[110:111], v[110:111], v[102:103]
	v_add_u32_e32 v174, 0x90, v224
	v_pk_add_f32 v[162:163], v[162:163], 1.0 op_sel_hi:[1,0]
	v_mul_f32_e32 v110, 0xbfb8aa3b, v110
	v_mul_f32_e32 v162, v162, v163
	v_rcp_f32_e32 v162, v162
	v_exp_f32_e32 v184, v110
	v_ashrrev_i32_e32 v175, 31, v174
	v_add_u32_e32 v172, 0xa0, v224
	v_mul_f32_e32 v162, v164, v162
	v_cvt_pk_bf16_f32 v161, v161, v162
	v_lshlrev_b64 v[162:163], 13, v[224:225]
	v_lshl_add_u64 v[162:163], s[44:45], 0, v[162:163]
	v_lshl_add_u64 v[162:163], v[162:163], 0, v[204:205]
	global_store_dwordx4 v[162:163], v[158:161], off
	v_ashrrev_i32_e32 v173, 31, v172
	v_ashrrev_i32_e32 v171, 31, v170
	v_lshlrev_b32_e32 v160, 16, v154
	v_exp_f32_e32 v158, v138
	v_mul_f32_e32 v138, 0xbfb8aa3b, v160
	v_exp_f32_e32 v159, v138
	v_lshlrev_b32_e32 v161, 16, v166
	v_mul_f32_e32 v138, v161, v160
	v_and_b32_e32 v154, 0xffff0000, v154
	v_pk_add_f32 v[158:159], v[158:159], 1.0 op_sel_hi:[1,0]
	v_lshlrev_b64 v[160:161], 14, v[172:173]
	v_mul_f32_e32 v158, v158, v159
	v_rcp_f32_e32 v158, v158
	v_and_b32_e32 v159, 0xffff0000, v166
	v_pk_add_f32 v[112:113], v[112:113], v[104:105]
	v_pk_add_f32 v[106:107], v[106:107], v[98:99]
	v_mul_f32_e32 v158, v138, v158
	v_mul_f32_e32 v138, 0xbfb8aa3b, v139
	v_mul_f32_e32 v139, 0xbfb8aa3b, v154
	v_exp_f32_e32 v138, v138
	v_exp_f32_e32 v139, v139
	v_mul_f32_e32 v154, v159, v154
	v_mul_f32_e32 v112, 0xbfb8aa3b, v112
; __device__ __forceinline__ unsigned cvt_pk_bf16(float lo, float hi) { unsigned r; asm volatile("v_cvt_pk_bf16_f32 %0, %1, %2" : "=v"(r) : "v"(lo), "v"(hi)); return r; }
; __device__ __forceinline__ float bf_lo(unsigned w) { return __uint_as_float(w << 16); }
; __device__ __forceinline__ float bf_hi(unsigned w) { return __uint_as_float(w & 0xffff0000u); }
; __device__ __forceinline__ float fast_rcp(float x) { return __builtin_amdgcn_rcpf(x); }
; __device__ __forceinline__ float glu_gate_f(float g, float v, float z) {
;     const float ev = __builtin_amdgcn_exp2f(v * -1.44269504f), ez = __builtin_amdgcn_exp2f(z * -1.44269504f);
;     return g * z * fast_rcp((1.0f + ev) * (1.0f + ez));
; }
;     __device__ __forceinline__ void operator()(const f32x4 (&acc)[2][2][4][2], const Unit& u, int wr, int wc, int fr, int fq, const Pre&) const {
;     ...
;             for (int ai = 0; ai < 2; ++ai) { u32x4 zv[4], gv[4];
; #pragma unroll
;                 for (int m = 0; m < 4; ++m) { const int r = row0 + ai * HALF + m * 16; zv[m] = *(const u32x4*)(Z + (size_t)r * DE2 + c); gv[m] = *(const u32x4*)(Gm + (size_t)(c >> 4) * GSTR + r * 16 + (c & 15)); }
; #pragma unroll
;                 for (int m = 0; m < 4; ++m) { const int r = row0 + ai * HALF + m * 16;
;                     const u32x4 zw = zv[m], gw = gv[m];
;                     const f32x4 a0 = acc[ai][bj][m][0] + bs[bj][0], a1 = acc[ai][bj][m][1] + bs[bj][1];
;                     u32x4 w;
;                     w.x = cvt_pk_bf16(glu_gate_f(bf_lo(gw.x), a0[0], bf_lo(zw.x)), glu_gate_f(bf_hi(gw.x), a0[1], bf_hi(zw.x)));
;                     w.y = cvt_pk_bf16(glu_gate_f(bf_lo(gw.y), a0[2], bf_lo(zw.y)), glu_gate_f(bf_hi(gw.y), a0[3], bf_hi(zw.y)));
;                     w.z = cvt_pk_bf16(glu_gate_f(bf_lo(gw.z), a1[0], bf_lo(zw.z)), glu_gate_f(bf_hi(gw.z), a1[1], bf_hi(zw.z)));
;                     w.w = cvt_pk_bf16(glu_gate_f(bf_lo(gw.w), a1[2], bf_lo(zw.w)), glu_gate_f(bf_hi(gw.w), a1[3], bf_hi(zw.w)));
;                     *(u32x4*)(O + (size_t)r * DE + c) = w; } } }
	v_mul_f32_e32 v106, 0xbfb8aa3b, v106
	v_pk_add_f32 v[138:139], v[138:139], 1.0 op_sel_hi:[1,0]
	v_pk_add_f32 v[108:109], v[108:109], v[100:101]
	v_mul_f32_e32 v138, v138, v139
	v_rcp_f32_e32 v138, v138
	v_lshlrev_b32_e32 v139, 16, v155
	v_and_b32_e32 v155, 0xffff0000, v155
	v_pk_add_f32 v[94:95], v[94:95], v[102:103]
	v_mul_f32_e32 v138, v154, v138
	v_cvt_pk_bf16_f32 v138, v158, v138
	v_exp_f32_e32 v158, v140
	v_mul_f32_e32 v140, 0xbfb8aa3b, v139
	v_exp_f32_e32 v159, v140
	v_lshlrev_b32_e32 v154, 16, v167
	v_mul_f32_e32 v139, v154, v139
	v_and_b32_e32 v154, 0xffff0000, v167
	v_pk_add_f32 v[158:159], v[158:159], 1.0 op_sel_hi:[1,0]
	v_mul_f32_e32 v154, v154, v155
	v_mul_f32_e32 v140, v158, v159
	v_rcp_f32_e32 v140, v140
	v_lshlrev_b64 v[166:167], 14, v[170:171]
	v_mul_f32_e32 v94, 0xbfb8aa3b, v94
	v_pk_add_f32 v[96:97], v[96:97], v[104:105]
	v_mul_f32_e32 v139, v139, v140
	v_mul_f32_e32 v140, 0xbfb8aa3b, v141
	v_mul_f32_e32 v141, 0xbfb8aa3b, v155
	v_exp_f32_e32 v140, v140
	v_exp_f32_e32 v141, v141
	v_lshlrev_b32_e32 v155, 16, v168
	v_mul_f32_e32 v96, 0xbfb8aa3b, v96
	v_pk_add_f32 v[90:91], v[90:91], v[98:99]
	v_pk_add_f32 v[140:141], v[140:141], 1.0 op_sel_hi:[1,0]
	v_mul_f32_e32 v90, 0xbfb8aa3b, v90
	v_mul_f32_e32 v140, v140, v141
	v_rcp_f32_e32 v140, v140
	v_pk_add_f32 v[92:93], v[92:93], v[100:101]
	v_pk_add_f32 v[86:87], v[86:87], v[102:103]
	v_pk_add_f32 v[88:89], v[88:89], v[104:105]
	v_mul_f32_e32 v140, v154, v140
	v_lshlrev_b32_e32 v154, 16, v156
	v_cvt_pk_bf16_f32 v139, v139, v140
	v_exp_f32_e32 v140, v134
	v_mul_f32_e32 v134, 0xbfb8aa3b, v154
	v_exp_f32_e32 v141, v134
	v_mul_f32_e32 v134, v155, v154
	v_and_b32_e32 v154, 0xffff0000, v156
	v_mul_f32_e32 v86, 0xbfb8aa3b, v86
	v_pk_add_f32 v[140:141], v[140:141], 1.0 op_sel_hi:[1,0]
	v_mul_f32_e32 v88, 0xbfb8aa3b, v88
	v_mul_f32_e32 v140, v140, v141
	v_rcp_f32_e32 v140, v140
	v_and_b32_e32 v141, 0xffff0000, v168
	v_mul_f32_e32 v141, v141, v154
	v_pk_add_f32 v[82:83], v[82:83], v[98:99]
	v_mul_f32_e32 v140, v134, v140
	v_mul_f32_e32 v134, 0xbfb8aa3b, v135
	v_mul_f32_e32 v135, 0xbfb8aa3b, v154
	v_exp_f32_e32 v134, v134
	v_exp_f32_e32 v135, v135
	v_lshlrev_b32_e32 v154, 16, v169
	v_mul_f32_e32 v82, 0xbfb8aa3b, v82
	v_pk_add_f32 v[84:85], v[84:85], v[100:101]
	v_pk_add_f32 v[134:135], v[134:135], 1.0 op_sel_hi:[1,0]
	v_pk_add_f32 v[78:79], v[78:79], v[102:103]
	v_mul_f32_e32 v134, v134, v135
	v_rcp_f32_e32 v134, v134
	v_mul_f32_e32 v78, 0xbfb8aa3b, v78
	v_pk_add_f32 v[80:81], v[80:81], v[104:105]
	v_pk_add_f32 v[74:75], v[74:75], v[98:99]
	v_mul_f32_e32 v134, v141, v134
	v_lshlrev_b32_e32 v141, 16, v157
	v_cvt_pk_bf16_f32 v140, v140, v134
	v_mul_f32_e32 v134, 0xbfb8aa3b, v136
	v_mul_f32_e32 v135, 0xbfb8aa3b, v141
	v_exp_f32_e32 v134, v134
	v_exp_f32_e32 v135, v135
	v_mul_f32_e32 v136, v154, v141
	v_and_b32_e32 v154, 0xffff0000, v157
	v_and_b32_e32 v141, 0xffff0000, v169
	v_pk_add_f32 v[134:135], v[134:135], 1.0 op_sel_hi:[1,0]
	v_lshlrev_b64 v[156:157], 14, v[174:175]
	v_mul_f32_e32 v134, v134, v135
	v_rcp_f32_e32 v134, v134
	v_mul_f32_e32 v135, 0xbfb8aa3b, v154
	v_exp_f32_e32 v135, v135
	v_mul_f32_e32 v80, 0xbfb8aa3b, v80
	v_mul_f32_e32 v136, v136, v134
	v_mul_f32_e32 v134, 0xbfb8aa3b, v137
	v_exp_f32_e32 v134, v134
	v_mul_f32_e32 v137, v141, v154
	v_mul_f32_e32 v74, 0xbfb8aa3b, v74
	v_pk_add_f32 v[76:77], v[76:77], v[100:101]
	v_pk_add_f32 v[134:135], v[134:135], 1.0 op_sel_hi:[1,0]
	v_pk_add_f32 v[70:71], v[70:71], v[30:31]
	v_mul_f32_e32 v134, v134, v135
	v_rcp_f32_e32 v134, v134
	v_mul_f32_e32 v70, 0xbfb8aa3b, v70
	v_pk_add_f32 v[72:73], v[72:73], v[32:33]
	v_pk_add_f32 v[66:67], v[66:67], v[26:27]
	v_mul_f32_e32 v134, v137, v134
	v_cvt_pk_bf16_f32 v141, v136, v134
	v_lshlrev_b64 v[134:135], 13, v[230:231]
	v_lshl_add_u64 v[134:135], s[44:45], 0, v[134:135]
	v_lshlrev_b32_e32 v136, 16, v146
	v_lshl_add_u64 v[154:155], v[134:135], 0, v[204:205]
	v_exp_f32_e32 v134, v126
	v_mul_f32_e32 v126, 0xbfb8aa3b, v136
	v_exp_f32_e32 v135, v126
	v_lshlrev_b32_e32 v137, 16, v150
	v_mul_f32_e32 v126, v137, v136
	v_and_b32_e32 v136, 0xffff0000, v146
	v_pk_add_f32 v[134:135], v[134:135], 1.0 op_sel_hi:[1,0]
	global_store_dwordx4 v[154:155], v[138:141], off
	v_mul_f32_e32 v134, v134, v135
	v_rcp_f32_e32 v134, v134
	v_and_b32_e32 v135, 0xffff0000, v150
	v_mul_f32_e32 v135, v135, v136
	v_mul_f32_e32 v72, 0xbfb8aa3b, v72
	v_mul_f32_e32 v134, v126, v134
	v_mul_f32_e32 v126, 0xbfb8aa3b, v127
	v_mul_f32_e32 v127, 0xbfb8aa3b, v136
	v_exp_f32_e32 v126, v126
	v_exp_f32_e32 v127, v127
	v_lshlrev_b32_e32 v136, 16, v151
	v_mul_f32_e32 v66, 0xbfb8aa3b, v66
	v_pk_add_f32 v[68:69], v[68:69], v[28:29]
	v_pk_add_f32 v[126:127], v[126:127], 1.0 op_sel_hi:[1,0]
	v_pk_add_f32 v[62:63], v[62:63], v[30:31]
	v_mul_f32_e32 v126, v126, v127
	v_rcp_f32_e32 v126, v126
	v_lshlrev_b32_e32 v127, 16, v147
	v_mul_f32_e32 v62, 0xbfb8aa3b, v62
	v_pk_add_f32 v[64:65], v[64:65], v[32:33]
	v_mul_f32_e32 v126, v135, v126
	v_cvt_pk_bf16_f32 v126, v134, v126
	v_exp_f32_e32 v134, v128
	v_mul_f32_e32 v128, 0xbfb8aa3b, v127
	v_exp_f32_e32 v135, v128
	v_mul_f32_e32 v127, v136, v127
	v_mul_f32_e32 v64, 0xbfb8aa3b, v64
	v_pk_add_f32 v[58:59], v[58:59], v[26:27]
	v_pk_add_f32 v[134:135], v[134:135], 1.0 op_sel_hi:[1,0]
	v_mul_f32_e32 v58, 0xbfb8aa3b, v58
	v_mul_f32_e32 v128, v134, v135
	v_rcp_f32_e32 v128, v128
	v_and_b32_e32 v135, 0xffff0000, v147
	v_and_b32_e32 v134, 0xffff0000, v151
	v_mul_f32_e32 v134, v134, v135
	v_mul_f32_e32 v127, v127, v128
	v_mul_f32_e32 v128, 0xbfb8aa3b, v129
	v_mul_f32_e32 v129, 0xbfb8aa3b, v135
	v_exp_f32_e32 v128, v128
	v_exp_f32_e32 v129, v129
	v_lshlrev_b32_e32 v135, 16, v152
	v_lshlrev_b64 v[150:151], 14, v[176:177]
; __device__ __forceinline__ unsigned cvt_pk_bf16(float lo, float hi) { unsigned r; asm volatile("v_cvt_pk_bf16_f32 %0, %1, %2" : "=v"(r) : "v"(lo), "v"(hi)); return r; }
; __device__ __forceinline__ float bf_lo(unsigned w) { return __uint_as_float(w << 16); }
; __device__ __forceinline__ float bf_hi(unsigned w) { return __uint_as_float(w & 0xffff0000u); }
; __device__ __forceinline__ float fast_rcp(float x) { return __builtin_amdgcn_rcpf(x); }
; __device__ __forceinline__ float glu_gate_f(float g, float v, float z) {
;     const float ev = __builtin_amdgcn_exp2f(v * -1.44269504f), ez = __builtin_amdgcn_exp2f(z * -1.44269504f);
;     return g * z * fast_rcp((1.0f + ev) * (1.0f + ez));
; }
;     __device__ __forceinline__ void operator()(const f32x4 (&acc)[2][2][4][2], const Unit& u, int wr, int wc, int fr, int fq, const Pre&) const {
;     ...
;             for (int ai = 0; ai < 2; ++ai) { u32x4 zv[4], gv[4];
; #pragma unroll
;                 for (int m = 0; m < 4; ++m) { const int r = row0 + ai * HALF + m * 16; zv[m] = *(const u32x4*)(Z + (size_t)r * DE2 + c); gv[m] = *(const u32x4*)(Gm + (size_t)(c >> 4) * GSTR + r * 16 + (c & 15)); }
; #pragma unroll
;                 for (int m = 0; m < 4; ++m) { const int r = row0 + ai * HALF + m * 16;
;                     const u32x4 zw = zv[m], gw = gv[m];
;                     const f32x4 a0 = acc[ai][bj][m][0] + bs[bj][0], a1 = acc[ai][bj][m][1] + bs[bj][1];
;                     u32x4 w;
;                     w.x = cvt_pk_bf16(glu_gate_f(bf_lo(gw.x), a0[0], bf_lo(zw.x)), glu_gate_f(bf_hi(gw.x), a0[1], bf_hi(zw.x)));
;                     w.y = cvt_pk_bf16(glu_gate_f(bf_lo(gw.y), a0[2], bf_lo(zw.y)), glu_gate_f(bf_hi(gw.y), a0[3], bf_hi(zw.y)));
;                     w.z = cvt_pk_bf16(glu_gate_f(bf_lo(gw.z), a1[0], bf_lo(zw.z)), glu_gate_f(bf_hi(gw.z), a1[1], bf_hi(zw.z)));
;                     w.w = cvt_pk_bf16(glu_gate_f(bf_lo(gw.w), a1[2], bf_lo(zw.w)), glu_gate_f(bf_hi(gw.w), a1[3], bf_hi(zw.w)));
;                     *(u32x4*)(O + (size_t)r * DE + c) = w; } } }
	v_pk_add_f32 v[60:61], v[60:61], v[28:29]
	v_pk_add_f32 v[128:129], v[128:129], 1.0 op_sel_hi:[1,0]
	v_pk_add_f32 v[54:55], v[54:55], v[30:31]
	v_mul_f32_e32 v128, v128, v129
	v_rcp_f32_e32 v128, v128
	v_mul_f32_e32 v54, 0xbfb8aa3b, v54
	v_pk_add_f32 v[56:57], v[56:57], v[32:33]
	v_pk_add_f32 v[50:51], v[50:51], v[26:27]
	v_mul_f32_e32 v128, v134, v128
	v_lshlrev_b32_e32 v134, 16, v148
	v_cvt_pk_bf16_f32 v127, v127, v128
	v_exp_f32_e32 v128, v122
	v_mul_f32_e32 v122, 0xbfb8aa3b, v134
	v_exp_f32_e32 v129, v122
	v_mul_f32_e32 v122, v135, v134
	v_and_b32_e32 v134, 0xffff0000, v148
	v_mul_f32_e32 v56, 0xbfb8aa3b, v56
	v_pk_add_f32 v[128:129], v[128:129], 1.0 op_sel_hi:[1,0]
	v_mul_f32_e32 v50, 0xbfb8aa3b, v50
	v_mul_f32_e32 v128, v128, v129
	v_rcp_f32_e32 v128, v128
	v_and_b32_e32 v129, 0xffff0000, v152
	v_mul_f32_e32 v129, v129, v134
	v_pk_add_f32 v[52:53], v[52:53], v[28:29]
	v_mul_f32_e32 v128, v122, v128
	v_mul_f32_e32 v122, 0xbfb8aa3b, v123
	v_mul_f32_e32 v123, 0xbfb8aa3b, v134
	v_exp_f32_e32 v122, v122
	v_exp_f32_e32 v123, v123
	v_lshlrev_b32_e32 v134, 16, v153
	v_pk_add_f32 v[46:47], v[46:47], v[30:31]
	v_pk_add_f32 v[48:49], v[48:49], v[32:33]
	v_pk_add_f32 v[122:123], v[122:123], 1.0 op_sel_hi:[1,0]
	v_mul_f32_e32 v46, 0xbfb8aa3b, v46
	v_mul_f32_e32 v122, v122, v123
	v_rcp_f32_e32 v122, v122
	v_mul_f32_e32 v48, 0xbfb8aa3b, v48
	v_pk_add_f32 v[42:43], v[42:43], v[26:27]
	v_pk_add_f32 v[44:45], v[44:45], v[28:29]
	v_mul_f32_e32 v122, v129, v122
	v_lshlrev_b32_e32 v129, 16, v149
	v_cvt_pk_bf16_f32 v128, v128, v122
	v_mul_f32_e32 v122, 0xbfb8aa3b, v124
	v_mul_f32_e32 v123, 0xbfb8aa3b, v129
	v_exp_f32_e32 v122, v122
	v_exp_f32_e32 v123, v123
	v_mul_f32_e32 v124, v134, v129
	v_and_b32_e32 v134, 0xffff0000, v149
	v_and_b32_e32 v129, 0xffff0000, v153
	v_pk_add_f32 v[122:123], v[122:123], 1.0 op_sel_hi:[1,0]
	v_mul_f32_e32 v42, 0xbfb8aa3b, v42
	v_mul_f32_e32 v122, v122, v123
	v_rcp_f32_e32 v122, v122
	v_mul_f32_e32 v123, 0xbfb8aa3b, v134
	v_exp_f32_e32 v123, v123
	v_pk_add_f32 v[38:39], v[38:39], v[30:31]
	v_mul_f32_e32 v124, v124, v122
	v_mul_f32_e32 v122, 0xbfb8aa3b, v125
	v_exp_f32_e32 v122, v122
	v_mul_f32_e32 v125, v129, v134
	v_mul_f32_e32 v38, 0xbfb8aa3b, v38
	v_pk_add_f32 v[40:41], v[40:41], v[32:33]
	v_pk_add_f32 v[122:123], v[122:123], 1.0 op_sel_hi:[1,0]
	v_mul_f32_e32 v40, 0xbfb8aa3b, v40
	v_mul_f32_e32 v122, v122, v123
	v_rcp_f32_e32 v122, v122
	v_pk_add_f32 v[34:35], v[34:35], v[26:27]
	v_pk_add_f32 v[36:37], v[36:37], v[28:29]
	v_mul_f32_e32 v34, 0xbfb8aa3b, v34
	v_mul_f32_e32 v122, v125, v122
	v_cvt_pk_bf16_f32 v129, v124, v122
	v_lshlrev_b64 v[122:123], 13, v[228:229]
	v_lshl_add_u64 v[122:123], s[44:45], 0, v[122:123]
	v_lshlrev_b32_e32 v124, 16, v130
	v_lshl_add_u64 v[146:147], v[122:123], 0, v[204:205]
	v_exp_f32_e32 v122, v118
	v_mul_f32_e32 v118, 0xbfb8aa3b, v124
	v_exp_f32_e32 v123, v118
	v_lshlrev_b32_e32 v125, 16, v142
	v_mul_f32_e32 v118, v125, v124
	v_and_b32_e32 v124, 0xffff0000, v130
	v_pk_add_f32 v[122:123], v[122:123], 1.0 op_sel_hi:[1,0]
	global_store_dwordx4 v[146:147], v[126:129], off
	v_mul_f32_e32 v122, v122, v123
	v_rcp_f32_e32 v122, v122
	v_and_b32_e32 v123, 0xffff0000, v142
	v_mul_f32_e32 v123, v123, v124
	v_pk_add_f32 v[22:23], v[22:23], v[30:31]
	v_mul_f32_e32 v122, v118, v122
	v_mul_f32_e32 v118, 0xbfb8aa3b, v119
	v_mul_f32_e32 v119, 0xbfb8aa3b, v124
	v_exp_f32_e32 v118, v118
	v_exp_f32_e32 v119, v119
	v_lshlrev_b32_e32 v124, 16, v143
	v_mul_f32_e32 v22, 0xbfb8aa3b, v22
	v_pk_add_f32 v[24:25], v[24:25], v[32:33]
	v_pk_add_f32 v[118:119], v[118:119], 1.0 op_sel_hi:[1,0]
	v_mul_f32_e32 v24, 0xbfb8aa3b, v24
	v_mul_f32_e32 v118, v118, v119
	v_rcp_f32_e32 v118, v118
	v_lshlrev_b32_e32 v119, 16, v131
	v_pk_add_f32 v[18:19], v[18:19], v[26:27]
	v_pk_add_f32 v[20:21], v[20:21], v[28:29]
	v_mul_f32_e32 v118, v123, v118
	v_cvt_pk_bf16_f32 v118, v122, v118
	v_exp_f32_e32 v122, v120
	v_mul_f32_e32 v120, 0xbfb8aa3b, v119
	v_exp_f32_e32 v123, v120
	v_mul_f32_e32 v119, v124, v119
	v_mul_f32_e32 v18, 0xbfb8aa3b, v18
	v_pk_add_f32 v[14:15], v[14:15], v[30:31]
	v_pk_add_f32 v[122:123], v[122:123], 1.0 op_sel_hi:[1,0]
	v_mul_f32_e32 v14, 0xbfb8aa3b, v14
	v_mul_f32_e32 v120, v122, v123
	v_rcp_f32_e32 v120, v120
	v_and_b32_e32 v123, 0xffff0000, v131
	v_and_b32_e32 v122, 0xffff0000, v143
	v_mul_f32_e32 v122, v122, v123
	v_mul_f32_e32 v119, v119, v120
	v_mul_f32_e32 v120, 0xbfb8aa3b, v121
	v_mul_f32_e32 v121, 0xbfb8aa3b, v123
	v_exp_f32_e32 v120, v120
	v_exp_f32_e32 v121, v121
	v_lshlrev_b32_e32 v123, 16, v144
	v_pk_add_f32 v[16:17], v[16:17], v[32:33]
	v_pk_add_f32 v[10:11], v[10:11], v[26:27]
	v_pk_add_f32 v[120:121], v[120:121], 1.0 op_sel_hi:[1,0]
	v_mul_f32_e32 v16, 0xbfb8aa3b, v16
	v_mul_f32_e32 v120, v120, v121
	v_rcp_f32_e32 v120, v120
	v_mul_f32_e32 v10, 0xbfb8aa3b, v10
	v_pk_add_f32 v[12:13], v[12:13], v[28:29]
	v_pk_add_f32 v[6:7], v[6:7], v[30:31]
	v_mul_f32_e32 v120, v122, v120
	v_lshlrev_b32_e32 v122, 16, v132
	v_cvt_pk_bf16_f32 v119, v119, v120
	v_exp_f32_e32 v120, v114
	v_mul_f32_e32 v114, 0xbfb8aa3b, v122
	v_exp_f32_e32 v121, v114
	v_mul_f32_e32 v114, v123, v122
	v_and_b32_e32 v122, 0xffff0000, v132
	v_mul_f32_e32 v6, 0xbfb8aa3b, v6
	v_pk_add_f32 v[120:121], v[120:121], 1.0 op_sel_hi:[1,0]
	v_pk_add_f32 v[8:9], v[8:9], v[32:33]
	v_mul_f32_e32 v120, v120, v121
	v_rcp_f32_e32 v120, v120
	v_and_b32_e32 v121, 0xffff0000, v144
	v_mul_f32_e32 v121, v121, v122
	v_mul_f32_e32 v8, 0xbfb8aa3b, v8
	v_mul_f32_e32 v120, v114, v120
	v_mul_f32_e32 v114, 0xbfb8aa3b, v115
	v_mul_f32_e32 v115, 0xbfb8aa3b, v122
	v_exp_f32_e32 v114, v114
	v_exp_f32_e32 v115, v115
	v_lshlrev_b32_e32 v122, 16, v145
	v_pk_add_f32 v[2:3], v[2:3], v[26:27]
; __device__ __forceinline__ unsigned cvt_pk_bf16(float lo, float hi) { unsigned r; asm volatile("v_cvt_pk_bf16_f32 %0, %1, %2" : "=v"(r) : "v"(lo), "v"(hi)); return r; }
; __device__ __forceinline__ float bf_lo(unsigned w) { return __uint_as_float(w << 16); }
; __device__ __forceinline__ float bf_hi(unsigned w) { return __uint_as_float(w & 0xffff0000u); }
; __device__ __forceinline__ float fast_rcp(float x) { return __builtin_amdgcn_rcpf(x); }
; __device__ __forceinline__ float glu_gate_f(float g, float v, float z) {
;     const float ev = __builtin_amdgcn_exp2f(v * -1.44269504f), ez = __builtin_amdgcn_exp2f(z * -1.44269504f);
;     return g * z * fast_rcp((1.0f + ev) * (1.0f + ez));
; }
;     __device__ __forceinline__ void operator()(const f32x4 (&acc)[2][2][4][2], const Unit& u, int wr, int wc, int fr, int fq, const Pre&) const {
;     ...
;             for (int ai = 0; ai < 2; ++ai) { u32x4 zv[4], gv[4];
; #pragma unroll
;                 for (int m = 0; m < 4; ++m) { const int r = row0 + ai * HALF + m * 16; zv[m] = *(const u32x4*)(Z + (size_t)r * DE2 + c); gv[m] = *(const u32x4*)(Gm + (size_t)(c >> 4) * GSTR + r * 16 + (c & 15)); }
; #pragma unroll
;                 for (int m = 0; m < 4; ++m) { const int r = row0 + ai * HALF + m * 16;
;                     const u32x4 zw = zv[m], gw = gv[m];
;                     const f32x4 a0 = acc[ai][bj][m][0] + bs[bj][0], a1 = acc[ai][bj][m][1] + bs[bj][1];
;                     u32x4 w;
;                     w.x = cvt_pk_bf16(glu_gate_f(bf_lo(gw.x), a0[0], bf_lo(zw.x)), glu_gate_f(bf_hi(gw.x), a0[1], bf_hi(zw.x)));
;                     w.y = cvt_pk_bf16(glu_gate_f(bf_lo(gw.y), a0[2], bf_lo(zw.y)), glu_gate_f(bf_hi(gw.y), a0[3], bf_hi(zw.y)));
;                     w.z = cvt_pk_bf16(glu_gate_f(bf_lo(gw.z), a1[0], bf_lo(zw.z)), glu_gate_f(bf_hi(gw.z), a1[1], bf_hi(zw.z)));
;                     w.w = cvt_pk_bf16(glu_gate_f(bf_lo(gw.w), a1[2], bf_lo(zw.w)), glu_gate_f(bf_hi(gw.w), a1[3], bf_hi(zw.w)));
;                     *(u32x4*)(O + (size_t)r * DE + c) = w; } } }
	v_pk_add_f32 v[4:5], v[4:5], v[28:29]
	v_pk_add_f32 v[114:115], v[114:115], 1.0 op_sel_hi:[1,0]
	v_mul_f32_e32 v2, 0xbfb8aa3b, v2
	v_mul_f32_e32 v114, v114, v115
	v_rcp_f32_e32 v114, v114
	s_nop 0
	v_mul_f32_e32 v114, v121, v114
	v_lshlrev_b32_e32 v121, 16, v133
	v_cvt_pk_bf16_f32 v120, v120, v114
	v_mul_f32_e32 v114, 0xbfb8aa3b, v116
	v_mul_f32_e32 v115, 0xbfb8aa3b, v121
	v_exp_f32_e32 v114, v114
	v_exp_f32_e32 v115, v115
	v_mul_f32_e32 v116, v122, v121
	v_and_b32_e32 v122, 0xffff0000, v133
	v_and_b32_e32 v121, 0xffff0000, v145
	v_pk_add_f32 v[114:115], v[114:115], 1.0 op_sel_hi:[1,0]
	s_nop 0
	v_mul_f32_e32 v114, v114, v115
	v_rcp_f32_e32 v114, v114
	v_mul_f32_e32 v115, 0xbfb8aa3b, v122
	v_exp_f32_e32 v115, v115
	v_mul_f32_e32 v116, v116, v114
	v_mul_f32_e32 v114, 0xbfb8aa3b, v117
	v_exp_f32_e32 v114, v114
	v_mul_f32_e32 v117, v121, v122
	v_pk_add_f32 v[114:115], v[114:115], 1.0 op_sel_hi:[1,0]
	s_nop 0
	v_mul_f32_e32 v114, v114, v115
	v_rcp_f32_e32 v114, v114
	s_nop 0
	v_mul_f32_e32 v114, v117, v114
	v_cvt_pk_bf16_f32 v121, v116, v114
	v_lshlrev_b64 v[114:115], 13, v[226:227]
	v_lshl_add_u64 v[114:115], s[44:45], 0, v[114:115]
	v_lshl_add_u64 v[148:149], v[114:115], 0, v[204:205]
	global_store_dwordx4 v[148:149], v[118:121], off
	v_lshl_add_u64 v[114:115], v[222:223], 0, v[150:151]
	global_load_dwordx4 v[138:141], v[114:115], off
	v_lshlrev_b32_e32 v118, 4, v170
	v_ashrrev_i32_e32 v119, 31, v118
	v_lshlrev_b64 v[168:169], 1, v[118:119]
	v_lshl_add_u64 v[118:119], v[220:221], 0, v[168:169]
	global_load_dwordx4 v[118:121], v[118:119], off
	v_lshlrev_b32_e32 v114, 4, v176
	v_ashrrev_i32_e32 v115, 31, v114
	v_lshlrev_b64 v[152:153], 1, v[114:115]
	v_lshl_add_u64 v[114:115], v[220:221], 0, v[152:153]
	global_load_dwordx4 v[142:145], v[114:115], off
	v_lshl_add_u64 v[114:115], v[222:223], 0, v[156:157]
	global_load_dwordx4 v[130:133], v[114:115], off
	v_lshlrev_b32_e32 v114, 4, v174
	v_ashrrev_i32_e32 v115, 31, v114
	v_lshlrev_b64 v[158:159], 1, v[114:115]
	v_lshl_add_u64 v[114:115], v[220:221], 0, v[158:159]
	global_load_dwordx4 v[134:137], v[114:115], off
	v_lshl_add_u64 v[114:115], v[222:223], 0, v[160:161]
	global_load_dwordx4 v[122:125], v[114:115], off
	v_lshlrev_b32_e32 v114, 4, v172
	v_ashrrev_i32_e32 v115, 31, v114
	v_lshlrev_b64 v[164:165], 1, v[114:115]
	v_lshl_add_u64 v[114:115], v[220:221], 0, v[164:165]
	global_load_dwordx4 v[126:129], v[114:115], off
	v_lshl_add_u64 v[114:115], v[222:223], 0, v[166:167]
	global_load_dwordx4 v[114:117], v[114:115], off
	s_waitcnt vmcnt(0)
	v_lshlrev_b32_e32 v186, 16, v138
	v_mul_f32_e32 v110, 0xbfb8aa3b, v186
	v_exp_f32_e32 v185, v110
	v_and_b32_e32 v138, 0xffff0000, v138
	v_pk_add_f32 v[184:185], v[184:185], 1.0 op_sel_hi:[1,0]
	s_nop 0
	v_mul_f32_e32 v184, v184, v185
	v_rcp_f32_e32 v184, v184
	v_lshlrev_b32_e32 v187, 16, v142
	v_mul_f32_e32 v110, v187, v186
	v_mul_f32_e32 v184, v110, v184
	v_mul_f32_e32 v110, 0xbfb8aa3b, v111
	v_mul_f32_e32 v111, 0xbfb8aa3b, v138
	v_exp_f32_e32 v110, v110
	v_exp_f32_e32 v111, v111
	v_and_b32_e32 v142, 0xffff0000, v142
	v_mul_f32_e32 v138, v142, v138
	v_pk_add_f32 v[110:111], v[110:111], 1.0 op_sel_hi:[1,0]
	s_nop 0
	v_mul_f32_e32 v110, v110, v111
	v_rcp_f32_e32 v110, v110
	v_lshlrev_b32_e32 v111, 16, v139
	v_and_b32_e32 v139, 0xffff0000, v139
	v_mul_f32_e32 v110, v138, v110
	v_cvt_pk_bf16_f32 v110, v184, v110
	v_exp_f32_e32 v184, v112
	v_mul_f32_e32 v112, 0xbfb8aa3b, v111
	v_exp_f32_e32 v185, v112
	v_lshlrev_b32_e32 v138, 16, v143
	v_mul_f32_e32 v111, v138, v111
	v_and_b32_e32 v138, 0xffff0000, v143
	v_pk_add_f32 v[184:185], v[184:185], 1.0 op_sel_hi:[1,0]
	v_mul_f32_e32 v138, v138, v139
	v_mul_f32_e32 v112, v184, v185
	v_rcp_f32_e32 v112, v112
	s_nop 0
	v_mul_f32_e32 v111, v111, v112
	v_mul_f32_e32 v112, 0xbfb8aa3b, v113
	v_mul_f32_e32 v113, 0xbfb8aa3b, v139
	v_exp_f32_e32 v112, v112
	v_exp_f32_e32 v113, v113
	v_lshlrev_b32_e32 v139, 16, v144
	v_pk_add_f32 v[112:113], v[112:113], 1.0 op_sel_hi:[1,0]
	s_nop 0
	v_mul_f32_e32 v112, v112, v113
	v_rcp_f32_e32 v112, v112
	s_nop 0
	v_mul_f32_e32 v112, v138, v112
	v_lshlrev_b32_e32 v138, 16, v140
	v_cvt_pk_bf16_f32 v111, v111, v112
	v_exp_f32_e32 v112, v106
	v_mul_f32_e32 v106, 0xbfb8aa3b, v138
	v_exp_f32_e32 v113, v106
	v_mul_f32_e32 v106, v139, v138
	v_and_b32_e32 v138, 0xffff0000, v140
	v_pk_add_f32 v[112:113], v[112:113], 1.0 op_sel_hi:[1,0]
	s_nop 0
	v_mul_f32_e32 v112, v112, v113
	v_rcp_f32_e32 v112, v112
	v_and_b32_e32 v113, 0xffff0000, v144
	v_mul_f32_e32 v113, v113, v138
	v_mul_f32_e32 v112, v106, v112
	v_mul_f32_e32 v106, 0xbfb8aa3b, v107
	v_mul_f32_e32 v107, 0xbfb8aa3b, v138
	v_exp_f32_e32 v106, v106
	v_exp_f32_e32 v107, v107
	v_lshlrev_b32_e32 v138, 16, v145
	v_pk_add_f32 v[106:107], v[106:107], 1.0 op_sel_hi:[1,0]
	s_nop 0
	v_mul_f32_e32 v106, v106, v107
	v_rcp_f32_e32 v106, v106
	s_nop 0
	v_mul_f32_e32 v106, v113, v106
	v_lshlrev_b32_e32 v113, 16, v141
	v_cvt_pk_bf16_f32 v112, v112, v106
	v_mul_f32_e32 v106, 0xbfb8aa3b, v108
	v_mul_f32_e32 v107, 0xbfb8aa3b, v113
	v_exp_f32_e32 v106, v106
	v_exp_f32_e32 v107, v107
	v_mul_f32_e32 v108, v138, v113
	v_and_b32_e32 v138, 0xffff0000, v141
	v_and_b32_e32 v113, 0xffff0000, v145
	v_pk_add_f32 v[106:107], v[106:107], 1.0 op_sel_hi:[1,0]
	s_nop 0
	v_mul_f32_e32 v106, v106, v107
	v_rcp_f32_e32 v106, v106
	v_mul_f32_e32 v107, 0xbfb8aa3b, v138
	v_exp_f32_e32 v107, v107
	v_mul_f32_e32 v108, v108, v106
	v_mul_f32_e32 v106, 0xbfb8aa3b, v109
	v_exp_f32_e32 v106, v106
	v_mul_f32_e32 v109, v113, v138
	v_pk_add_f32 v[106:107], v[106:107], 1.0 op_sel_hi:[1,0]
	s_nop 0
	v_mul_f32_e32 v106, v106, v107
	v_rcp_f32_e32 v106, v106
	s_nop 0
	v_mul_f32_e32 v106, v109, v106
; __device__ __forceinline__ unsigned cvt_pk_bf16(float lo, float hi) { unsigned r; asm volatile("v_cvt_pk_bf16_f32 %0, %1, %2" : "=v"(r) : "v"(lo), "v"(hi)); return r; }
; __device__ __forceinline__ float bf_lo(unsigned w) { return __uint_as_float(w << 16); }
; __device__ __forceinline__ float bf_hi(unsigned w) { return __uint_as_float(w & 0xffff0000u); }
; __device__ __forceinline__ float fast_rcp(float x) { return __builtin_amdgcn_rcpf(x); }
; __device__ __forceinline__ float glu_gate_f(float g, float v, float z) {
;     const float ev = __builtin_amdgcn_exp2f(v * -1.44269504f), ez = __builtin_amdgcn_exp2f(z * -1.44269504f);
;     return g * z * fast_rcp((1.0f + ev) * (1.0f + ez));
; }
;     __device__ __forceinline__ void operator()(const f32x4 (&acc)[2][2][4][2], const Unit& u, int wr, int wc, int fr, int fq, const Pre&) const {
;     ...
;             for (int ai = 0; ai < 2; ++ai) { u32x4 zv[4], gv[4];
; #pragma unroll
;                 for (int m = 0; m < 4; ++m) { const int r = row0 + ai * HALF + m * 16; zv[m] = *(const u32x4*)(Z + (size_t)r * DE2 + c); gv[m] = *(const u32x4*)(Gm + (size_t)(c >> 4) * GSTR + r * 16 + (c & 15)); }
; #pragma unroll
;                 for (int m = 0; m < 4; ++m) { const int r = row0 + ai * HALF + m * 16;
;                     const u32x4 zw = zv[m], gw = gv[m];
;                     const f32x4 a0 = acc[ai][bj][m][0] + bs[bj][0], a1 = acc[ai][bj][m][1] + bs[bj][1];
;                     u32x4 w;
;                     w.x = cvt_pk_bf16(glu_gate_f(bf_lo(gw.x), a0[0], bf_lo(zw.x)), glu_gate_f(bf_hi(gw.x), a0[1], bf_hi(zw.x)));
;                     w.y = cvt_pk_bf16(glu_gate_f(bf_lo(gw.y), a0[2], bf_lo(zw.y)), glu_gate_f(bf_hi(gw.y), a0[3], bf_hi(zw.y)));
;                     w.z = cvt_pk_bf16(glu_gate_f(bf_lo(gw.z), a1[0], bf_lo(zw.z)), glu_gate_f(bf_hi(gw.z), a1[1], bf_hi(zw.z)));
;                     w.w = cvt_pk_bf16(glu_gate_f(bf_lo(gw.w), a1[2], bf_lo(zw.w)), glu_gate_f(bf_hi(gw.w), a1[3], bf_hi(zw.w)));
;                     *(u32x4*)(O + (size_t)r * DE + c) = w; } } }
	v_cvt_pk_bf16_f32 v113, v108, v106
	v_lshlrev_b64 v[106:107], 13, v[176:177]
	v_lshl_add_u64 v[106:107], s[44:45], 0, v[106:107]
	v_lshl_add_u64 v[106:107], v[106:107], 0, v[204:205]
	global_store_dwordx4 v[106:107], v[110:113], off
	v_exp_f32_e32 v108, v94
	s_nop 0
	v_lshlrev_b32_e32 v110, 16, v130
	v_mul_f32_e32 v94, 0xbfb8aa3b, v110
	v_exp_f32_e32 v109, v94
	v_lshlrev_b32_e32 v111, 16, v134
	v_mul_f32_e32 v94, v111, v110
	v_and_b32_e32 v110, 0xffff0000, v130
	v_pk_add_f32 v[108:109], v[108:109], 1.0 op_sel_hi:[1,0]
	s_nop 0
	v_mul_f32_e32 v108, v108, v109
	v_rcp_f32_e32 v108, v108
	v_and_b32_e32 v109, 0xffff0000, v134
	v_mul_f32_e32 v109, v109, v110
	v_mul_f32_e32 v108, v94, v108
	v_mul_f32_e32 v94, 0xbfb8aa3b, v95
	v_mul_f32_e32 v95, 0xbfb8aa3b, v110
	v_exp_f32_e32 v94, v94
	v_exp_f32_e32 v95, v95
	v_lshlrev_b32_e32 v110, 16, v135
	v_pk_add_f32 v[94:95], v[94:95], 1.0 op_sel_hi:[1,0]
	s_nop 0
	v_mul_f32_e32 v94, v94, v95
	v_rcp_f32_e32 v94, v94
	v_lshlrev_b32_e32 v95, 16, v131
	v_mul_f32_e32 v94, v109, v94
	v_cvt_pk_bf16_f32 v94, v108, v94
	v_exp_f32_e32 v108, v96
	v_mul_f32_e32 v96, 0xbfb8aa3b, v95
	v_exp_f32_e32 v109, v96
	v_mul_f32_e32 v95, v110, v95
	v_pk_add_f32 v[108:109], v[108:109], 1.0 op_sel_hi:[1,0]
	s_nop 0
	v_mul_f32_e32 v96, v108, v109
	v_rcp_f32_e32 v96, v96
	v_and_b32_e32 v109, 0xffff0000, v131
	v_and_b32_e32 v108, 0xffff0000, v135
	v_mul_f32_e32 v108, v108, v109
	v_mul_f32_e32 v95, v95, v96
	v_mul_f32_e32 v96, 0xbfb8aa3b, v97
	v_mul_f32_e32 v97, 0xbfb8aa3b, v109
	v_exp_f32_e32 v96, v96
	v_exp_f32_e32 v97, v97
	v_lshlrev_b32_e32 v109, 16, v136
	v_pk_add_f32 v[96:97], v[96:97], 1.0 op_sel_hi:[1,0]
	s_nop 0
	v_mul_f32_e32 v96, v96, v97
	v_rcp_f32_e32 v96, v96
	s_nop 0
	v_mul_f32_e32 v96, v108, v96
	v_lshlrev_b32_e32 v108, 16, v132
	v_cvt_pk_bf16_f32 v95, v95, v96
	v_exp_f32_e32 v96, v90
	v_mul_f32_e32 v90, 0xbfb8aa3b, v108
	v_exp_f32_e32 v97, v90
	v_mul_f32_e32 v90, v109, v108
	v_and_b32_e32 v108, 0xffff0000, v132
	v_pk_add_f32 v[96:97], v[96:97], 1.0 op_sel_hi:[1,0]
	s_nop 0
	v_mul_f32_e32 v96, v96, v97
	v_rcp_f32_e32 v96, v96
	v_and_b32_e32 v97, 0xffff0000, v136
	v_mul_f32_e32 v97, v97, v108
	v_mul_f32_e32 v96, v90, v96
	v_mul_f32_e32 v90, 0xbfb8aa3b, v91
	v_mul_f32_e32 v91, 0xbfb8aa3b, v108
	v_exp_f32_e32 v90, v90
	v_exp_f32_e32 v91, v91
	v_lshlrev_b32_e32 v108, 16, v137
	v_pk_add_f32 v[90:91], v[90:91], 1.0 op_sel_hi:[1,0]
	s_nop 0
	v_mul_f32_e32 v90, v90, v91
	v_rcp_f32_e32 v90, v90
	s_nop 0
	v_mul_f32_e32 v90, v97, v90
	v_lshlrev_b32_e32 v97, 16, v133
	v_cvt_pk_bf16_f32 v96, v96, v90
	v_mul_f32_e32 v90, 0xbfb8aa3b, v92
	v_mul_f32_e32 v91, 0xbfb8aa3b, v97
	v_exp_f32_e32 v90, v90
	v_exp_f32_e32 v91, v91
	v_mul_f32_e32 v92, v108, v97
	v_and_b32_e32 v108, 0xffff0000, v133
	v_and_b32_e32 v97, 0xffff0000, v137
	v_pk_add_f32 v[90:91], v[90:91], 1.0 op_sel_hi:[1,0]
	s_nop 0
	v_mul_f32_e32 v90, v90, v91
	v_rcp_f32_e32 v90, v90
	v_mul_f32_e32 v91, 0xbfb8aa3b, v108
	v_exp_f32_e32 v91, v91
	v_mul_f32_e32 v92, v92, v90
	v_mul_f32_e32 v90, 0xbfb8aa3b, v93
	v_exp_f32_e32 v90, v90
	v_mul_f32_e32 v93, v97, v108
	v_pk_add_f32 v[90:91], v[90:91], 1.0 op_sel_hi:[1,0]
	s_nop 0
	v_mul_f32_e32 v90, v90, v91
	v_rcp_f32_e32 v90, v90
	s_nop 0
	v_mul_f32_e32 v90, v93, v90
	v_cvt_pk_bf16_f32 v97, v92, v90
	v_lshlrev_b64 v[90:91], 13, v[174:175]
	v_lshl_add_u64 v[90:91], s[44:45], 0, v[90:91]
	v_lshlrev_b32_e32 v92, 16, v122
	v_lshl_add_u64 v[108:109], v[90:91], 0, v[204:205]
	v_exp_f32_e32 v90, v86
	v_mul_f32_e32 v86, 0xbfb8aa3b, v92
	v_exp_f32_e32 v91, v86
	v_lshlrev_b32_e32 v93, 16, v126
	v_mul_f32_e32 v86, v93, v92
	v_and_b32_e32 v92, 0xffff0000, v122
	v_pk_add_f32 v[90:91], v[90:91], 1.0 op_sel_hi:[1,0]
	global_store_dwordx4 v[108:109], v[94:97], off
	v_mul_f32_e32 v90, v90, v91
	v_rcp_f32_e32 v90, v90
	v_and_b32_e32 v91, 0xffff0000, v126
	v_mul_f32_e32 v91, v91, v92
	v_mul_f32_e32 v90, v86, v90
	v_mul_f32_e32 v86, 0xbfb8aa3b, v87
	v_mul_f32_e32 v87, 0xbfb8aa3b, v92
	v_exp_f32_e32 v86, v86
	v_exp_f32_e32 v87, v87
	v_lshlrev_b32_e32 v92, 16, v127
	v_pk_add_f32 v[86:87], v[86:87], 1.0 op_sel_hi:[1,0]
	s_nop 0
	v_mul_f32_e32 v86, v86, v87
	v_rcp_f32_e32 v86, v86
	v_lshlrev_b32_e32 v87, 16, v123
	v_mul_f32_e32 v86, v91, v86
	v_cvt_pk_bf16_f32 v86, v90, v86
	v_exp_f32_e32 v90, v88
	v_mul_f32_e32 v88, 0xbfb8aa3b, v87
	v_exp_f32_e32 v91, v88
	v_mul_f32_e32 v87, v92, v87
	v_pk_add_f32 v[90:91], v[90:91], 1.0 op_sel_hi:[1,0]
	s_nop 0
	v_mul_f32_e32 v88, v90, v91
	v_rcp_f32_e32 v88, v88
	v_and_b32_e32 v91, 0xffff0000, v123
	v_and_b32_e32 v90, 0xffff0000, v127
	v_mul_f32_e32 v90, v90, v91
	v_mul_f32_e32 v87, v87, v88
	v_mul_f32_e32 v88, 0xbfb8aa3b, v89
	v_mul_f32_e32 v89, 0xbfb8aa3b, v91
	v_exp_f32_e32 v88, v88
	v_exp_f32_e32 v89, v89
	v_lshlrev_b32_e32 v91, 16, v128
	v_pk_add_f32 v[88:89], v[88:89], 1.0 op_sel_hi:[1,0]
	s_nop 0
	v_mul_f32_e32 v88, v88, v89
	v_rcp_f32_e32 v88, v88
	s_nop 0
	v_mul_f32_e32 v88, v90, v88
	v_lshlrev_b32_e32 v90, 16, v124
	v_cvt_pk_bf16_f32 v87, v87, v88
	v_exp_f32_e32 v88, v82
	v_mul_f32_e32 v82, 0xbfb8aa3b, v90
	v_exp_f32_e32 v89, v82
	v_mul_f32_e32 v82, v91, v90
	v_and_b32_e32 v90, 0xffff0000, v124
	v_pk_add_f32 v[88:89], v[88:89], 1.0 op_sel_hi:[1,0]
	s_nop 0
	v_mul_f32_e32 v88, v88, v89
	v_rcp_f32_e32 v88, v88
	v_and_b32_e32 v89, 0xffff0000, v128
	v_mul_f32_e32 v89, v89, v90
	v_mul_f32_e32 v88, v82, v88
	v_mul_f32_e32 v82, 0xbfb8aa3b, v83
	v_mul_f32_e32 v83, 0xbfb8aa3b, v90
	v_exp_f32_e32 v82, v82
	v_exp_f32_e32 v83, v83
	v_lshlrev_b32_e32 v90, 16, v129
	v_pk_add_f32 v[82:83], v[82:83], 1.0 op_sel_hi:[1,0]
	s_nop 0
	v_mul_f32_e32 v82, v82, v83
	v_rcp_f32_e32 v82, v82
	s_nop 0
	v_mul_f32_e32 v82, v89, v82
; __device__ __forceinline__ unsigned cvt_pk_bf16(float lo, float hi) { unsigned r; asm volatile("v_cvt_pk_bf16_f32 %0, %1, %2" : "=v"(r) : "v"(lo), "v"(hi)); return r; }
; __device__ __forceinline__ float bf_lo(unsigned w) { return __uint_as_float(w << 16); }
; __device__ __forceinline__ float bf_hi(unsigned w) { return __uint_as_float(w & 0xffff0000u); }
; __device__ __forceinline__ float fast_rcp(float x) { return __builtin_amdgcn_rcpf(x); }
; __device__ __forceinline__ float glu_gate_f(float g, float v, float z) {
;     const float ev = __builtin_amdgcn_exp2f(v * -1.44269504f), ez = __builtin_amdgcn_exp2f(z * -1.44269504f);
;     return g * z * fast_rcp((1.0f + ev) * (1.0f + ez));
; }
;     __device__ __forceinline__ void operator()(const f32x4 (&acc)[2][2][4][2], const Unit& u, int wr, int wc, int fr, int fq, const Pre&) const {
;     ...
;             for (int ai = 0; ai < 2; ++ai) { u32x4 zv[4], gv[4];
; #pragma unroll
;                 for (int m = 0; m < 4; ++m) { const int r = row0 + ai * HALF + m * 16; zv[m] = *(const u32x4*)(Z + (size_t)r * DE2 + c); gv[m] = *(const u32x4*)(Gm + (size_t)(c >> 4) * GSTR + r * 16 + (c & 15)); }
; #pragma unroll
;                 for (int m = 0; m < 4; ++m) { const int r = row0 + ai * HALF + m * 16;
;                     const u32x4 zw = zv[m], gw = gv[m];
;                     const f32x4 a0 = acc[ai][bj][m][0] + bs[bj][0], a1 = acc[ai][bj][m][1] + bs[bj][1];
;                     u32x4 w;
;                     w.x = cvt_pk_bf16(glu_gate_f(bf_lo(gw.x), a0[0], bf_lo(zw.x)), glu_gate_f(bf_hi(gw.x), a0[1], bf_hi(zw.x)));
;                     w.y = cvt_pk_bf16(glu_gate_f(bf_lo(gw.y), a0[2], bf_lo(zw.y)), glu_gate_f(bf_hi(gw.y), a0[3], bf_hi(zw.y)));
;                     w.z = cvt_pk_bf16(glu_gate_f(bf_lo(gw.z), a1[0], bf_lo(zw.z)), glu_gate_f(bf_hi(gw.z), a1[1], bf_hi(zw.z)));
;                     w.w = cvt_pk_bf16(glu_gate_f(bf_lo(gw.w), a1[2], bf_lo(zw.w)), glu_gate_f(bf_hi(gw.w), a1[3], bf_hi(zw.w)));
;                     *(u32x4*)(O + (size_t)r * DE + c) = w; } } }
	v_lshlrev_b32_e32 v89, 16, v125
	v_cvt_pk_bf16_f32 v88, v88, v82
	v_mul_f32_e32 v82, 0xbfb8aa3b, v84
	v_mul_f32_e32 v83, 0xbfb8aa3b, v89
	v_exp_f32_e32 v82, v82
	v_exp_f32_e32 v83, v83
	v_mul_f32_e32 v84, v90, v89
	v_and_b32_e32 v90, 0xffff0000, v125
	v_and_b32_e32 v89, 0xffff0000, v129
	v_pk_add_f32 v[82:83], v[82:83], 1.0 op_sel_hi:[1,0]
	s_nop 0
	v_mul_f32_e32 v82, v82, v83
	v_rcp_f32_e32 v82, v82
	v_mul_f32_e32 v83, 0xbfb8aa3b, v90
	v_exp_f32_e32 v83, v83
	v_mul_f32_e32 v84, v84, v82
	v_mul_f32_e32 v82, 0xbfb8aa3b, v85
	v_exp_f32_e32 v82, v82
	v_mul_f32_e32 v85, v89, v90
	v_pk_add_f32 v[82:83], v[82:83], 1.0 op_sel_hi:[1,0]
	s_nop 0
	v_mul_f32_e32 v82, v82, v83
	v_rcp_f32_e32 v82, v82
	s_nop 0
	v_mul_f32_e32 v82, v85, v82
	v_cvt_pk_bf16_f32 v89, v84, v82
	v_lshlrev_b64 v[82:83], 13, v[172:173]
	v_lshl_add_u64 v[82:83], s[44:45], 0, v[82:83]
	v_lshlrev_b32_e32 v84, 16, v114
	v_lshl_add_u64 v[110:111], v[82:83], 0, v[204:205]
	v_exp_f32_e32 v82, v78
	v_mul_f32_e32 v78, 0xbfb8aa3b, v84
	v_exp_f32_e32 v83, v78
	v_lshlrev_b32_e32 v85, 16, v118
	v_mul_f32_e32 v78, v85, v84
	v_and_b32_e32 v84, 0xffff0000, v114
	v_pk_add_f32 v[82:83], v[82:83], 1.0 op_sel_hi:[1,0]
	global_store_dwordx4 v[110:111], v[86:89], off
	v_mul_f32_e32 v82, v82, v83
	v_rcp_f32_e32 v82, v82
	v_and_b32_e32 v83, 0xffff0000, v118
	v_mul_f32_e32 v83, v83, v84
	v_exp_f32_e32 v118, v70
	v_mul_f32_e32 v82, v78, v82
	v_mul_f32_e32 v78, 0xbfb8aa3b, v79
	v_mul_f32_e32 v79, 0xbfb8aa3b, v84
	v_exp_f32_e32 v78, v78
	v_exp_f32_e32 v79, v79
	v_lshlrev_b32_e32 v84, 16, v119
	v_pk_add_f32 v[78:79], v[78:79], 1.0 op_sel_hi:[1,0]
	s_nop 0
	v_mul_f32_e32 v78, v78, v79
	v_rcp_f32_e32 v78, v78
	v_lshlrev_b32_e32 v79, 16, v115
	v_mul_f32_e32 v78, v83, v78
	v_cvt_pk_bf16_f32 v78, v82, v78
	v_exp_f32_e32 v82, v80
	v_mul_f32_e32 v80, 0xbfb8aa3b, v79
	v_exp_f32_e32 v83, v80
	v_mul_f32_e32 v79, v84, v79
	v_pk_add_f32 v[82:83], v[82:83], 1.0 op_sel_hi:[1,0]
	s_nop 0
	v_mul_f32_e32 v80, v82, v83
	v_rcp_f32_e32 v80, v80
	v_and_b32_e32 v83, 0xffff0000, v115
	v_and_b32_e32 v82, 0xffff0000, v119
	v_mul_f32_e32 v82, v82, v83
	v_mul_f32_e32 v79, v79, v80
	v_mul_f32_e32 v80, 0xbfb8aa3b, v81
	v_mul_f32_e32 v81, 0xbfb8aa3b, v83
	v_exp_f32_e32 v80, v80
	v_exp_f32_e32 v81, v81
	v_lshlrev_b32_e32 v83, 16, v120
	v_pk_add_f32 v[80:81], v[80:81], 1.0 op_sel_hi:[1,0]
	s_nop 0
	v_mul_f32_e32 v80, v80, v81
	v_rcp_f32_e32 v80, v80
	s_nop 0
	v_mul_f32_e32 v80, v82, v80
	v_lshlrev_b32_e32 v82, 16, v116
	v_cvt_pk_bf16_f32 v79, v79, v80
	v_exp_f32_e32 v80, v74
	v_mul_f32_e32 v74, 0xbfb8aa3b, v82
	v_exp_f32_e32 v81, v74
	v_mul_f32_e32 v74, v83, v82
	v_and_b32_e32 v82, 0xffff0000, v116
	v_pk_add_f32 v[80:81], v[80:81], 1.0 op_sel_hi:[1,0]
	s_nop 0
	v_mul_f32_e32 v80, v80, v81
	v_rcp_f32_e32 v80, v80
	v_and_b32_e32 v81, 0xffff0000, v120
	v_mul_f32_e32 v81, v81, v82
	v_mul_f32_e32 v80, v74, v80
	v_mul_f32_e32 v74, 0xbfb8aa3b, v75
	v_mul_f32_e32 v75, 0xbfb8aa3b, v82
	v_exp_f32_e32 v74, v74
	v_exp_f32_e32 v75, v75
	v_lshlrev_b32_e32 v82, 16, v121
	v_pk_add_f32 v[74:75], v[74:75], 1.0 op_sel_hi:[1,0]
	s_nop 0
	v_mul_f32_e32 v74, v74, v75
	v_rcp_f32_e32 v74, v74
	s_nop 0
	v_mul_f32_e32 v74, v81, v74
	v_lshlrev_b32_e32 v81, 16, v117
	v_cvt_pk_bf16_f32 v80, v80, v74
	v_mul_f32_e32 v74, 0xbfb8aa3b, v76
	v_mul_f32_e32 v75, 0xbfb8aa3b, v81
	v_exp_f32_e32 v74, v74
	v_exp_f32_e32 v75, v75
	v_mul_f32_e32 v76, v82, v81
	v_and_b32_e32 v82, 0xffff0000, v117
	v_and_b32_e32 v81, 0xffff0000, v121
	v_pk_add_f32 v[74:75], v[74:75], 1.0 op_sel_hi:[1,0]
	s_nop 0
	v_mul_f32_e32 v74, v74, v75
	v_rcp_f32_e32 v74, v74
	v_mul_f32_e32 v75, 0xbfb8aa3b, v82
	v_exp_f32_e32 v75, v75
	v_mul_f32_e32 v76, v76, v74
	v_mul_f32_e32 v74, 0xbfb8aa3b, v77
	v_exp_f32_e32 v74, v74
	v_mul_f32_e32 v77, v81, v82
	v_pk_add_f32 v[74:75], v[74:75], 1.0 op_sel_hi:[1,0]
	s_nop 0
	v_mul_f32_e32 v74, v74, v75
	v_rcp_f32_e32 v74, v74
	s_nop 0
	v_mul_f32_e32 v74, v77, v74
	v_cvt_pk_bf16_f32 v81, v76, v74
	v_lshlrev_b64 v[74:75], 13, v[170:171]
	v_lshl_add_u64 v[74:75], s[44:45], 0, v[74:75]
	v_lshl_add_u64 v[112:113], v[74:75], 0, v[204:205]
	v_or_b32_e32 v74, 0x80, v200
	v_ashrrev_i32_e32 v75, 31, v74
	v_ashrrev_i32_e32 v76, 4, v74
	v_mad_i64_i32 v[114:115], s[4:5], v76, s94, v[194:195]
	v_lshl_add_u64 v[76:77], s[46:47], 0, v[202:203]
	v_lshlrev_b64 v[116:117], 1, v[74:75]
	v_lshl_add_u64 v[74:75], v[76:77], 0, v[116:117]
	global_load_dwordx4 v[98:101], v[74:75], off
	s_nop 0
	global_store_dwordx4 v[112:113], v[78:81], off
	s_nop 1
	v_lshl_add_u64 v[78:79], v[114:115], 0, v[218:219]
	global_load_dwordx4 v[78:81], v[78:79], off
	v_lshl_add_u64 v[74:75], v[114:115], 0, v[206:207]
	global_load_dwordx4 v[102:105], v[74:75], off
	v_lshl_add_u64 v[74:75], s[46:47], 0, v[210:211]
	v_lshl_add_u64 v[74:75], v[74:75], 0, v[116:117]
	global_load_dwordx4 v[90:93], v[74:75], off
	v_lshl_add_u64 v[74:75], v[114:115], 0, v[208:209]
	global_load_dwordx4 v[94:97], v[74:75], off
	v_lshl_add_u64 v[74:75], s[46:47], 0, v[214:215]
	v_lshl_add_u64 v[74:75], v[74:75], 0, v[116:117]
	global_load_dwordx4 v[82:85], v[74:75], off
	v_lshl_add_u64 v[74:75], v[114:115], 0, v[212:213]
	global_load_dwordx4 v[86:89], v[74:75], off
	v_lshl_add_u64 v[74:75], s[46:47], 0, v[216:217]
	v_lshl_add_u64 v[74:75], v[74:75], 0, v[116:117]
	global_load_dwordx4 v[74:77], v[74:75], off
	s_waitcnt vmcnt(0)
; __device__ __forceinline__ unsigned cvt_pk_bf16(float lo, float hi) { unsigned r; asm volatile("v_cvt_pk_bf16_f32 %0, %1, %2" : "=v"(r) : "v"(lo), "v"(hi)); return r; }
; __device__ __forceinline__ float bf_lo(unsigned w) { return __uint_as_float(w << 16); }
; __device__ __forceinline__ float bf_hi(unsigned w) { return __uint_as_float(w & 0xffff0000u); }
; __device__ __forceinline__ float fast_rcp(float x) { return __builtin_amdgcn_rcpf(x); }
; __device__ __forceinline__ float glu_gate_f(float g, float v, float z) {
;     const float ev = __builtin_amdgcn_exp2f(v * -1.44269504f), ez = __builtin_amdgcn_exp2f(z * -1.44269504f);
;     return g * z * fast_rcp((1.0f + ev) * (1.0f + ez));
; }
;     __device__ __forceinline__ void operator()(const f32x4 (&acc)[2][2][4][2], const Unit& u, int wr, int wc, int fr, int fq, const Pre&) const {
;     ...
;             for (int ai = 0; ai < 2; ++ai) { u32x4 zv[4], gv[4];
; #pragma unroll
;                 for (int m = 0; m < 4; ++m) { const int r = row0 + ai * HALF + m * 16; zv[m] = *(const u32x4*)(Z + (size_t)r * DE2 + c); gv[m] = *(const u32x4*)(Gm + (size_t)(c >> 4) * GSTR + r * 16 + (c & 15)); }
; #pragma unroll
;                 for (int m = 0; m < 4; ++m) { const int r = row0 + ai * HALF + m * 16;
;                     const u32x4 zw = zv[m], gw = gv[m];
;                     const f32x4 a0 = acc[ai][bj][m][0] + bs[bj][0], a1 = acc[ai][bj][m][1] + bs[bj][1];
;                     u32x4 w;
;                     w.x = cvt_pk_bf16(glu_gate_f(bf_lo(gw.x), a0[0], bf_lo(zw.x)), glu_gate_f(bf_hi(gw.x), a0[1], bf_hi(zw.x)));
;                     w.y = cvt_pk_bf16(glu_gate_f(bf_lo(gw.y), a0[2], bf_lo(zw.y)), glu_gate_f(bf_hi(gw.y), a0[3], bf_hi(zw.y)));
;                     w.z = cvt_pk_bf16(glu_gate_f(bf_lo(gw.z), a1[0], bf_lo(zw.z)), glu_gate_f(bf_hi(gw.z), a1[1], bf_hi(zw.z)));
;                     w.w = cvt_pk_bf16(glu_gate_f(bf_lo(gw.w), a1[2], bf_lo(zw.w)), glu_gate_f(bf_hi(gw.w), a1[3], bf_hi(zw.w)));
;                     *(u32x4*)(O + (size_t)r * DE + c) = w; } } }
	v_lshlrev_b32_e32 v120, 16, v98
	v_mul_f32_e32 v70, 0xbfb8aa3b, v120
	v_exp_f32_e32 v119, v70
	v_and_b32_e32 v98, 0xffff0000, v98
	v_pk_add_f32 v[118:119], v[118:119], 1.0 op_sel_hi:[1,0]
	s_nop 0
	v_mul_f32_e32 v118, v118, v119
	v_rcp_f32_e32 v118, v118
	v_lshlrev_b32_e32 v121, 16, v102
	v_mul_f32_e32 v70, v121, v120
	v_and_b32_e32 v102, 0xffff0000, v102
	v_mul_f32_e32 v118, v70, v118
	v_mul_f32_e32 v70, 0xbfb8aa3b, v71
	v_mul_f32_e32 v71, 0xbfb8aa3b, v98
	v_exp_f32_e32 v70, v70
	v_exp_f32_e32 v71, v71
	v_mul_f32_e32 v98, v102, v98
	v_pk_add_f32 v[70:71], v[70:71], 1.0 op_sel_hi:[1,0]
	s_nop 0
	v_mul_f32_e32 v70, v70, v71
	v_rcp_f32_e32 v70, v70
	v_lshlrev_b32_e32 v71, 16, v99
	v_and_b32_e32 v99, 0xffff0000, v99
	v_mul_f32_e32 v70, v98, v70
	v_cvt_pk_bf16_f32 v70, v118, v70
	v_exp_f32_e32 v118, v72
	v_mul_f32_e32 v72, 0xbfb8aa3b, v71
	v_exp_f32_e32 v119, v72
	v_lshlrev_b32_e32 v98, 16, v103
	v_mul_f32_e32 v71, v98, v71
	v_and_b32_e32 v98, 0xffff0000, v103
	v_pk_add_f32 v[118:119], v[118:119], 1.0 op_sel_hi:[1,0]
	v_mul_f32_e32 v98, v98, v99
	v_mul_f32_e32 v72, v118, v119
	v_rcp_f32_e32 v72, v72
	s_nop 0
	v_mul_f32_e32 v71, v71, v72
	v_mul_f32_e32 v72, 0xbfb8aa3b, v73
	v_mul_f32_e32 v73, 0xbfb8aa3b, v99
	v_exp_f32_e32 v72, v72
	v_exp_f32_e32 v73, v73
	v_lshlrev_b32_e32 v99, 16, v104
	v_pk_add_f32 v[72:73], v[72:73], 1.0 op_sel_hi:[1,0]
	s_nop 0
	v_mul_f32_e32 v72, v72, v73
	v_rcp_f32_e32 v72, v72
	s_nop 0
	v_mul_f32_e32 v72, v98, v72
	v_lshlrev_b32_e32 v98, 16, v100
	v_cvt_pk_bf16_f32 v71, v71, v72
	v_exp_f32_e32 v72, v66
	v_mul_f32_e32 v66, 0xbfb8aa3b, v98
	v_exp_f32_e32 v73, v66
	v_mul_f32_e32 v66, v99, v98
	v_and_b32_e32 v98, 0xffff0000, v100
	v_pk_add_f32 v[72:73], v[72:73], 1.0 op_sel_hi:[1,0]
	s_nop 0
	v_mul_f32_e32 v72, v72, v73
	v_rcp_f32_e32 v72, v72
	v_and_b32_e32 v73, 0xffff0000, v104
	v_mul_f32_e32 v73, v73, v98
	v_mul_f32_e32 v72, v66, v72
	v_mul_f32_e32 v66, 0xbfb8aa3b, v67
	v_mul_f32_e32 v67, 0xbfb8aa3b, v98
	v_exp_f32_e32 v66, v66
	v_exp_f32_e32 v67, v67
	v_lshlrev_b32_e32 v98, 16, v105
	v_pk_add_f32 v[66:67], v[66:67], 1.0 op_sel_hi:[1,0]
	s_nop 0
	v_mul_f32_e32 v66, v66, v67
	v_rcp_f32_e32 v66, v66
	s_nop 0
	v_mul_f32_e32 v66, v73, v66
	v_lshlrev_b32_e32 v73, 16, v101
	v_cvt_pk_bf16_f32 v72, v72, v66
	v_mul_f32_e32 v66, 0xbfb8aa3b, v68
	v_mul_f32_e32 v67, 0xbfb8aa3b, v73
	v_exp_f32_e32 v66, v66
	v_exp_f32_e32 v67, v67
	v_mul_f32_e32 v68, v98, v73
	v_and_b32_e32 v98, 0xffff0000, v101
	v_and_b32_e32 v73, 0xffff0000, v105
	v_pk_add_f32 v[66:67], v[66:67], 1.0 op_sel_hi:[1,0]
	s_nop 0
	v_mul_f32_e32 v66, v66, v67
	v_rcp_f32_e32 v66, v66
	v_mul_f32_e32 v67, 0xbfb8aa3b, v98
	v_exp_f32_e32 v67, v67
	v_mul_f32_e32 v68, v68, v66
	v_mul_f32_e32 v66, 0xbfb8aa3b, v69
	v_exp_f32_e32 v66, v66
	v_mul_f32_e32 v69, v73, v98
	v_pk_add_f32 v[66:67], v[66:67], 1.0 op_sel_hi:[1,0]
	s_nop 0
	v_mul_f32_e32 v66, v66, v67
	v_rcp_f32_e32 v66, v66
	s_nop 0
	v_mul_f32_e32 v66, v69, v66
	v_cvt_pk_bf16_f32 v73, v68, v66
	v_lshlrev_b32_e32 v68, 16, v90
	v_exp_f32_e32 v66, v62
	v_mul_f32_e32 v62, 0xbfb8aa3b, v68
	v_exp_f32_e32 v67, v62
	v_lshlrev_b32_e32 v69, 16, v94
	v_mul_f32_e32 v62, v69, v68
	v_and_b32_e32 v68, 0xffff0000, v90
	v_pk_add_f32 v[66:67], v[66:67], 1.0 op_sel_hi:[1,0]
	global_store_dwordx4 v[162:163], v[70:73], off offset:256
	v_mul_f32_e32 v66, v66, v67
	v_rcp_f32_e32 v66, v66
	v_and_b32_e32 v67, 0xffff0000, v94
	v_mul_f32_e32 v67, v67, v68
	v_mul_f32_e32 v66, v62, v66
	v_mul_f32_e32 v62, 0xbfb8aa3b, v63
	v_mul_f32_e32 v63, 0xbfb8aa3b, v68
	v_exp_f32_e32 v62, v62
	v_exp_f32_e32 v63, v63
	v_lshlrev_b32_e32 v68, 16, v95
	v_pk_add_f32 v[62:63], v[62:63], 1.0 op_sel_hi:[1,0]
	s_nop 0
	v_mul_f32_e32 v62, v62, v63
	v_rcp_f32_e32 v62, v62
	v_lshlrev_b32_e32 v63, 16, v91
	v_mul_f32_e32 v62, v67, v62
	v_cvt_pk_bf16_f32 v62, v66, v62
	v_exp_f32_e32 v66, v64
	v_mul_f32_e32 v64, 0xbfb8aa3b, v63
	v_exp_f32_e32 v67, v64
	v_mul_f32_e32 v63, v68, v63
	v_pk_add_f32 v[66:67], v[66:67], 1.0 op_sel_hi:[1,0]
	s_nop 0
	v_mul_f32_e32 v64, v66, v67
	v_rcp_f32_e32 v64, v64
	v_and_b32_e32 v67, 0xffff0000, v91
	v_and_b32_e32 v66, 0xffff0000, v95
	v_mul_f32_e32 v66, v66, v67
	v_mul_f32_e32 v63, v63, v64
	v_mul_f32_e32 v64, 0xbfb8aa3b, v65
	v_mul_f32_e32 v65, 0xbfb8aa3b, v67
	v_exp_f32_e32 v64, v64
	v_exp_f32_e32 v65, v65
	v_lshlrev_b32_e32 v67, 16, v96
	v_pk_add_f32 v[64:65], v[64:65], 1.0 op_sel_hi:[1,0]
	s_nop 0
	v_mul_f32_e32 v64, v64, v65
	v_rcp_f32_e32 v64, v64
	s_nop 0
	v_mul_f32_e32 v64, v66, v64
	v_lshlrev_b32_e32 v66, 16, v92
	v_cvt_pk_bf16_f32 v63, v63, v64
	v_exp_f32_e32 v64, v58
	v_mul_f32_e32 v58, 0xbfb8aa3b, v66
	v_exp_f32_e32 v65, v58
	v_mul_f32_e32 v58, v67, v66
	v_and_b32_e32 v66, 0xffff0000, v92
	v_pk_add_f32 v[64:65], v[64:65], 1.0 op_sel_hi:[1,0]
	s_nop 0
	v_mul_f32_e32 v64, v64, v65
	v_rcp_f32_e32 v64, v64
	v_and_b32_e32 v65, 0xffff0000, v96
	v_mul_f32_e32 v65, v65, v66
	v_mul_f32_e32 v64, v58, v64
	v_mul_f32_e32 v58, 0xbfb8aa3b, v59
	v_mul_f32_e32 v59, 0xbfb8aa3b, v66
	v_exp_f32_e32 v58, v58
	v_exp_f32_e32 v59, v59
	v_lshlrev_b32_e32 v66, 16, v97
	v_pk_add_f32 v[58:59], v[58:59], 1.0 op_sel_hi:[1,0]
	s_nop 0
	v_mul_f32_e32 v58, v58, v59
	v_rcp_f32_e32 v58, v58
	s_nop 0
	v_mul_f32_e32 v58, v65, v58
	v_lshlrev_b32_e32 v65, 16, v93
	v_cvt_pk_bf16_f32 v64, v64, v58
	v_mul_f32_e32 v58, 0xbfb8aa3b, v60
	v_mul_f32_e32 v59, 0xbfb8aa3b, v65
	v_exp_f32_e32 v58, v58
	v_exp_f32_e32 v59, v59
	v_mul_f32_e32 v60, v66, v65
	v_and_b32_e32 v66, 0xffff0000, v93
	v_and_b32_e32 v65, 0xffff0000, v97
	v_pk_add_f32 v[58:59], v[58:59], 1.0 op_sel_hi:[1,0]
	s_nop 0
	v_mul_f32_e32 v58, v58, v59
	v_rcp_f32_e32 v58, v58
	v_mul_f32_e32 v59, 0xbfb8aa3b, v66
; __device__ __forceinline__ unsigned cvt_pk_bf16(float lo, float hi) { unsigned r; asm volatile("v_cvt_pk_bf16_f32 %0, %1, %2" : "=v"(r) : "v"(lo), "v"(hi)); return r; }
; __device__ __forceinline__ float bf_lo(unsigned w) { return __uint_as_float(w << 16); }
; __device__ __forceinline__ float bf_hi(unsigned w) { return __uint_as_float(w & 0xffff0000u); }
; __device__ __forceinline__ float fast_rcp(float x) { return __builtin_amdgcn_rcpf(x); }
; __device__ __forceinline__ float glu_gate_f(float g, float v, float z) {
;     const float ev = __builtin_amdgcn_exp2f(v * -1.44269504f), ez = __builtin_amdgcn_exp2f(z * -1.44269504f);
;     return g * z * fast_rcp((1.0f + ev) * (1.0f + ez));
; }
;     __device__ __forceinline__ void operator()(const f32x4 (&acc)[2][2][4][2], const Unit& u, int wr, int wc, int fr, int fq, const Pre&) const {
;     ...
;             for (int ai = 0; ai < 2; ++ai) { u32x4 zv[4], gv[4];
; #pragma unroll
;                 for (int m = 0; m < 4; ++m) { const int r = row0 + ai * HALF + m * 16; zv[m] = *(const u32x4*)(Z + (size_t)r * DE2 + c); gv[m] = *(const u32x4*)(Gm + (size_t)(c >> 4) * GSTR + r * 16 + (c & 15)); }
; #pragma unroll
;                 for (int m = 0; m < 4; ++m) { const int r = row0 + ai * HALF + m * 16;
;                     const u32x4 zw = zv[m], gw = gv[m];
;                     const f32x4 a0 = acc[ai][bj][m][0] + bs[bj][0], a1 = acc[ai][bj][m][1] + bs[bj][1];
;                     u32x4 w;
;                     w.x = cvt_pk_bf16(glu_gate_f(bf_lo(gw.x), a0[0], bf_lo(zw.x)), glu_gate_f(bf_hi(gw.x), a0[1], bf_hi(zw.x)));
;                     w.y = cvt_pk_bf16(glu_gate_f(bf_lo(gw.y), a0[2], bf_lo(zw.y)), glu_gate_f(bf_hi(gw.y), a0[3], bf_hi(zw.y)));
;                     w.z = cvt_pk_bf16(glu_gate_f(bf_lo(gw.z), a1[0], bf_lo(zw.z)), glu_gate_f(bf_hi(gw.z), a1[1], bf_hi(zw.z)));
;                     w.w = cvt_pk_bf16(glu_gate_f(bf_lo(gw.w), a1[2], bf_lo(zw.w)), glu_gate_f(bf_hi(gw.w), a1[3], bf_hi(zw.w)));
;                     *(u32x4*)(O + (size_t)r * DE + c) = w; } } }
	v_exp_f32_e32 v59, v59
	v_mul_f32_e32 v60, v60, v58
	v_mul_f32_e32 v58, 0xbfb8aa3b, v61
	v_exp_f32_e32 v58, v58
	v_mul_f32_e32 v61, v65, v66
	v_pk_add_f32 v[58:59], v[58:59], 1.0 op_sel_hi:[1,0]
	s_nop 0
	v_mul_f32_e32 v58, v58, v59
	v_rcp_f32_e32 v58, v58
	s_nop 0
	v_mul_f32_e32 v58, v61, v58
	v_cvt_pk_bf16_f32 v65, v60, v58
	v_lshlrev_b32_e32 v60, 16, v82
	v_exp_f32_e32 v58, v54
	v_mul_f32_e32 v54, 0xbfb8aa3b, v60
	v_exp_f32_e32 v59, v54
	v_lshlrev_b32_e32 v61, 16, v86
	v_mul_f32_e32 v54, v61, v60
	v_and_b32_e32 v60, 0xffff0000, v82
	v_pk_add_f32 v[58:59], v[58:59], 1.0 op_sel_hi:[1,0]
	global_store_dwordx4 v[154:155], v[62:65], off offset:256
	v_mul_f32_e32 v58, v58, v59
	v_rcp_f32_e32 v58, v58
	v_and_b32_e32 v59, 0xffff0000, v86
	v_mul_f32_e32 v59, v59, v60
	v_mul_f32_e32 v58, v54, v58
	v_mul_f32_e32 v54, 0xbfb8aa3b, v55
	v_mul_f32_e32 v55, 0xbfb8aa3b, v60
	v_exp_f32_e32 v54, v54
	v_exp_f32_e32 v55, v55
	v_lshlrev_b32_e32 v60, 16, v87
	v_pk_add_f32 v[54:55], v[54:55], 1.0 op_sel_hi:[1,0]
	s_nop 0
	v_mul_f32_e32 v54, v54, v55
	v_rcp_f32_e32 v54, v54
	v_lshlrev_b32_e32 v55, 16, v83
	v_mul_f32_e32 v54, v59, v54
	v_cvt_pk_bf16_f32 v54, v58, v54
	v_exp_f32_e32 v58, v56
	v_mul_f32_e32 v56, 0xbfb8aa3b, v55
	v_exp_f32_e32 v59, v56
	v_mul_f32_e32 v55, v60, v55
	v_pk_add_f32 v[58:59], v[58:59], 1.0 op_sel_hi:[1,0]
	s_nop 0
	v_mul_f32_e32 v56, v58, v59
	v_rcp_f32_e32 v56, v56
	v_and_b32_e32 v59, 0xffff0000, v83
	v_and_b32_e32 v58, 0xffff0000, v87
	v_mul_f32_e32 v58, v58, v59
	v_mul_f32_e32 v55, v55, v56
	v_mul_f32_e32 v56, 0xbfb8aa3b, v57
	v_mul_f32_e32 v57, 0xbfb8aa3b, v59
	v_exp_f32_e32 v56, v56
	v_exp_f32_e32 v57, v57
	v_lshlrev_b32_e32 v59, 16, v88
	v_pk_add_f32 v[56:57], v[56:57], 1.0 op_sel_hi:[1,0]
	s_nop 0
	v_mul_f32_e32 v56, v56, v57
	v_rcp_f32_e32 v56, v56
	s_nop 0
	v_mul_f32_e32 v56, v58, v56
	v_lshlrev_b32_e32 v58, 16, v84
	v_cvt_pk_bf16_f32 v55, v55, v56
	v_exp_f32_e32 v56, v50
	v_mul_f32_e32 v50, 0xbfb8aa3b, v58
	v_exp_f32_e32 v57, v50
	v_mul_f32_e32 v50, v59, v58
	v_and_b32_e32 v58, 0xffff0000, v84
	v_pk_add_f32 v[56:57], v[56:57], 1.0 op_sel_hi:[1,0]
	s_nop 0
	v_mul_f32_e32 v56, v56, v57
	v_rcp_f32_e32 v56, v56
	v_and_b32_e32 v57, 0xffff0000, v88
	v_mul_f32_e32 v57, v57, v58
	v_mul_f32_e32 v56, v50, v56
	v_mul_f32_e32 v50, 0xbfb8aa3b, v51
	v_mul_f32_e32 v51, 0xbfb8aa3b, v58
	v_exp_f32_e32 v50, v50
	v_exp_f32_e32 v51, v51
	v_lshlrev_b32_e32 v58, 16, v89
	v_pk_add_f32 v[50:51], v[50:51], 1.0 op_sel_hi:[1,0]
	s_nop 0
	v_mul_f32_e32 v50, v50, v51
	v_rcp_f32_e32 v50, v50
	s_nop 0
	v_mul_f32_e32 v50, v57, v50
	v_lshlrev_b32_e32 v57, 16, v85
	v_cvt_pk_bf16_f32 v56, v56, v50
	v_mul_f32_e32 v50, 0xbfb8aa3b, v52
	v_mul_f32_e32 v51, 0xbfb8aa3b, v57
	v_exp_f32_e32 v50, v50
	v_exp_f32_e32 v51, v51
	v_mul_f32_e32 v52, v58, v57
	v_and_b32_e32 v58, 0xffff0000, v85
	v_and_b32_e32 v57, 0xffff0000, v89
	v_pk_add_f32 v[50:51], v[50:51], 1.0 op_sel_hi:[1,0]
	s_nop 0
	v_mul_f32_e32 v50, v50, v51
	v_rcp_f32_e32 v50, v50
	v_mul_f32_e32 v51, 0xbfb8aa3b, v58
	v_exp_f32_e32 v51, v51
	v_mul_f32_e32 v52, v52, v50
	v_mul_f32_e32 v50, 0xbfb8aa3b, v53
	v_exp_f32_e32 v50, v50
	v_mul_f32_e32 v53, v57, v58
	v_pk_add_f32 v[50:51], v[50:51], 1.0 op_sel_hi:[1,0]
	s_nop 0
	v_mul_f32_e32 v50, v50, v51
	v_rcp_f32_e32 v50, v50
	s_nop 0
	v_mul_f32_e32 v50, v53, v50
	v_cvt_pk_bf16_f32 v57, v52, v50
	v_lshlrev_b32_e32 v52, 16, v74
	v_exp_f32_e32 v50, v46
	v_mul_f32_e32 v46, 0xbfb8aa3b, v52
	v_exp_f32_e32 v51, v46
	v_lshlrev_b32_e32 v53, 16, v78
	v_mul_f32_e32 v46, v53, v52
	v_and_b32_e32 v52, 0xffff0000, v74
	v_pk_add_f32 v[50:51], v[50:51], 1.0 op_sel_hi:[1,0]
	global_store_dwordx4 v[146:147], v[54:57], off offset:256
	v_mul_f32_e32 v50, v50, v51
	v_rcp_f32_e32 v50, v50
	v_and_b32_e32 v51, 0xffff0000, v78
	v_mul_f32_e32 v51, v51, v52
	v_exp_f32_e32 v74, v38
	v_mul_f32_e32 v50, v46, v50
	v_mul_f32_e32 v46, 0xbfb8aa3b, v47
	v_mul_f32_e32 v47, 0xbfb8aa3b, v52
	v_exp_f32_e32 v46, v46
	v_exp_f32_e32 v47, v47
	v_lshlrev_b32_e32 v52, 16, v79
	v_pk_add_f32 v[46:47], v[46:47], 1.0 op_sel_hi:[1,0]
	s_nop 0
	v_mul_f32_e32 v46, v46, v47
	v_rcp_f32_e32 v46, v46
	v_lshlrev_b32_e32 v47, 16, v75
	v_mul_f32_e32 v46, v51, v46
	v_cvt_pk_bf16_f32 v46, v50, v46
	v_exp_f32_e32 v50, v48
	v_mul_f32_e32 v48, 0xbfb8aa3b, v47
	v_exp_f32_e32 v51, v48
	v_mul_f32_e32 v47, v52, v47
	v_pk_add_f32 v[50:51], v[50:51], 1.0 op_sel_hi:[1,0]
	s_nop 0
	v_mul_f32_e32 v48, v50, v51
	v_rcp_f32_e32 v48, v48
	v_and_b32_e32 v51, 0xffff0000, v75
	v_and_b32_e32 v50, 0xffff0000, v79
	v_mul_f32_e32 v50, v50, v51
	v_mul_f32_e32 v47, v47, v48
	v_mul_f32_e32 v48, 0xbfb8aa3b, v49
	v_mul_f32_e32 v49, 0xbfb8aa3b, v51
	v_exp_f32_e32 v48, v48
	v_exp_f32_e32 v49, v49
	v_lshlrev_b32_e32 v51, 16, v80
	v_pk_add_f32 v[48:49], v[48:49], 1.0 op_sel_hi:[1,0]
	s_nop 0
	v_mul_f32_e32 v48, v48, v49
	v_rcp_f32_e32 v48, v48
	s_nop 0
	v_mul_f32_e32 v48, v50, v48
	v_lshlrev_b32_e32 v50, 16, v76
	v_cvt_pk_bf16_f32 v47, v47, v48
	v_exp_f32_e32 v48, v42
	v_mul_f32_e32 v42, 0xbfb8aa3b, v50
	v_exp_f32_e32 v49, v42
	v_mul_f32_e32 v42, v51, v50
	v_and_b32_e32 v50, 0xffff0000, v76
	v_pk_add_f32 v[48:49], v[48:49], 1.0 op_sel_hi:[1,0]
	s_nop 0
	v_mul_f32_e32 v48, v48, v49
	v_rcp_f32_e32 v48, v48
	v_and_b32_e32 v49, 0xffff0000, v80
	v_mul_f32_e32 v49, v49, v50
	v_mul_f32_e32 v48, v42, v48
	v_mul_f32_e32 v42, 0xbfb8aa3b, v43
	v_mul_f32_e32 v43, 0xbfb8aa3b, v50
	v_exp_f32_e32 v42, v42
	v_exp_f32_e32 v43, v43
	v_lshlrev_b32_e32 v50, 16, v81
	v_pk_add_f32 v[42:43], v[42:43], 1.0 op_sel_hi:[1,0]
	s_nop 0
	v_mul_f32_e32 v42, v42, v43
	v_rcp_f32_e32 v42, v42
	s_nop 0
	v_mul_f32_e32 v42, v49, v42
	v_lshlrev_b32_e32 v49, 16, v77
	v_cvt_pk_bf16_f32 v48, v48, v42
; __device__ __forceinline__ unsigned cvt_pk_bf16(float lo, float hi) { unsigned r; asm volatile("v_cvt_pk_bf16_f32 %0, %1, %2" : "=v"(r) : "v"(lo), "v"(hi)); return r; }
; __device__ __forceinline__ float bf_lo(unsigned w) { return __uint_as_float(w << 16); }
; __device__ __forceinline__ float bf_hi(unsigned w) { return __uint_as_float(w & 0xffff0000u); }
; __device__ __forceinline__ float fast_rcp(float x) { return __builtin_amdgcn_rcpf(x); }
; __device__ __forceinline__ float glu_gate_f(float g, float v, float z) {
;     const float ev = __builtin_amdgcn_exp2f(v * -1.44269504f), ez = __builtin_amdgcn_exp2f(z * -1.44269504f);
;     return g * z * fast_rcp((1.0f + ev) * (1.0f + ez));
; }
;     __device__ __forceinline__ void operator()(const f32x4 (&acc)[2][2][4][2], const Unit& u, int wr, int wc, int fr, int fq, const Pre&) const {
;     ...
;             for (int ai = 0; ai < 2; ++ai) { u32x4 zv[4], gv[4];
; #pragma unroll
;                 for (int m = 0; m < 4; ++m) { const int r = row0 + ai * HALF + m * 16; zv[m] = *(const u32x4*)(Z + (size_t)r * DE2 + c); gv[m] = *(const u32x4*)(Gm + (size_t)(c >> 4) * GSTR + r * 16 + (c & 15)); }
; #pragma unroll
;                 for (int m = 0; m < 4; ++m) { const int r = row0 + ai * HALF + m * 16;
;                     const u32x4 zw = zv[m], gw = gv[m];
;                     const f32x4 a0 = acc[ai][bj][m][0] + bs[bj][0], a1 = acc[ai][bj][m][1] + bs[bj][1];
;                     u32x4 w;
;                     w.x = cvt_pk_bf16(glu_gate_f(bf_lo(gw.x), a0[0], bf_lo(zw.x)), glu_gate_f(bf_hi(gw.x), a0[1], bf_hi(zw.x)));
;                     w.y = cvt_pk_bf16(glu_gate_f(bf_lo(gw.y), a0[2], bf_lo(zw.y)), glu_gate_f(bf_hi(gw.y), a0[3], bf_hi(zw.y)));
;                     w.z = cvt_pk_bf16(glu_gate_f(bf_lo(gw.z), a1[0], bf_lo(zw.z)), glu_gate_f(bf_hi(gw.z), a1[1], bf_hi(zw.z)));
;                     w.w = cvt_pk_bf16(glu_gate_f(bf_lo(gw.w), a1[2], bf_lo(zw.w)), glu_gate_f(bf_hi(gw.w), a1[3], bf_hi(zw.w)));
;                     *(u32x4*)(O + (size_t)r * DE + c) = w; } } }
	v_mul_f32_e32 v42, 0xbfb8aa3b, v44
	v_mul_f32_e32 v43, 0xbfb8aa3b, v49
	v_exp_f32_e32 v42, v42
	v_exp_f32_e32 v43, v43
	v_mul_f32_e32 v44, v50, v49
	v_and_b32_e32 v50, 0xffff0000, v77
	v_and_b32_e32 v49, 0xffff0000, v81
	v_pk_add_f32 v[42:43], v[42:43], 1.0 op_sel_hi:[1,0]
	s_nop 0
	v_mul_f32_e32 v42, v42, v43
	v_rcp_f32_e32 v42, v42
	v_mul_f32_e32 v43, 0xbfb8aa3b, v50
	v_exp_f32_e32 v43, v43
	v_mul_f32_e32 v44, v44, v42
	v_mul_f32_e32 v42, 0xbfb8aa3b, v45
	v_exp_f32_e32 v42, v42
	v_mul_f32_e32 v45, v49, v50
	v_pk_add_f32 v[42:43], v[42:43], 1.0 op_sel_hi:[1,0]
	s_nop 0
	v_mul_f32_e32 v42, v42, v43
	v_rcp_f32_e32 v42, v42
	s_nop 0
	v_mul_f32_e32 v42, v45, v42
	v_cvt_pk_bf16_f32 v49, v44, v42
	v_lshl_add_u64 v[42:43], s[46:47], 0, v[150:151]
	global_store_dwordx4 v[148:149], v[46:49], off offset:256
	v_lshl_add_u64 v[42:43], v[42:43], 0, v[116:117]
	global_load_dwordx4 v[66:69], v[42:43], off
	v_lshl_add_u64 v[46:47], v[114:115], 0, v[168:169]
	global_load_dwordx4 v[46:49], v[46:47], off
	v_lshl_add_u64 v[42:43], v[114:115], 0, v[152:153]
	global_load_dwordx4 v[70:73], v[42:43], off
	v_lshl_add_u64 v[42:43], s[46:47], 0, v[156:157]
	v_lshl_add_u64 v[42:43], v[42:43], 0, v[116:117]
	global_load_dwordx4 v[58:61], v[42:43], off
	v_lshl_add_u64 v[42:43], v[114:115], 0, v[158:159]
	global_load_dwordx4 v[62:65], v[42:43], off
	v_lshl_add_u64 v[42:43], s[46:47], 0, v[160:161]
	v_lshl_add_u64 v[42:43], v[42:43], 0, v[116:117]
	global_load_dwordx4 v[50:53], v[42:43], off
	v_lshl_add_u64 v[42:43], v[114:115], 0, v[164:165]
	global_load_dwordx4 v[54:57], v[42:43], off
	v_lshl_add_u64 v[42:43], s[46:47], 0, v[166:167]
	v_lshl_add_u64 v[42:43], v[42:43], 0, v[116:117]
	global_load_dwordx4 v[42:45], v[42:43], off
	s_waitcnt vmcnt(0)
	v_lshlrev_b32_e32 v76, 16, v66
	v_mul_f32_e32 v38, 0xbfb8aa3b, v76
	v_exp_f32_e32 v75, v38
	v_and_b32_e32 v66, 0xffff0000, v66
	v_lshlrev_b32_e32 v77, 16, v70
	v_mul_f32_e32 v38, v77, v76
	v_pk_add_f32 v[74:75], v[74:75], 1.0 op_sel_hi:[1,0]
	v_and_b32_e32 v70, 0xffff0000, v70
	v_mul_f32_e32 v74, v74, v75
	v_rcp_f32_e32 v74, v74
	s_nop 0
	v_mul_f32_e32 v74, v38, v74
	v_mul_f32_e32 v38, 0xbfb8aa3b, v39
	v_mul_f32_e32 v39, 0xbfb8aa3b, v66
	v_exp_f32_e32 v38, v38
	v_exp_f32_e32 v39, v39
	v_mul_f32_e32 v66, v70, v66
	v_pk_add_f32 v[38:39], v[38:39], 1.0 op_sel_hi:[1,0]
	s_nop 0
	v_mul_f32_e32 v38, v38, v39
	v_rcp_f32_e32 v38, v38
	v_lshlrev_b32_e32 v39, 16, v67
	v_and_b32_e32 v67, 0xffff0000, v67
	v_mul_f32_e32 v38, v66, v38
	v_cvt_pk_bf16_f32 v38, v74, v38
	v_exp_f32_e32 v74, v40
	v_mul_f32_e32 v40, 0xbfb8aa3b, v39
	v_exp_f32_e32 v75, v40
	v_lshlrev_b32_e32 v66, 16, v71
	v_mul_f32_e32 v39, v66, v39
	v_and_b32_e32 v66, 0xffff0000, v71
	v_pk_add_f32 v[74:75], v[74:75], 1.0 op_sel_hi:[1,0]
	v_mul_f32_e32 v66, v66, v67
	v_mul_f32_e32 v40, v74, v75
	v_rcp_f32_e32 v40, v40
	s_nop 0
	v_mul_f32_e32 v39, v39, v40
	v_mul_f32_e32 v40, 0xbfb8aa3b, v41
	v_mul_f32_e32 v41, 0xbfb8aa3b, v67
	v_exp_f32_e32 v40, v40
	v_exp_f32_e32 v41, v41
	v_lshlrev_b32_e32 v67, 16, v72
	v_pk_add_f32 v[40:41], v[40:41], 1.0 op_sel_hi:[1,0]
	s_nop 0
	v_mul_f32_e32 v40, v40, v41
	v_rcp_f32_e32 v40, v40
	s_nop 0
	v_mul_f32_e32 v40, v66, v40
	v_lshlrev_b32_e32 v66, 16, v68
	v_cvt_pk_bf16_f32 v39, v39, v40
	v_exp_f32_e32 v40, v34
	v_mul_f32_e32 v34, 0xbfb8aa3b, v66
	v_exp_f32_e32 v41, v34
	v_mul_f32_e32 v34, v67, v66
	v_and_b32_e32 v66, 0xffff0000, v68
	v_pk_add_f32 v[40:41], v[40:41], 1.0 op_sel_hi:[1,0]
	s_nop 0
	v_mul_f32_e32 v40, v40, v41
	v_rcp_f32_e32 v40, v40
	v_and_b32_e32 v41, 0xffff0000, v72
	v_mul_f32_e32 v41, v41, v66
	v_mul_f32_e32 v40, v34, v40
	v_mul_f32_e32 v34, 0xbfb8aa3b, v35
	v_mul_f32_e32 v35, 0xbfb8aa3b, v66
	v_exp_f32_e32 v34, v34
	v_exp_f32_e32 v35, v35
	v_lshlrev_b32_e32 v66, 16, v73
	v_pk_add_f32 v[34:35], v[34:35], 1.0 op_sel_hi:[1,0]
	s_nop 0
	v_mul_f32_e32 v34, v34, v35
	v_rcp_f32_e32 v34, v34
	s_nop 0
	v_mul_f32_e32 v34, v41, v34
	v_lshlrev_b32_e32 v41, 16, v69
	v_cvt_pk_bf16_f32 v40, v40, v34
	v_mul_f32_e32 v34, 0xbfb8aa3b, v36
	v_mul_f32_e32 v35, 0xbfb8aa3b, v41
	v_exp_f32_e32 v34, v34
	v_exp_f32_e32 v35, v35
	v_mul_f32_e32 v36, v66, v41
	v_and_b32_e32 v66, 0xffff0000, v69
	v_and_b32_e32 v41, 0xffff0000, v73
	v_pk_add_f32 v[34:35], v[34:35], 1.0 op_sel_hi:[1,0]
	s_nop 0
	v_mul_f32_e32 v34, v34, v35
	v_rcp_f32_e32 v34, v34
	v_mul_f32_e32 v35, 0xbfb8aa3b, v66
	v_exp_f32_e32 v35, v35
	v_mul_f32_e32 v36, v36, v34
	v_mul_f32_e32 v34, 0xbfb8aa3b, v37
	v_exp_f32_e32 v34, v34
	v_mul_f32_e32 v37, v41, v66
	v_pk_add_f32 v[34:35], v[34:35], 1.0 op_sel_hi:[1,0]
	s_nop 0
	v_mul_f32_e32 v34, v34, v35
	v_rcp_f32_e32 v34, v34
	s_nop 0
	v_mul_f32_e32 v34, v37, v34
	v_cvt_pk_bf16_f32 v41, v36, v34
	v_lshlrev_b32_e32 v36, 16, v58
	v_exp_f32_e32 v34, v22
	v_mul_f32_e32 v22, 0xbfb8aa3b, v36
	v_exp_f32_e32 v35, v22
	v_lshlrev_b32_e32 v37, 16, v62
	v_mul_f32_e32 v22, v37, v36
	v_and_b32_e32 v36, 0xffff0000, v58
	v_pk_add_f32 v[34:35], v[34:35], 1.0 op_sel_hi:[1,0]
	global_store_dwordx4 v[106:107], v[38:41], off offset:256
	v_mul_f32_e32 v34, v34, v35
	v_rcp_f32_e32 v34, v34
	v_and_b32_e32 v35, 0xffff0000, v62
	v_mul_f32_e32 v35, v35, v36
	v_mul_f32_e32 v34, v22, v34
	v_mul_f32_e32 v22, 0xbfb8aa3b, v23
	v_mul_f32_e32 v23, 0xbfb8aa3b, v36
	v_exp_f32_e32 v22, v22
	v_exp_f32_e32 v23, v23
	v_lshlrev_b32_e32 v36, 16, v63
	v_pk_add_f32 v[22:23], v[22:23], 1.0 op_sel_hi:[1,0]
	s_nop 0
	v_mul_f32_e32 v22, v22, v23
	v_rcp_f32_e32 v22, v22
	v_lshlrev_b32_e32 v23, 16, v59
	v_mul_f32_e32 v22, v35, v22
	v_cvt_pk_bf16_f32 v22, v34, v22
	v_exp_f32_e32 v34, v24
	v_mul_f32_e32 v24, 0xbfb8aa3b, v23
	v_exp_f32_e32 v35, v24
	v_mul_f32_e32 v23, v36, v23
; __device__ __forceinline__ unsigned cvt_pk_bf16(float lo, float hi) { unsigned r; asm volatile("v_cvt_pk_bf16_f32 %0, %1, %2" : "=v"(r) : "v"(lo), "v"(hi)); return r; }
; __device__ __forceinline__ float bf_lo(unsigned w) { return __uint_as_float(w << 16); }
; __device__ __forceinline__ float bf_hi(unsigned w) { return __uint_as_float(w & 0xffff0000u); }
; __device__ __forceinline__ float fast_rcp(float x) { return __builtin_amdgcn_rcpf(x); }
; __device__ __forceinline__ float glu_gate_f(float g, float v, float z) {
;     const float ev = __builtin_amdgcn_exp2f(v * -1.44269504f), ez = __builtin_amdgcn_exp2f(z * -1.44269504f);
;     return g * z * fast_rcp((1.0f + ev) * (1.0f + ez));
; }
;     __device__ __forceinline__ void operator()(const f32x4 (&acc)[2][2][4][2], const Unit& u, int wr, int wc, int fr, int fq, const Pre&) const {
;     ...
;             for (int ai = 0; ai < 2; ++ai) { u32x4 zv[4], gv[4];
; #pragma unroll
;                 for (int m = 0; m < 4; ++m) { const int r = row0 + ai * HALF + m * 16; zv[m] = *(const u32x4*)(Z + (size_t)r * DE2 + c); gv[m] = *(const u32x4*)(Gm + (size_t)(c >> 4) * GSTR + r * 16 + (c & 15)); }
; #pragma unroll
;                 for (int m = 0; m < 4; ++m) { const int r = row0 + ai * HALF + m * 16;
;                     const u32x4 zw = zv[m], gw = gv[m];
;                     const f32x4 a0 = acc[ai][bj][m][0] + bs[bj][0], a1 = acc[ai][bj][m][1] + bs[bj][1];
;                     u32x4 w;
;                     w.x = cvt_pk_bf16(glu_gate_f(bf_lo(gw.x), a0[0], bf_lo(zw.x)), glu_gate_f(bf_hi(gw.x), a0[1], bf_hi(zw.x)));
;                     w.y = cvt_pk_bf16(glu_gate_f(bf_lo(gw.y), a0[2], bf_lo(zw.y)), glu_gate_f(bf_hi(gw.y), a0[3], bf_hi(zw.y)));
;                     w.z = cvt_pk_bf16(glu_gate_f(bf_lo(gw.z), a1[0], bf_lo(zw.z)), glu_gate_f(bf_hi(gw.z), a1[1], bf_hi(zw.z)));
;                     w.w = cvt_pk_bf16(glu_gate_f(bf_lo(gw.w), a1[2], bf_lo(zw.w)), glu_gate_f(bf_hi(gw.w), a1[3], bf_hi(zw.w)));
;                     *(u32x4*)(O + (size_t)r * DE + c) = w; } } }
	v_pk_add_f32 v[34:35], v[34:35], 1.0 op_sel_hi:[1,0]
	s_nop 0
	v_mul_f32_e32 v24, v34, v35
	v_rcp_f32_e32 v24, v24
	v_and_b32_e32 v35, 0xffff0000, v59
	v_and_b32_e32 v34, 0xffff0000, v63
	v_mul_f32_e32 v34, v34, v35
	v_mul_f32_e32 v23, v23, v24
	v_mul_f32_e32 v24, 0xbfb8aa3b, v25
	v_mul_f32_e32 v25, 0xbfb8aa3b, v35
	v_exp_f32_e32 v24, v24
	v_exp_f32_e32 v25, v25
	v_lshlrev_b32_e32 v35, 16, v64
	v_pk_add_f32 v[24:25], v[24:25], 1.0 op_sel_hi:[1,0]
	s_nop 0
	v_mul_f32_e32 v24, v24, v25
	v_rcp_f32_e32 v24, v24
	s_nop 0
	v_mul_f32_e32 v24, v34, v24
	v_lshlrev_b32_e32 v34, 16, v60
	v_cvt_pk_bf16_f32 v23, v23, v24
	v_exp_f32_e32 v24, v18
	v_mul_f32_e32 v18, 0xbfb8aa3b, v34
	v_exp_f32_e32 v25, v18
	v_mul_f32_e32 v18, v35, v34
	v_and_b32_e32 v34, 0xffff0000, v60
	v_pk_add_f32 v[24:25], v[24:25], 1.0 op_sel_hi:[1,0]
	s_nop 0
	v_mul_f32_e32 v24, v24, v25
	v_rcp_f32_e32 v24, v24
	v_and_b32_e32 v25, 0xffff0000, v64
	v_mul_f32_e32 v25, v25, v34
	v_mul_f32_e32 v24, v18, v24
	v_mul_f32_e32 v18, 0xbfb8aa3b, v19
	v_mul_f32_e32 v19, 0xbfb8aa3b, v34
	v_exp_f32_e32 v18, v18
	v_exp_f32_e32 v19, v19
	v_lshlrev_b32_e32 v34, 16, v65
	v_pk_add_f32 v[18:19], v[18:19], 1.0 op_sel_hi:[1,0]
	s_nop 0
	v_mul_f32_e32 v18, v18, v19
	v_rcp_f32_e32 v18, v18
	s_nop 0
	v_mul_f32_e32 v18, v25, v18
	v_lshlrev_b32_e32 v25, 16, v61
	v_cvt_pk_bf16_f32 v24, v24, v18
	v_mul_f32_e32 v18, 0xbfb8aa3b, v20
	v_mul_f32_e32 v19, 0xbfb8aa3b, v25
	v_exp_f32_e32 v18, v18
	v_exp_f32_e32 v19, v19
	v_mul_f32_e32 v20, v34, v25
	v_and_b32_e32 v34, 0xffff0000, v61
	v_and_b32_e32 v25, 0xffff0000, v65
	v_pk_add_f32 v[18:19], v[18:19], 1.0 op_sel_hi:[1,0]
	s_nop 0
	v_mul_f32_e32 v18, v18, v19
	v_rcp_f32_e32 v18, v18
	v_mul_f32_e32 v19, 0xbfb8aa3b, v34
	v_exp_f32_e32 v19, v19
	v_mul_f32_e32 v20, v20, v18
	v_mul_f32_e32 v18, 0xbfb8aa3b, v21
	v_exp_f32_e32 v18, v18
	v_mul_f32_e32 v21, v25, v34
	v_pk_add_f32 v[18:19], v[18:19], 1.0 op_sel_hi:[1,0]
	s_nop 0
	v_mul_f32_e32 v18, v18, v19
	v_rcp_f32_e32 v18, v18
	s_nop 0
	v_mul_f32_e32 v18, v21, v18
	v_cvt_pk_bf16_f32 v25, v20, v18
	v_lshlrev_b32_e32 v20, 16, v50
	v_exp_f32_e32 v18, v14
	v_mul_f32_e32 v14, 0xbfb8aa3b, v20
	v_exp_f32_e32 v19, v14
	v_lshlrev_b32_e32 v21, 16, v54
	v_mul_f32_e32 v14, v21, v20
	v_and_b32_e32 v20, 0xffff0000, v50
	v_pk_add_f32 v[18:19], v[18:19], 1.0 op_sel_hi:[1,0]
	global_store_dwordx4 v[108:109], v[22:25], off offset:256
	v_mul_f32_e32 v18, v18, v19
	v_rcp_f32_e32 v18, v18
	v_and_b32_e32 v19, 0xffff0000, v54
	v_mul_f32_e32 v19, v19, v20
	v_mul_f32_e32 v18, v14, v18
	v_mul_f32_e32 v14, 0xbfb8aa3b, v15
	v_mul_f32_e32 v15, 0xbfb8aa3b, v20
	v_exp_f32_e32 v14, v14
	v_exp_f32_e32 v15, v15
	v_lshlrev_b32_e32 v20, 16, v55
	v_pk_add_f32 v[14:15], v[14:15], 1.0 op_sel_hi:[1,0]
	s_nop 0
	v_mul_f32_e32 v14, v14, v15
	v_rcp_f32_e32 v14, v14
	v_lshlrev_b32_e32 v15, 16, v51
	v_mul_f32_e32 v14, v19, v14
	v_cvt_pk_bf16_f32 v14, v18, v14
	v_exp_f32_e32 v18, v16
	v_mul_f32_e32 v16, 0xbfb8aa3b, v15
	v_exp_f32_e32 v19, v16
	v_mul_f32_e32 v15, v20, v15
	v_pk_add_f32 v[18:19], v[18:19], 1.0 op_sel_hi:[1,0]
	s_nop 0
	v_mul_f32_e32 v16, v18, v19
	v_rcp_f32_e32 v16, v16
	v_and_b32_e32 v19, 0xffff0000, v51
	v_and_b32_e32 v18, 0xffff0000, v55
	v_mul_f32_e32 v18, v18, v19
	v_mul_f32_e32 v15, v15, v16
	v_mul_f32_e32 v16, 0xbfb8aa3b, v17
	v_mul_f32_e32 v17, 0xbfb8aa3b, v19
	v_exp_f32_e32 v16, v16
	v_exp_f32_e32 v17, v17
	v_lshlrev_b32_e32 v19, 16, v56
	v_pk_add_f32 v[16:17], v[16:17], 1.0 op_sel_hi:[1,0]
	s_nop 0
	v_mul_f32_e32 v16, v16, v17
	v_rcp_f32_e32 v16, v16
	s_nop 0
	v_mul_f32_e32 v16, v18, v16
	v_lshlrev_b32_e32 v18, 16, v52
	v_cvt_pk_bf16_f32 v15, v15, v16
	v_exp_f32_e32 v16, v10
	v_mul_f32_e32 v10, 0xbfb8aa3b, v18
	v_exp_f32_e32 v17, v10
	v_mul_f32_e32 v10, v19, v18
	v_and_b32_e32 v18, 0xffff0000, v52
	v_pk_add_f32 v[16:17], v[16:17], 1.0 op_sel_hi:[1,0]
	s_nop 0
	v_mul_f32_e32 v16, v16, v17
	v_rcp_f32_e32 v16, v16
	v_and_b32_e32 v17, 0xffff0000, v56
	v_mul_f32_e32 v17, v17, v18
	v_mul_f32_e32 v16, v10, v16
	v_mul_f32_e32 v10, 0xbfb8aa3b, v11
	v_mul_f32_e32 v11, 0xbfb8aa3b, v18
	v_exp_f32_e32 v10, v10
; __device__ __forceinline__ unsigned cvt_pk_bf16(float lo, float hi) { unsigned r; asm volatile("v_cvt_pk_bf16_f32 %0, %1, %2" : "=v"(r) : "v"(lo), "v"(hi)); return r; }
; __device__ __forceinline__ float bf_lo(unsigned w) { return __uint_as_float(w << 16); }
; __device__ __forceinline__ float bf_hi(unsigned w) { return __uint_as_float(w & 0xffff0000u); }
; #define PG8_WAIT_V(n) asm volatile("s_waitcnt vmcnt(" #n ")" ::: "memory")
; #define PG8_BAR __builtin_amdgcn_s_barrier()
; template <class Epi>
; __device__ __forceinline__ void gemm_phase(LAS unsigned char* lds, const Gemm g, const StaticOrder& S, const Epi& E) {
;     ...
;     PG8_WAIT_V(0);
;     if (wr == 0) PG8_BAR;
;     __device__ __forceinline__ void operator()(const f32x4 (&acc)[2][2][4][2], const Unit& u, int wr, int wc, int fr, int fq, const Pre&) const {
;     ...
;                     w.x = cvt_pk_bf16(glu_gate_f(bf_lo(gw.x), a0[0], bf_lo(zw.x)), glu_gate_f(bf_hi(gw.x), a0[1], bf_hi(zw.x)));
;                     w.y = cvt_pk_bf16(glu_gate_f(bf_lo(gw.y), a0[2], bf_lo(zw.y)), glu_gate_f(bf_hi(gw.y), a0[3], bf_hi(zw.y)));
;                     w.z = cvt_pk_bf16(glu_gate_f(bf_lo(gw.z), a1[0], bf_lo(zw.z)), glu_gate_f(bf_hi(gw.z), a1[1], bf_hi(zw.z)));
;                     w.w = cvt_pk_bf16(glu_gate_f(bf_lo(gw.w), a1[2], bf_lo(zw.w)), glu_gate_f(bf_hi(gw.w), a1[3], bf_hi(zw.w)));
;                     *(u32x4*)(O + (size_t)r * DE + c) = w; } } }
	v_exp_f32_e32 v11, v11
	v_lshlrev_b32_e32 v18, 16, v57
	v_pk_add_f32 v[10:11], v[10:11], 1.0 op_sel_hi:[1,0]
	s_nop 0
	v_mul_f32_e32 v10, v10, v11
	v_rcp_f32_e32 v10, v10
	s_nop 0
	v_mul_f32_e32 v10, v17, v10
	v_lshlrev_b32_e32 v17, 16, v53
	v_cvt_pk_bf16_f32 v16, v16, v10
	v_mul_f32_e32 v10, 0xbfb8aa3b, v12
	v_mul_f32_e32 v11, 0xbfb8aa3b, v17
	v_exp_f32_e32 v10, v10
	v_exp_f32_e32 v11, v11
	v_mul_f32_e32 v12, v18, v17
	v_and_b32_e32 v18, 0xffff0000, v53
	v_and_b32_e32 v17, 0xffff0000, v57
	v_pk_add_f32 v[10:11], v[10:11], 1.0 op_sel_hi:[1,0]
	s_nop 0
	v_mul_f32_e32 v10, v10, v11
	v_rcp_f32_e32 v10, v10
	v_mul_f32_e32 v11, 0xbfb8aa3b, v18
	v_exp_f32_e32 v11, v11
	v_mul_f32_e32 v12, v12, v10
	v_mul_f32_e32 v10, 0xbfb8aa3b, v13
	v_exp_f32_e32 v10, v10
	v_mul_f32_e32 v13, v17, v18
	v_pk_add_f32 v[10:11], v[10:11], 1.0 op_sel_hi:[1,0]
	s_nop 0
	v_mul_f32_e32 v10, v10, v11
	v_rcp_f32_e32 v10, v10
	s_nop 0
	v_mul_f32_e32 v10, v13, v10
	v_cvt_pk_bf16_f32 v17, v12, v10
	v_lshlrev_b32_e32 v12, 16, v42
	v_exp_f32_e32 v10, v6
	v_mul_f32_e32 v6, 0xbfb8aa3b, v12
	v_exp_f32_e32 v11, v6
	v_lshlrev_b32_e32 v13, 16, v46
	v_mul_f32_e32 v6, v13, v12
	v_and_b32_e32 v12, 0xffff0000, v42
	v_pk_add_f32 v[10:11], v[10:11], 1.0 op_sel_hi:[1,0]
	global_store_dwordx4 v[110:111], v[14:17], off offset:256
	v_mul_f32_e32 v10, v10, v11
	v_rcp_f32_e32 v10, v10
	v_and_b32_e32 v11, 0xffff0000, v46
	v_mul_f32_e32 v11, v11, v12
	v_mul_f32_e32 v10, v6, v10
	v_mul_f32_e32 v6, 0xbfb8aa3b, v7
	v_mul_f32_e32 v7, 0xbfb8aa3b, v12
	v_exp_f32_e32 v6, v6
	v_exp_f32_e32 v7, v7
	v_lshlrev_b32_e32 v12, 16, v47
	v_pk_add_f32 v[6:7], v[6:7], 1.0 op_sel_hi:[1,0]
	s_nop 0
	v_mul_f32_e32 v6, v6, v7
	v_rcp_f32_e32 v6, v6
	v_lshlrev_b32_e32 v7, 16, v43
	v_mul_f32_e32 v6, v11, v6
	v_cvt_pk_bf16_f32 v6, v10, v6
	v_exp_f32_e32 v10, v8
	v_mul_f32_e32 v8, 0xbfb8aa3b, v7
	v_exp_f32_e32 v11, v8
	v_mul_f32_e32 v7, v12, v7
	v_pk_add_f32 v[10:11], v[10:11], 1.0 op_sel_hi:[1,0]
	s_nop 0
	v_mul_f32_e32 v8, v10, v11
	v_rcp_f32_e32 v8, v8
	v_and_b32_e32 v11, 0xffff0000, v43
	v_and_b32_e32 v10, 0xffff0000, v47
	v_mul_f32_e32 v10, v10, v11
	v_mul_f32_e32 v7, v7, v8
	v_mul_f32_e32 v8, 0xbfb8aa3b, v9
	v_mul_f32_e32 v9, 0xbfb8aa3b, v11
	v_exp_f32_e32 v8, v8
	v_exp_f32_e32 v9, v9
	v_lshlrev_b32_e32 v11, 16, v48
	v_pk_add_f32 v[8:9], v[8:9], 1.0 op_sel_hi:[1,0]
	s_nop 0
	v_mul_f32_e32 v8, v8, v9
	v_rcp_f32_e32 v8, v8
	s_nop 0
	v_mul_f32_e32 v8, v10, v8
	v_lshlrev_b32_e32 v10, 16, v44
	v_cvt_pk_bf16_f32 v7, v7, v8
	v_exp_f32_e32 v8, v2
	v_mul_f32_e32 v2, 0xbfb8aa3b, v10
	v_exp_f32_e32 v9, v2
	v_mul_f32_e32 v2, v11, v10
	v_and_b32_e32 v10, 0xffff0000, v44
	v_pk_add_f32 v[8:9], v[8:9], 1.0 op_sel_hi:[1,0]
	s_nop 0
	v_mul_f32_e32 v8, v8, v9
	v_rcp_f32_e32 v8, v8
	v_and_b32_e32 v9, 0xffff0000, v48
	v_mul_f32_e32 v9, v9, v10
	v_mul_f32_e32 v8, v2, v8
	v_mul_f32_e32 v2, 0xbfb8aa3b, v3
	v_mul_f32_e32 v3, 0xbfb8aa3b, v10
	v_exp_f32_e32 v2, v2
	v_exp_f32_e32 v3, v3
	v_lshlrev_b32_e32 v10, 16, v49
	v_pk_add_f32 v[2:3], v[2:3], 1.0 op_sel_hi:[1,0]
	s_nop 0
	v_mul_f32_e32 v2, v2, v3
	v_rcp_f32_e32 v2, v2
	s_nop 0
	v_mul_f32_e32 v2, v9, v2
	v_lshlrev_b32_e32 v9, 16, v45
	v_cvt_pk_bf16_f32 v8, v8, v2
	v_mul_f32_e32 v2, 0xbfb8aa3b, v4
	v_mul_f32_e32 v3, 0xbfb8aa3b, v9
	v_exp_f32_e32 v2, v2
	v_exp_f32_e32 v3, v3
	v_mul_f32_e32 v4, v10, v9
	v_and_b32_e32 v10, 0xffff0000, v45
	v_and_b32_e32 v9, 0xffff0000, v49
	v_pk_add_f32 v[2:3], v[2:3], 1.0 op_sel_hi:[1,0]
	s_nop 0
	v_mul_f32_e32 v2, v2, v3
	v_rcp_f32_e32 v2, v2
	v_mul_f32_e32 v3, 0xbfb8aa3b, v10
	v_exp_f32_e32 v3, v3
	v_mul_f32_e32 v4, v4, v2
	v_mul_f32_e32 v2, 0xbfb8aa3b, v5
	v_exp_f32_e32 v2, v2
	v_mul_f32_e32 v5, v9, v10
	v_pk_add_f32 v[2:3], v[2:3], 1.0 op_sel_hi:[1,0]
	s_nop 0
	v_mul_f32_e32 v2, v2, v3
	v_rcp_f32_e32 v2, v2
	s_nop 0
	v_mul_f32_e32 v2, v5, v2
	v_cvt_pk_bf16_f32 v9, v4, v2
	global_store_dwordx4 v[112:113], v[6:9], off offset:256
	s_cbranch_vccz .LBB0_789
	s_waitcnt vmcnt(0)
	v_readlane_b32 s36, v254, 56
	s_cmpk_gt_u32 s18, 0xff
	v_readlane_b32 s37, v254, 57
	s_cbranch_scc1 .LBB0_800
	s_barrier
